# K-loops: the redundant s_waitcnt lgkmcnt(0) after each pre-MMA barrier removed (the same wait sits before the barrier)
# baseline (speedup 1.0000x reference)
.LBB0_219:
	ds_read_b128 v[180:183], v173
	ds_read_b128 v[184:187], v173 offset:1024
	ds_read_b128 v[188:191], v173 offset:2048
	ds_read_b128 v[192:195], v173 offset:3072
	ds_read_b128 v[196:199], v174
	ds_read_b128 v[200:203], v174 offset:1024
	ds_read_b128 v[204:207], v174 offset:2048
	ds_read_b128 v[208:211], v174 offset:3072
	s_add_u32 s36, s34, 0xfffc0080
	s_addc_u32 s37, s35, -1
	s_cmp_eq_u32 s59, 12
	s_cselect_b32 s39, s1, s37
	s_cselect_b32 s38, s9, s36
	s_cselect_b32 s37, s12, s58
	s_cselect_b32 s36, s25, s27
	v_lshl_add_u64 v[156:157], s[34:35], 0, v[142:143]
	s_add_i32 m0, s45, 0xc000
	ds_read_b128 v[212:215], v175
	ds_read_b128 v[216:219], v175 offset:1024
	ds_read_b128 v[220:223], v175 offset:2048
	ds_read_b128 v[224:227], v175 offset:3072
	ds_read_b128 v[228:231], v175 offset:4096
	ds_read_b128 v[232:235], v175 offset:5120
	ds_read_b128 v[236:239], v175 offset:6144
	ds_read_b128 v[240:243], v175 offset:7168
	global_load_lds_dwordx4 v[156:157], off
	v_lshl_add_u64 v[156:157], s[34:35], 0, v[140:141]
	s_add_i32 m0, s45, 0xe000
	s_nop 0
	global_load_lds_dwordx4 v[156:157], off
	s_waitcnt vmcnt(8)
	s_waitcnt lgkmcnt(0)
	s_barrier
	s_setprio 1
	v_mfma_f32_16x16x32_bf16 v[126:129], v[180:183], v[212:215], v[126:129]
	v_mfma_f32_16x16x32_bf16 v[122:125], v[188:191], v[212:215], v[122:125]
	v_mfma_f32_16x16x32_bf16 v[110:113], v[180:183], v[220:223], v[110:113]
	v_mfma_f32_16x16x32_bf16 v[106:109], v[188:191], v[220:223], v[106:109]
	v_mfma_f32_16x16x32_bf16 v[94:97], v[180:183], v[228:231], v[94:97]
	v_mfma_f32_16x16x32_bf16 v[90:93], v[188:191], v[228:231], v[90:93]
	v_mfma_f32_16x16x32_bf16 v[78:81], v[180:183], v[236:239], v[78:81]
	v_mfma_f32_16x16x32_bf16 v[74:77], v[188:191], v[236:239], v[74:77]
	v_mfma_f32_16x16x32_bf16 v[126:129], v[184:187], v[216:219], v[126:129]
	v_mfma_f32_16x16x32_bf16 v[122:125], v[192:195], v[216:219], v[122:125]
	v_mfma_f32_16x16x32_bf16 v[110:113], v[184:187], v[224:227], v[110:113]
	v_mfma_f32_16x16x32_bf16 v[106:109], v[192:195], v[224:227], v[106:109]
	v_mfma_f32_16x16x32_bf16 v[94:97], v[184:187], v[232:235], v[94:97]
	v_mfma_f32_16x16x32_bf16 v[90:93], v[192:195], v[232:235], v[90:93]
	v_mfma_f32_16x16x32_bf16 v[78:81], v[184:187], v[240:243], v[78:81]
	v_mfma_f32_16x16x32_bf16 v[74:77], v[192:195], v[240:243], v[74:77]
	v_mfma_f32_16x16x32_bf16 v[118:121], v[196:199], v[212:215], v[118:121]
	v_mfma_f32_16x16x32_bf16 v[114:117], v[204:207], v[212:215], v[114:117]
	v_mfma_f32_16x16x32_bf16 v[102:105], v[196:199], v[220:223], v[102:105]
	v_mfma_f32_16x16x32_bf16 v[98:101], v[204:207], v[220:223], v[98:101]
	v_mfma_f32_16x16x32_bf16 v[86:89], v[196:199], v[228:231], v[86:89]
	v_mfma_f32_16x16x32_bf16 v[82:85], v[204:207], v[228:231], v[82:85]
	v_mfma_f32_16x16x32_bf16 v[70:73], v[196:199], v[236:239], v[70:73]
	v_mfma_f32_16x16x32_bf16 v[66:69], v[204:207], v[236:239], v[66:69]
	v_mfma_f32_16x16x32_bf16 v[118:121], v[200:203], v[216:219], v[118:121]
	v_mfma_f32_16x16x32_bf16 v[114:117], v[208:211], v[216:219], v[114:117]
	v_mfma_f32_16x16x32_bf16 v[102:105], v[200:203], v[224:227], v[102:105]
	v_mfma_f32_16x16x32_bf16 v[98:101], v[208:211], v[224:227], v[98:101]
	v_mfma_f32_16x16x32_bf16 v[86:89], v[200:203], v[232:235], v[86:89]
	v_mfma_f32_16x16x32_bf16 v[82:85], v[208:211], v[232:235], v[82:85]
	v_mfma_f32_16x16x32_bf16 v[70:73], v[200:203], v[240:243], v[70:73]
	v_mfma_f32_16x16x32_bf16 v[66:69], v[208:211], v[240:243], v[66:69]
	s_setprio 0
	s_barrier
	s_add_i32 s60, s55, s44
	v_lshl_add_u64 v[156:157], s[36:37], 0, v[132:133]
	s_mov_b32 m0, s60
	ds_read_b128 v[212:215], v175 offset:16384
	ds_read_b128 v[216:219], v175 offset:17408
	ds_read_b128 v[220:223], v175 offset:18432
	ds_read_b128 v[224:227], v175 offset:19456
	ds_read_b128 v[228:231], v175 offset:20480
	ds_read_b128 v[232:235], v175 offset:21504
	ds_read_b128 v[236:239], v175 offset:22528
	ds_read_b128 v[240:243], v175 offset:23552
	global_load_lds_dwordx4 v[156:157], off
	s_add_i32 m0, s60, 0x2000
	s_add_u32 s60, s36, 0x40000
	v_lshl_add_u64 v[160:161], s[36:37], 0, v[136:137]
	s_addc_u32 s61, s37, 0
	s_add_i32 s62, s56, s44
	global_load_lds_dwordx4 v[160:161], off
	v_lshl_add_u64 v[176:177], s[60:61], 0, v[132:133]
	s_mov_b32 m0, s62
	v_lshl_add_u64 v[244:245], s[38:39], 0, v[134:135]
	global_load_lds_dwordx4 v[176:177], off
	v_lshl_add_u64 v[176:177], s[60:61], 0, v[136:137]
	s_add_i32 m0, s62, 0x2000
	s_nop 0
	global_load_lds_dwordx4 v[176:177], off
	v_lshl_add_u64 v[176:177], s[38:39], 0, v[130:131]
	s_mov_b32 m0, s45
	s_nop 0
	global_load_lds_dwordx4 v[176:177], off
	s_mov_b32 m0, s46
	s_nop 0
	global_load_lds_dwordx4 v[244:245], off
	s_waitcnt vmcnt(8)
	s_waitcnt lgkmcnt(0)
	s_barrier
	s_setprio 1
	v_mfma_f32_16x16x32_bf16 v[62:65], v[180:183], v[212:215], v[62:65]
	v_mfma_f32_16x16x32_bf16 v[58:61], v[188:191], v[212:215], v[58:61]
	v_mfma_f32_16x16x32_bf16 v[46:49], v[180:183], v[220:223], v[46:49]
	v_mfma_f32_16x16x32_bf16 v[42:45], v[188:191], v[220:223], v[42:45]
	v_mfma_f32_16x16x32_bf16 v[30:33], v[180:183], v[228:231], v[30:33]
	v_mfma_f32_16x16x32_bf16 v[26:29], v[188:191], v[228:231], v[26:29]
	v_mfma_f32_16x16x32_bf16 v[14:17], v[180:183], v[236:239], v[14:17]
	v_mfma_f32_16x16x32_bf16 v[10:13], v[188:191], v[236:239], v[10:13]
	v_mfma_f32_16x16x32_bf16 v[62:65], v[184:187], v[216:219], v[62:65]
	v_mfma_f32_16x16x32_bf16 v[58:61], v[192:195], v[216:219], v[58:61]
	v_mfma_f32_16x16x32_bf16 v[46:49], v[184:187], v[224:227], v[46:49]
	v_mfma_f32_16x16x32_bf16 v[42:45], v[192:195], v[224:227], v[42:45]
	v_mfma_f32_16x16x32_bf16 v[30:33], v[184:187], v[232:235], v[30:33]
	v_mfma_f32_16x16x32_bf16 v[26:29], v[192:195], v[232:235], v[26:29]
	v_mfma_f32_16x16x32_bf16 v[14:17], v[184:187], v[240:243], v[14:17]
	v_mfma_f32_16x16x32_bf16 v[10:13], v[192:195], v[240:243], v[10:13]
	v_mfma_f32_16x16x32_bf16 v[54:57], v[196:199], v[212:215], v[54:57]
	v_mfma_f32_16x16x32_bf16 v[50:53], v[204:207], v[212:215], v[50:53]
	v_mfma_f32_16x16x32_bf16 v[38:41], v[196:199], v[220:223], v[38:41]
	v_mfma_f32_16x16x32_bf16 v[34:37], v[204:207], v[220:223], v[34:37]
	v_mfma_f32_16x16x32_bf16 v[22:25], v[196:199], v[228:231], v[22:25]
	v_mfma_f32_16x16x32_bf16 v[18:21], v[204:207], v[228:231], v[18:21]
	v_mfma_f32_16x16x32_bf16 v[6:9], v[196:199], v[236:239], v[6:9]
	v_mfma_f32_16x16x32_bf16 v[2:5], v[204:207], v[236:239], v[2:5]
	v_mfma_f32_16x16x32_bf16 v[54:57], v[200:203], v[216:219], v[54:57]
	v_mfma_f32_16x16x32_bf16 v[50:53], v[208:211], v[216:219], v[50:53]
	v_mfma_f32_16x16x32_bf16 v[38:41], v[200:203], v[224:227], v[38:41]
	v_mfma_f32_16x16x32_bf16 v[34:37], v[208:211], v[224:227], v[34:37]
	v_mfma_f32_16x16x32_bf16 v[22:25], v[200:203], v[232:235], v[22:25]
	v_mfma_f32_16x16x32_bf16 v[18:21], v[208:211], v[232:235], v[18:21]
	v_mfma_f32_16x16x32_bf16 v[6:9], v[200:203], v[240:243], v[6:9]
	v_mfma_f32_16x16x32_bf16 v[2:5], v[208:211], v[240:243], v[2:5]
	s_setprio 0
	s_barrier
	s_add_i32 s60, 0, 0x18000
	v_add_u32_e32 v149, s60, v171
	s_add_i32 s61, 0, 0x1c000
	ds_read_b128 v[180:183], v149
	ds_read_b128 v[184:187], v149 offset:1024
	ds_read_b128 v[188:191], v149 offset:2048
	ds_read_b128 v[192:195], v149 offset:3072
	v_add_u32_e32 v149, s61, v171
	ds_read_b128 v[196:199], v149
	ds_read_b128 v[200:203], v149 offset:1024
	ds_read_b128 v[204:207], v149 offset:2048
	ds_read_b128 v[208:211], v149 offset:3072
	s_add_u32 s38, s38, 0x40000
	s_addc_u32 s39, s39, 0
	s_mov_b32 m0, s47
	v_lshl_add_u64 v[246:247], s[38:39], 0, v[130:131]
	ds_read_b128 v[212:215], v175 offset:32768
	ds_read_b128 v[216:219], v175 offset:33792
	ds_read_b128 v[220:223], v175 offset:34816
	ds_read_b128 v[224:227], v175 offset:35840
	ds_read_b128 v[228:231], v175 offset:36864
	ds_read_b128 v[232:235], v175 offset:37888
	ds_read_b128 v[236:239], v175 offset:38912
	ds_read_b128 v[240:243], v175 offset:39936
	global_load_lds_dwordx4 v[246:247], off
	v_lshl_add_u64 v[246:247], s[38:39], 0, v[134:135]
	s_mov_b32 m0, s48
	s_nop 0
	global_load_lds_dwordx4 v[246:247], off
	s_waitcnt vmcnt(8)
	s_waitcnt lgkmcnt(0)
	s_barrier
	s_setprio 1
	v_mfma_f32_16x16x32_bf16 v[126:129], v[180:183], v[212:215], v[126:129]
	v_mfma_f32_16x16x32_bf16 v[122:125], v[188:191], v[212:215], v[122:125]
	v_mfma_f32_16x16x32_bf16 v[110:113], v[180:183], v[220:223], v[110:113]
	v_mfma_f32_16x16x32_bf16 v[106:109], v[188:191], v[220:223], v[106:109]
	v_mfma_f32_16x16x32_bf16 v[94:97], v[180:183], v[228:231], v[94:97]
	v_mfma_f32_16x16x32_bf16 v[90:93], v[188:191], v[228:231], v[90:93]
	v_mfma_f32_16x16x32_bf16 v[78:81], v[180:183], v[236:239], v[78:81]
	v_mfma_f32_16x16x32_bf16 v[74:77], v[188:191], v[236:239], v[74:77]
	v_mfma_f32_16x16x32_bf16 v[126:129], v[184:187], v[216:219], v[126:129]
	v_mfma_f32_16x16x32_bf16 v[122:125], v[192:195], v[216:219], v[122:125]
	v_mfma_f32_16x16x32_bf16 v[110:113], v[184:187], v[224:227], v[110:113]
	v_mfma_f32_16x16x32_bf16 v[106:109], v[192:195], v[224:227], v[106:109]
	v_mfma_f32_16x16x32_bf16 v[94:97], v[184:187], v[232:235], v[94:97]
	v_mfma_f32_16x16x32_bf16 v[90:93], v[192:195], v[232:235], v[90:93]
	v_mfma_f32_16x16x32_bf16 v[78:81], v[184:187], v[240:243], v[78:81]
	v_mfma_f32_16x16x32_bf16 v[74:77], v[192:195], v[240:243], v[74:77]
	v_mfma_f32_16x16x32_bf16 v[118:121], v[196:199], v[212:215], v[118:121]
	v_mfma_f32_16x16x32_bf16 v[114:117], v[204:207], v[212:215], v[114:117]
	v_mfma_f32_16x16x32_bf16 v[102:105], v[196:199], v[220:223], v[102:105]
	v_mfma_f32_16x16x32_bf16 v[98:101], v[204:207], v[220:223], v[98:101]
	v_mfma_f32_16x16x32_bf16 v[86:89], v[196:199], v[228:231], v[86:89]
	v_mfma_f32_16x16x32_bf16 v[82:85], v[204:207], v[228:231], v[82:85]
	v_mfma_f32_16x16x32_bf16 v[70:73], v[196:199], v[236:239], v[70:73]
	v_mfma_f32_16x16x32_bf16 v[66:69], v[204:207], v[236:239], v[66:69]
	v_mfma_f32_16x16x32_bf16 v[118:121], v[200:203], v[216:219], v[118:121]
	v_mfma_f32_16x16x32_bf16 v[114:117], v[208:211], v[216:219], v[114:117]
	v_mfma_f32_16x16x32_bf16 v[102:105], v[200:203], v[224:227], v[102:105]
	v_mfma_f32_16x16x32_bf16 v[98:101], v[208:211], v[224:227], v[98:101]
	v_mfma_f32_16x16x32_bf16 v[86:89], v[200:203], v[232:235], v[86:89]
	v_mfma_f32_16x16x32_bf16 v[82:85], v[208:211], v[232:235], v[82:85]
	v_mfma_f32_16x16x32_bf16 v[70:73], v[200:203], v[240:243], v[70:73]
	v_mfma_f32_16x16x32_bf16 v[66:69], v[208:211], v[240:243], v[66:69]
	s_setprio 0
	s_barrier
	s_add_i32 s38, s60, s44
	v_lshl_add_u64 v[156:157], v[156:157], 0, s[18:19]
	s_mov_b32 m0, s38
	ds_read_b128 v[212:215], v175 offset:49152
	ds_read_b128 v[216:219], v175 offset:50176
	ds_read_b128 v[220:223], v175 offset:51200
	ds_read_b128 v[224:227], v175 offset:52224
	ds_read_b128 v[228:231], v175 offset:53248
	ds_read_b128 v[232:235], v175 offset:54272
	ds_read_b128 v[236:239], v175 offset:55296
	ds_read_b128 v[240:243], v175 offset:56320
	global_load_lds_dwordx4 v[156:157], off
	s_add_i32 m0, s38, 0x2000
	s_add_u32 s36, s36, 0x40080
	v_lshl_add_u64 v[156:157], v[160:161], 0, s[18:19]
	s_addc_u32 s37, s37, 0
	s_add_i32 s38, s61, s44
	global_load_lds_dwordx4 v[156:157], off
	v_lshl_add_u64 v[156:157], s[36:37], 0, v[132:133]
	s_mov_b32 m0, s38
	s_nop 0
	global_load_lds_dwordx4 v[156:157], off
	v_lshl_add_u64 v[156:157], s[36:37], 0, v[136:137]
	s_add_i32 m0, s38, 0x2000
	s_nop 0
	global_load_lds_dwordx4 v[156:157], off
	v_lshl_add_u64 v[156:157], v[176:177], 0, s[18:19]
	s_mov_b32 m0, s51
	s_nop 0
	global_load_lds_dwordx4 v[156:157], off
	v_lshl_add_u64 v[156:157], v[244:245], 0, s[18:19]
	s_mov_b32 m0, s52
	s_nop 0
	global_load_lds_dwordx4 v[156:157], off
	s_waitcnt vmcnt(8)
	s_waitcnt lgkmcnt(0)
	s_barrier
	s_setprio 1
	v_mfma_f32_16x16x32_bf16 v[62:65], v[180:183], v[212:215], v[62:65]
	v_mfma_f32_16x16x32_bf16 v[58:61], v[188:191], v[212:215], v[58:61]
	v_mfma_f32_16x16x32_bf16 v[46:49], v[180:183], v[220:223], v[46:49]
	v_mfma_f32_16x16x32_bf16 v[42:45], v[188:191], v[220:223], v[42:45]
	v_mfma_f32_16x16x32_bf16 v[30:33], v[180:183], v[228:231], v[30:33]
	v_mfma_f32_16x16x32_bf16 v[26:29], v[188:191], v[228:231], v[26:29]
	v_mfma_f32_16x16x32_bf16 v[14:17], v[180:183], v[236:239], v[14:17]
	v_mfma_f32_16x16x32_bf16 v[10:13], v[188:191], v[236:239], v[10:13]
	v_mfma_f32_16x16x32_bf16 v[62:65], v[184:187], v[216:219], v[62:65]
	v_mfma_f32_16x16x32_bf16 v[58:61], v[192:195], v[216:219], v[58:61]
	v_mfma_f32_16x16x32_bf16 v[46:49], v[184:187], v[224:227], v[46:49]
	v_mfma_f32_16x16x32_bf16 v[42:45], v[192:195], v[224:227], v[42:45]
	v_mfma_f32_16x16x32_bf16 v[30:33], v[184:187], v[232:235], v[30:33]
	v_mfma_f32_16x16x32_bf16 v[26:29], v[192:195], v[232:235], v[26:29]
	v_mfma_f32_16x16x32_bf16 v[14:17], v[184:187], v[240:243], v[14:17]
	v_mfma_f32_16x16x32_bf16 v[10:13], v[192:195], v[240:243], v[10:13]
	v_mfma_f32_16x16x32_bf16 v[54:57], v[196:199], v[212:215], v[54:57]
	v_mfma_f32_16x16x32_bf16 v[50:53], v[204:207], v[212:215], v[50:53]
	v_mfma_f32_16x16x32_bf16 v[38:41], v[196:199], v[220:223], v[38:41]
	v_mfma_f32_16x16x32_bf16 v[34:37], v[204:207], v[220:223], v[34:37]
	v_mfma_f32_16x16x32_bf16 v[22:25], v[196:199], v[228:231], v[22:25]
	v_mfma_f32_16x16x32_bf16 v[18:21], v[204:207], v[228:231], v[18:21]
	v_mfma_f32_16x16x32_bf16 v[6:9], v[196:199], v[236:239], v[6:9]
	v_mfma_f32_16x16x32_bf16 v[2:5], v[204:207], v[236:239], v[2:5]
	v_mfma_f32_16x16x32_bf16 v[54:57], v[200:203], v[216:219], v[54:57]
	v_mfma_f32_16x16x32_bf16 v[50:53], v[208:211], v[216:219], v[50:53]
	v_mfma_f32_16x16x32_bf16 v[38:41], v[200:203], v[224:227], v[38:41]
	v_mfma_f32_16x16x32_bf16 v[34:37], v[208:211], v[224:227], v[34:37]
	v_mfma_f32_16x16x32_bf16 v[22:25], v[200:203], v[232:235], v[22:25]
	v_mfma_f32_16x16x32_bf16 v[18:21], v[208:211], v[232:235], v[18:21]
	v_mfma_f32_16x16x32_bf16 v[6:9], v[200:203], v[240:243], v[6:9]
	v_mfma_f32_16x16x32_bf16 v[2:5], v[208:211], v[240:243], v[2:5]
	s_setprio 0
	s_barrier
	s_add_i32 s59, s59, 2
	s_add_u32 s27, s27, 0x100
	s_addc_u32 s58, s58, 0
	s_add_u32 s34, s34, 0x100
	s_addc_u32 s35, s35, 0
	s_cmp_gt_u32 s59, 13
	s_cbranch_scc0 .LBB0_219
	s_and_b64 vcc, exec, s[20:21]
	s_cbranch_vccz .LBB0_222
	s_barrier

.LBB0_681:
	v_add_u32_e32 v154, s62, v156
	ds_read_b128 v[130:133], v154
	ds_read_b128 v[150:153], v154 offset:1024
	ds_read_b128 v[160:163], v154 offset:2048
	ds_read_b128 v[164:167], v154 offset:3072
	v_add_u32_e32 v154, s63, v156
	ds_read_b128 v[168:171], v154
	ds_read_b128 v[172:175], v154 offset:1024
	ds_read_b128 v[180:183], v154 offset:2048
	ds_read_b128 v[184:187], v154 offset:3072
	s_add_u32 s42, s40, 0xfffc0080
	s_addc_u32 s43, s41, -1
	s_cmp_eq_u32 s68, 12
	s_cselect_b32 s45, s31, s43
	s_cselect_b32 s44, s39, s42
	s_cselect_b32 s43, s29, s67
	s_cselect_b32 s42, s65, s66
	v_lshl_add_u64 v[154:155], s[40:41], 0, v[144:145]
	s_add_i32 m0, s51, 0xc000
	ds_read_b128 v[188:191], v158
	ds_read_b128 v[192:195], v158 offset:1024
	ds_read_b128 v[196:199], v158 offset:2048
	ds_read_b128 v[200:203], v158 offset:3072
	ds_read_b128 v[204:207], v158 offset:4096
	ds_read_b128 v[208:211], v158 offset:5120
	ds_read_b128 v[212:215], v158 offset:6144
	ds_read_b128 v[216:219], v158 offset:7168
	global_load_lds_dwordx4 v[154:155], off
	v_lshl_add_u64 v[154:155], s[40:41], 0, v[142:143]
	s_add_i32 m0, s51, 0xe000
	s_nop 0
	global_load_lds_dwordx4 v[154:155], off
	s_waitcnt vmcnt(8)
	s_waitcnt lgkmcnt(0)
	s_barrier
	s_setprio 1
	v_mfma_f32_16x16x32_bf16 v[114:117], v[130:133], v[188:191], v[114:117]
	v_mfma_f32_16x16x32_bf16 v[118:121], v[160:163], v[188:191], v[118:121]
	v_mfma_f32_16x16x32_bf16 v[98:101], v[130:133], v[196:199], v[98:101]
	v_mfma_f32_16x16x32_bf16 v[102:105], v[160:163], v[196:199], v[102:105]
	v_mfma_f32_16x16x32_bf16 v[82:85], v[130:133], v[204:207], v[82:85]
	v_mfma_f32_16x16x32_bf16 v[86:89], v[160:163], v[204:207], v[86:89]
	v_mfma_f32_16x16x32_bf16 v[66:69], v[130:133], v[212:215], v[66:69]
	v_mfma_f32_16x16x32_bf16 v[70:73], v[160:163], v[212:215], v[70:73]
	v_mfma_f32_16x16x32_bf16 v[114:117], v[150:153], v[192:195], v[114:117]
	v_mfma_f32_16x16x32_bf16 v[118:121], v[164:167], v[192:195], v[118:121]
	v_mfma_f32_16x16x32_bf16 v[98:101], v[150:153], v[200:203], v[98:101]
	v_mfma_f32_16x16x32_bf16 v[102:105], v[164:167], v[200:203], v[102:105]
	v_mfma_f32_16x16x32_bf16 v[82:85], v[150:153], v[208:211], v[82:85]
	v_mfma_f32_16x16x32_bf16 v[86:89], v[164:167], v[208:211], v[86:89]
	v_mfma_f32_16x16x32_bf16 v[66:69], v[150:153], v[216:219], v[66:69]
	v_mfma_f32_16x16x32_bf16 v[70:73], v[164:167], v[216:219], v[70:73]
	v_mfma_f32_16x16x32_bf16 v[122:125], v[168:171], v[188:191], v[122:125]
	v_mfma_f32_16x16x32_bf16 v[126:129], v[180:183], v[188:191], v[126:129]
	v_mfma_f32_16x16x32_bf16 v[106:109], v[168:171], v[196:199], v[106:109]
	v_mfma_f32_16x16x32_bf16 v[110:113], v[180:183], v[196:199], v[110:113]
	v_mfma_f32_16x16x32_bf16 v[90:93], v[168:171], v[204:207], v[90:93]
	v_mfma_f32_16x16x32_bf16 v[94:97], v[180:183], v[204:207], v[94:97]
	v_mfma_f32_16x16x32_bf16 v[74:77], v[168:171], v[212:215], v[74:77]
	v_mfma_f32_16x16x32_bf16 v[78:81], v[180:183], v[212:215], v[78:81]
	v_mfma_f32_16x16x32_bf16 v[122:125], v[172:175], v[192:195], v[122:125]
	v_mfma_f32_16x16x32_bf16 v[126:129], v[184:187], v[192:195], v[126:129]
	v_mfma_f32_16x16x32_bf16 v[106:109], v[172:175], v[200:203], v[106:109]
	v_mfma_f32_16x16x32_bf16 v[110:113], v[184:187], v[200:203], v[110:113]
	v_mfma_f32_16x16x32_bf16 v[90:93], v[172:175], v[208:211], v[90:93]
	v_mfma_f32_16x16x32_bf16 v[94:97], v[184:187], v[208:211], v[94:97]
	v_mfma_f32_16x16x32_bf16 v[74:77], v[172:175], v[216:219], v[74:77]
	v_mfma_f32_16x16x32_bf16 v[78:81], v[184:187], v[216:219], v[78:81]
	s_setprio 0
	s_barrier
	s_add_i32 s69, s62, s50
	v_lshl_add_u64 v[154:155], s[42:43], 0, v[136:137]
	s_mov_b32 m0, s69
	ds_read_b128 v[188:191], v158 offset:16384
	ds_read_b128 v[192:195], v158 offset:17408
	ds_read_b128 v[196:199], v158 offset:18432
	ds_read_b128 v[200:203], v158 offset:19456
	ds_read_b128 v[204:207], v158 offset:20480
	ds_read_b128 v[208:211], v158 offset:21504
	ds_read_b128 v[212:215], v158 offset:22528
	ds_read_b128 v[216:219], v158 offset:23552
	global_load_lds_dwordx4 v[154:155], off
	s_add_i32 m0, s69, 0x2000
	s_add_u32 s70, s42, 0x40000
	v_lshl_add_u64 v[176:177], s[42:43], 0, v[140:141]
	s_addc_u32 s71, s43, 0
	s_add_i32 s69, s63, s50
	global_load_lds_dwordx4 v[176:177], off
	v_lshl_add_u64 v[220:221], s[70:71], 0, v[136:137]
	s_mov_b32 m0, s69
	v_lshl_add_u64 v[222:223], s[44:45], 0, v[138:139]
	global_load_lds_dwordx4 v[220:221], off
	v_lshl_add_u64 v[220:221], s[70:71], 0, v[140:141]
	s_add_i32 m0, s69, 0x2000
	s_nop 0
	global_load_lds_dwordx4 v[220:221], off
	v_lshl_add_u64 v[220:221], s[44:45], 0, v[134:135]
	s_mov_b32 m0, s51
	s_nop 0
	global_load_lds_dwordx4 v[220:221], off
	s_mov_b32 m0, s52
	s_nop 0
	global_load_lds_dwordx4 v[222:223], off
	s_waitcnt vmcnt(8)
	s_waitcnt lgkmcnt(0)
	s_barrier
	s_setprio 1
	v_mfma_f32_16x16x32_bf16 v[50:53], v[130:133], v[188:191], v[50:53]
	v_mfma_f32_16x16x32_bf16 v[54:57], v[160:163], v[188:191], v[54:57]
	v_mfma_f32_16x16x32_bf16 v[26:29], v[130:133], v[196:199], v[26:29]
	v_mfma_f32_16x16x32_bf16 v[30:33], v[160:163], v[196:199], v[30:33]
	v_mfma_f32_16x16x32_bf16 v[18:21], v[130:133], v[204:207], v[18:21]
	v_mfma_f32_16x16x32_bf16 v[22:25], v[160:163], v[204:207], v[22:25]
	v_mfma_f32_16x16x32_bf16 v[2:5], v[130:133], v[212:215], v[2:5]
	v_mfma_f32_16x16x32_bf16 v[6:9], v[160:163], v[212:215], v[6:9]
	v_mfma_f32_16x16x32_bf16 v[50:53], v[150:153], v[192:195], v[50:53]
	v_mfma_f32_16x16x32_bf16 v[54:57], v[164:167], v[192:195], v[54:57]
	v_mfma_f32_16x16x32_bf16 v[26:29], v[150:153], v[200:203], v[26:29]
	v_mfma_f32_16x16x32_bf16 v[30:33], v[164:167], v[200:203], v[30:33]
	v_mfma_f32_16x16x32_bf16 v[18:21], v[150:153], v[208:211], v[18:21]
	v_mfma_f32_16x16x32_bf16 v[22:25], v[164:167], v[208:211], v[22:25]
	v_mfma_f32_16x16x32_bf16 v[2:5], v[150:153], v[216:219], v[2:5]
	v_mfma_f32_16x16x32_bf16 v[6:9], v[164:167], v[216:219], v[6:9]
	v_mfma_f32_16x16x32_bf16 v[58:61], v[168:171], v[188:191], v[58:61]
	v_mfma_f32_16x16x32_bf16 v[62:65], v[180:183], v[188:191], v[62:65]
	v_mfma_f32_16x16x32_bf16 v[42:45], v[168:171], v[196:199], v[42:45]
	v_mfma_f32_16x16x32_bf16 v[46:49], v[180:183], v[196:199], v[46:49]
	v_mfma_f32_16x16x32_bf16 v[34:37], v[168:171], v[204:207], v[34:37]
	v_mfma_f32_16x16x32_bf16 v[38:41], v[180:183], v[204:207], v[38:41]
	v_mfma_f32_16x16x32_bf16 v[10:13], v[168:171], v[212:215], v[10:13]
	v_mfma_f32_16x16x32_bf16 v[14:17], v[180:183], v[212:215], v[14:17]
	v_mfma_f32_16x16x32_bf16 v[58:61], v[172:175], v[192:195], v[58:61]
	v_mfma_f32_16x16x32_bf16 v[62:65], v[184:187], v[192:195], v[62:65]
	v_mfma_f32_16x16x32_bf16 v[42:45], v[172:175], v[200:203], v[42:45]
	v_mfma_f32_16x16x32_bf16 v[46:49], v[184:187], v[200:203], v[46:49]
	v_mfma_f32_16x16x32_bf16 v[34:37], v[172:175], v[208:211], v[34:37]
	v_mfma_f32_16x16x32_bf16 v[38:41], v[184:187], v[208:211], v[38:41]
	v_mfma_f32_16x16x32_bf16 v[10:13], v[172:175], v[216:219], v[10:13]
	v_mfma_f32_16x16x32_bf16 v[14:17], v[184:187], v[216:219], v[14:17]
	s_setprio 0
	s_barrier
	s_add_i32 s69, 0, 0x18000
	s_add_i32 s70, 0, 0x1c000
	v_add_u32_e32 v164, s69, v156
	v_add_u32_e32 v179, s70, v156
	ds_read_b128 v[130:133], v164
	ds_read_b128 v[150:153], v164 offset:1024
	ds_read_b128 v[160:163], v164 offset:2048
	ds_read_b128 v[164:167], v164 offset:3072
	ds_read_b128 v[168:171], v179
	ds_read_b128 v[172:175], v179 offset:1024
	ds_read_b128 v[180:183], v179 offset:2048
	ds_read_b128 v[184:187], v179 offset:3072
	s_add_u32 s44, s44, 0x40000
	s_addc_u32 s45, s45, 0
	s_mov_b32 m0, s53
	v_lshl_add_u64 v[224:225], s[44:45], 0, v[134:135]
	ds_read_b128 v[188:191], v158 offset:32768
	ds_read_b128 v[192:195], v158 offset:33792
	ds_read_b128 v[196:199], v158 offset:34816
	ds_read_b128 v[200:203], v158 offset:35840
	ds_read_b128 v[204:207], v158 offset:36864
	ds_read_b128 v[208:211], v158 offset:37888
	ds_read_b128 v[212:215], v158 offset:38912
	ds_read_b128 v[216:219], v158 offset:39936
	global_load_lds_dwordx4 v[224:225], off
	v_lshl_add_u64 v[224:225], s[44:45], 0, v[138:139]
	s_mov_b32 m0, s54
	s_nop 0
	global_load_lds_dwordx4 v[224:225], off
	s_waitcnt vmcnt(8)
	s_waitcnt lgkmcnt(0)
	s_barrier
	s_setprio 1
	v_mfma_f32_16x16x32_bf16 v[114:117], v[130:133], v[188:191], v[114:117]
	v_mfma_f32_16x16x32_bf16 v[118:121], v[160:163], v[188:191], v[118:121]
	v_mfma_f32_16x16x32_bf16 v[98:101], v[130:133], v[196:199], v[98:101]
	v_mfma_f32_16x16x32_bf16 v[102:105], v[160:163], v[196:199], v[102:105]
	v_mfma_f32_16x16x32_bf16 v[82:85], v[130:133], v[204:207], v[82:85]
	v_mfma_f32_16x16x32_bf16 v[86:89], v[160:163], v[204:207], v[86:89]
	v_mfma_f32_16x16x32_bf16 v[66:69], v[130:133], v[212:215], v[66:69]
	v_mfma_f32_16x16x32_bf16 v[70:73], v[160:163], v[212:215], v[70:73]
	v_mfma_f32_16x16x32_bf16 v[114:117], v[150:153], v[192:195], v[114:117]
	v_mfma_f32_16x16x32_bf16 v[118:121], v[164:167], v[192:195], v[118:121]
	v_mfma_f32_16x16x32_bf16 v[98:101], v[150:153], v[200:203], v[98:101]
	v_mfma_f32_16x16x32_bf16 v[102:105], v[164:167], v[200:203], v[102:105]
	v_mfma_f32_16x16x32_bf16 v[82:85], v[150:153], v[208:211], v[82:85]
	v_mfma_f32_16x16x32_bf16 v[86:89], v[164:167], v[208:211], v[86:89]
	v_mfma_f32_16x16x32_bf16 v[66:69], v[150:153], v[216:219], v[66:69]
	v_mfma_f32_16x16x32_bf16 v[70:73], v[164:167], v[216:219], v[70:73]
	v_mfma_f32_16x16x32_bf16 v[122:125], v[168:171], v[188:191], v[122:125]
	v_mfma_f32_16x16x32_bf16 v[126:129], v[180:183], v[188:191], v[126:129]
	v_mfma_f32_16x16x32_bf16 v[106:109], v[168:171], v[196:199], v[106:109]
	v_mfma_f32_16x16x32_bf16 v[110:113], v[180:183], v[196:199], v[110:113]
	v_mfma_f32_16x16x32_bf16 v[90:93], v[168:171], v[204:207], v[90:93]
	v_mfma_f32_16x16x32_bf16 v[94:97], v[180:183], v[204:207], v[94:97]
	v_mfma_f32_16x16x32_bf16 v[74:77], v[168:171], v[212:215], v[74:77]
	v_mfma_f32_16x16x32_bf16 v[78:81], v[180:183], v[212:215], v[78:81]
	v_mfma_f32_16x16x32_bf16 v[122:125], v[172:175], v[192:195], v[122:125]
	v_mfma_f32_16x16x32_bf16 v[126:129], v[184:187], v[192:195], v[126:129]
	v_mfma_f32_16x16x32_bf16 v[106:109], v[172:175], v[200:203], v[106:109]
	v_mfma_f32_16x16x32_bf16 v[110:113], v[184:187], v[200:203], v[110:113]
	v_mfma_f32_16x16x32_bf16 v[90:93], v[172:175], v[208:211], v[90:93]
	v_mfma_f32_16x16x32_bf16 v[94:97], v[184:187], v[208:211], v[94:97]
	v_mfma_f32_16x16x32_bf16 v[74:77], v[172:175], v[216:219], v[74:77]
	v_mfma_f32_16x16x32_bf16 v[78:81], v[184:187], v[216:219], v[78:81]
	s_setprio 0
	s_barrier
	s_add_i32 s44, s69, s50
	v_lshl_add_u64 v[154:155], v[154:155], 0, s[22:23]
	s_mov_b32 m0, s44
	ds_read_b128 v[188:191], v158 offset:49152
	ds_read_b128 v[192:195], v158 offset:50176
	ds_read_b128 v[196:199], v158 offset:51200
	ds_read_b128 v[200:203], v158 offset:52224
	ds_read_b128 v[204:207], v158 offset:53248
	ds_read_b128 v[208:211], v158 offset:54272
	ds_read_b128 v[212:215], v158 offset:55296
	ds_read_b128 v[216:219], v158 offset:56320
	global_load_lds_dwordx4 v[154:155], off
	s_add_i32 m0, s44, 0x2000
	s_add_u32 s42, s42, 0x40080
	v_lshl_add_u64 v[154:155], v[176:177], 0, s[22:23]
	s_addc_u32 s43, s43, 0
	s_add_i32 s44, s70, s50
	global_load_lds_dwordx4 v[154:155], off
	v_lshl_add_u64 v[154:155], s[42:43], 0, v[136:137]
	s_mov_b32 m0, s44
	s_nop 0
	global_load_lds_dwordx4 v[154:155], off
	v_lshl_add_u64 v[154:155], s[42:43], 0, v[140:141]
	s_add_i32 m0, s44, 0x2000
	s_nop 0
	global_load_lds_dwordx4 v[154:155], off
	v_lshl_add_u64 v[154:155], v[220:221], 0, s[22:23]
	s_mov_b32 m0, s57
	s_nop 0
	global_load_lds_dwordx4 v[154:155], off
	v_lshl_add_u64 v[154:155], v[222:223], 0, s[22:23]
	s_mov_b32 m0, s58
	s_nop 0
	global_load_lds_dwordx4 v[154:155], off
	s_waitcnt vmcnt(8)
	s_waitcnt lgkmcnt(0)
	s_barrier
	s_setprio 1
	v_mfma_f32_16x16x32_bf16 v[50:53], v[130:133], v[188:191], v[50:53]
	v_mfma_f32_16x16x32_bf16 v[54:57], v[160:163], v[188:191], v[54:57]
	v_mfma_f32_16x16x32_bf16 v[26:29], v[130:133], v[196:199], v[26:29]
	v_mfma_f32_16x16x32_bf16 v[30:33], v[160:163], v[196:199], v[30:33]
	v_mfma_f32_16x16x32_bf16 v[18:21], v[130:133], v[204:207], v[18:21]
	v_mfma_f32_16x16x32_bf16 v[22:25], v[160:163], v[204:207], v[22:25]
	v_mfma_f32_16x16x32_bf16 v[2:5], v[130:133], v[212:215], v[2:5]
	v_mfma_f32_16x16x32_bf16 v[6:9], v[160:163], v[212:215], v[6:9]
	v_mfma_f32_16x16x32_bf16 v[50:53], v[150:153], v[192:195], v[50:53]
	v_mfma_f32_16x16x32_bf16 v[54:57], v[164:167], v[192:195], v[54:57]
	v_mfma_f32_16x16x32_bf16 v[26:29], v[150:153], v[200:203], v[26:29]
	v_mfma_f32_16x16x32_bf16 v[30:33], v[164:167], v[200:203], v[30:33]
	v_mfma_f32_16x16x32_bf16 v[18:21], v[150:153], v[208:211], v[18:21]
	v_mfma_f32_16x16x32_bf16 v[22:25], v[164:167], v[208:211], v[22:25]
	v_mfma_f32_16x16x32_bf16 v[2:5], v[150:153], v[216:219], v[2:5]
	v_mfma_f32_16x16x32_bf16 v[6:9], v[164:167], v[216:219], v[6:9]
	v_mfma_f32_16x16x32_bf16 v[58:61], v[168:171], v[188:191], v[58:61]
	v_mfma_f32_16x16x32_bf16 v[62:65], v[180:183], v[188:191], v[62:65]
	v_mfma_f32_16x16x32_bf16 v[42:45], v[168:171], v[196:199], v[42:45]
	v_mfma_f32_16x16x32_bf16 v[46:49], v[180:183], v[196:199], v[46:49]
	v_mfma_f32_16x16x32_bf16 v[34:37], v[168:171], v[204:207], v[34:37]
	v_mfma_f32_16x16x32_bf16 v[38:41], v[180:183], v[204:207], v[38:41]
	v_mfma_f32_16x16x32_bf16 v[10:13], v[168:171], v[212:215], v[10:13]
	v_mfma_f32_16x16x32_bf16 v[14:17], v[180:183], v[212:215], v[14:17]
	v_mfma_f32_16x16x32_bf16 v[58:61], v[172:175], v[192:195], v[58:61]
	v_mfma_f32_16x16x32_bf16 v[62:65], v[184:187], v[192:195], v[62:65]
	v_mfma_f32_16x16x32_bf16 v[42:45], v[172:175], v[200:203], v[42:45]
	v_mfma_f32_16x16x32_bf16 v[46:49], v[184:187], v[200:203], v[46:49]
	v_mfma_f32_16x16x32_bf16 v[34:37], v[172:175], v[208:211], v[34:37]
	v_mfma_f32_16x16x32_bf16 v[38:41], v[184:187], v[208:211], v[38:41]
	v_mfma_f32_16x16x32_bf16 v[10:13], v[172:175], v[216:219], v[10:13]
	v_mfma_f32_16x16x32_bf16 v[14:17], v[184:187], v[216:219], v[14:17]
	s_setprio 0
	s_barrier
	s_add_i32 s68, s68, 2
	s_add_u32 s66, s66, 0x100
	s_addc_u32 s67, s67, 0
	s_add_u32 s40, s40, 0x100
	s_addc_u32 s41, s41, 0
	s_cmp_gt_u32 s68, 13
	s_cbranch_scc0 .LBB0_681
	s_and_b64 vcc, exec, s[24:25]
	s_cbranch_vccz .LBB0_684
	s_barrier

.LBB0_858:
	ds_read_b128 v[164:167], v173
	ds_read_b128 v[180:183], v173 offset:1024
	ds_read_b128 v[184:187], v173 offset:2048
	ds_read_b128 v[188:191], v173 offset:3072
	ds_read_b128 v[192:195], v174
	ds_read_b128 v[196:199], v174 offset:1024
	ds_read_b128 v[200:203], v174 offset:2048
	ds_read_b128 v[204:207], v174 offset:3072
	s_add_u32 s38, s36, 0xfffc0080
	s_addc_u32 s39, s37, -1
	s_cmp_eq_u32 s61, 12
	s_cselect_b32 s41, s25, s39
	s_cselect_b32 s40, s31, s38
	s_cselect_b32 s39, s23, s60
	s_cselect_b32 s38, s58, s59
	v_lshl_add_u64 v[176:177], s[36:37], 0, v[142:143]
	s_add_i32 m0, s35, 0xc000
	ds_read_b128 v[208:211], v175
	ds_read_b128 v[212:215], v175 offset:1024
	ds_read_b128 v[216:219], v175 offset:2048
	ds_read_b128 v[220:223], v175 offset:3072
	ds_read_b128 v[224:227], v175 offset:4096
	ds_read_b128 v[228:231], v175 offset:5120
	ds_read_b128 v[232:235], v175 offset:6144
	ds_read_b128 v[236:239], v175 offset:7168
	global_load_lds_dwordx4 v[176:177], off
	v_lshl_add_u64 v[176:177], s[36:37], 0, v[140:141]
	s_add_i32 m0, s35, 0xe000
	s_nop 0
	global_load_lds_dwordx4 v[176:177], off
	s_waitcnt vmcnt(8)
	s_waitcnt lgkmcnt(0)
	s_barrier
	s_setprio 1
	v_mfma_f32_16x16x32_bf16 v[126:129], v[164:167], v[208:211], v[126:129]
	v_mfma_f32_16x16x32_bf16 v[122:125], v[184:187], v[208:211], v[122:125]
	v_mfma_f32_16x16x32_bf16 v[110:113], v[164:167], v[216:219], v[110:113]
	v_mfma_f32_16x16x32_bf16 v[106:109], v[184:187], v[216:219], v[106:109]
	v_mfma_f32_16x16x32_bf16 v[94:97], v[164:167], v[224:227], v[94:97]
	v_mfma_f32_16x16x32_bf16 v[90:93], v[184:187], v[224:227], v[90:93]
	v_mfma_f32_16x16x32_bf16 v[78:81], v[164:167], v[232:235], v[78:81]
	v_mfma_f32_16x16x32_bf16 v[74:77], v[184:187], v[232:235], v[74:77]
	v_mfma_f32_16x16x32_bf16 v[126:129], v[180:183], v[212:215], v[126:129]
	v_mfma_f32_16x16x32_bf16 v[122:125], v[188:191], v[212:215], v[122:125]
	v_mfma_f32_16x16x32_bf16 v[110:113], v[180:183], v[220:223], v[110:113]
	v_mfma_f32_16x16x32_bf16 v[106:109], v[188:191], v[220:223], v[106:109]
	v_mfma_f32_16x16x32_bf16 v[94:97], v[180:183], v[228:231], v[94:97]
	v_mfma_f32_16x16x32_bf16 v[90:93], v[188:191], v[228:231], v[90:93]
	v_mfma_f32_16x16x32_bf16 v[78:81], v[180:183], v[236:239], v[78:81]
	v_mfma_f32_16x16x32_bf16 v[74:77], v[188:191], v[236:239], v[74:77]
	v_mfma_f32_16x16x32_bf16 v[118:121], v[192:195], v[208:211], v[118:121]
	v_mfma_f32_16x16x32_bf16 v[114:117], v[200:203], v[208:211], v[114:117]
	v_mfma_f32_16x16x32_bf16 v[102:105], v[192:195], v[216:219], v[102:105]
	v_mfma_f32_16x16x32_bf16 v[98:101], v[200:203], v[216:219], v[98:101]
	v_mfma_f32_16x16x32_bf16 v[86:89], v[192:195], v[224:227], v[86:89]
	v_mfma_f32_16x16x32_bf16 v[82:85], v[200:203], v[224:227], v[82:85]
	v_mfma_f32_16x16x32_bf16 v[70:73], v[192:195], v[232:235], v[70:73]
	v_mfma_f32_16x16x32_bf16 v[66:69], v[200:203], v[232:235], v[66:69]
	v_mfma_f32_16x16x32_bf16 v[118:121], v[196:199], v[212:215], v[118:121]
	v_mfma_f32_16x16x32_bf16 v[114:117], v[204:207], v[212:215], v[114:117]
	v_mfma_f32_16x16x32_bf16 v[102:105], v[196:199], v[220:223], v[102:105]
	v_mfma_f32_16x16x32_bf16 v[98:101], v[204:207], v[220:223], v[98:101]
	v_mfma_f32_16x16x32_bf16 v[86:89], v[196:199], v[228:231], v[86:89]
	v_mfma_f32_16x16x32_bf16 v[82:85], v[204:207], v[228:231], v[82:85]
	v_mfma_f32_16x16x32_bf16 v[70:73], v[196:199], v[236:239], v[70:73]
	v_mfma_f32_16x16x32_bf16 v[66:69], v[204:207], v[236:239], v[66:69]
	s_setprio 0
	s_barrier
	s_add_i32 s62, s56, s45
	v_lshl_add_u64 v[176:177], s[38:39], 0, v[132:133]
	s_mov_b32 m0, s62
	ds_read_b128 v[208:211], v175 offset:16384
	ds_read_b128 v[212:215], v175 offset:17408
	ds_read_b128 v[216:219], v175 offset:18432
	ds_read_b128 v[220:223], v175 offset:19456
	ds_read_b128 v[224:227], v175 offset:20480
	ds_read_b128 v[228:231], v175 offset:21504
	ds_read_b128 v[232:235], v175 offset:22528
	ds_read_b128 v[236:239], v175 offset:23552
	global_load_lds_dwordx4 v[176:177], off
	s_add_i32 m0, s62, 0x2000
	s_add_u32 s62, s38, 0x40000
	v_lshl_add_u64 v[240:241], s[38:39], 0, v[136:137]
	s_addc_u32 s63, s39, 0
	s_add_i32 s64, s57, s45
	global_load_lds_dwordx4 v[240:241], off
	v_lshl_add_u64 v[242:243], s[62:63], 0, v[132:133]
	s_mov_b32 m0, s64
	v_lshl_add_u64 v[244:245], s[40:41], 0, v[134:135]
	global_load_lds_dwordx4 v[242:243], off
	v_lshl_add_u64 v[242:243], s[62:63], 0, v[136:137]
	s_add_i32 m0, s64, 0x2000
	s_nop 0
	global_load_lds_dwordx4 v[242:243], off
	v_lshl_add_u64 v[242:243], s[40:41], 0, v[130:131]
	s_mov_b32 m0, s35
	s_nop 0
	global_load_lds_dwordx4 v[242:243], off
	s_mov_b32 m0, s46
	s_nop 0
	global_load_lds_dwordx4 v[244:245], off
	s_waitcnt vmcnt(8)
	s_waitcnt lgkmcnt(0)
	s_barrier
	s_setprio 1
	v_mfma_f32_16x16x32_bf16 v[62:65], v[164:167], v[208:211], v[62:65]
	v_mfma_f32_16x16x32_bf16 v[58:61], v[184:187], v[208:211], v[58:61]
	v_mfma_f32_16x16x32_bf16 v[46:49], v[164:167], v[216:219], v[46:49]
	v_mfma_f32_16x16x32_bf16 v[42:45], v[184:187], v[216:219], v[42:45]
	v_mfma_f32_16x16x32_bf16 v[30:33], v[164:167], v[224:227], v[30:33]
	v_mfma_f32_16x16x32_bf16 v[26:29], v[184:187], v[224:227], v[26:29]
	v_mfma_f32_16x16x32_bf16 v[14:17], v[164:167], v[232:235], v[14:17]
	v_mfma_f32_16x16x32_bf16 v[10:13], v[184:187], v[232:235], v[10:13]
	v_mfma_f32_16x16x32_bf16 v[62:65], v[180:183], v[212:215], v[62:65]
	v_mfma_f32_16x16x32_bf16 v[58:61], v[188:191], v[212:215], v[58:61]
	v_mfma_f32_16x16x32_bf16 v[46:49], v[180:183], v[220:223], v[46:49]
	v_mfma_f32_16x16x32_bf16 v[42:45], v[188:191], v[220:223], v[42:45]
	v_mfma_f32_16x16x32_bf16 v[30:33], v[180:183], v[228:231], v[30:33]
	v_mfma_f32_16x16x32_bf16 v[26:29], v[188:191], v[228:231], v[26:29]
	v_mfma_f32_16x16x32_bf16 v[14:17], v[180:183], v[236:239], v[14:17]
	v_mfma_f32_16x16x32_bf16 v[10:13], v[188:191], v[236:239], v[10:13]
	v_mfma_f32_16x16x32_bf16 v[54:57], v[192:195], v[208:211], v[54:57]
	v_mfma_f32_16x16x32_bf16 v[50:53], v[200:203], v[208:211], v[50:53]
	v_mfma_f32_16x16x32_bf16 v[38:41], v[192:195], v[216:219], v[38:41]
	v_mfma_f32_16x16x32_bf16 v[34:37], v[200:203], v[216:219], v[34:37]
	v_mfma_f32_16x16x32_bf16 v[22:25], v[192:195], v[224:227], v[22:25]
	v_mfma_f32_16x16x32_bf16 v[18:21], v[200:203], v[224:227], v[18:21]
	v_mfma_f32_16x16x32_bf16 v[6:9], v[192:195], v[232:235], v[6:9]
	v_mfma_f32_16x16x32_bf16 v[2:5], v[200:203], v[232:235], v[2:5]
	v_mfma_f32_16x16x32_bf16 v[54:57], v[196:199], v[212:215], v[54:57]
	v_mfma_f32_16x16x32_bf16 v[50:53], v[204:207], v[212:215], v[50:53]
	v_mfma_f32_16x16x32_bf16 v[38:41], v[196:199], v[220:223], v[38:41]
	v_mfma_f32_16x16x32_bf16 v[34:37], v[204:207], v[220:223], v[34:37]
	v_mfma_f32_16x16x32_bf16 v[22:25], v[196:199], v[228:231], v[22:25]
	v_mfma_f32_16x16x32_bf16 v[18:21], v[204:207], v[228:231], v[18:21]
	v_mfma_f32_16x16x32_bf16 v[6:9], v[196:199], v[236:239], v[6:9]
	v_mfma_f32_16x16x32_bf16 v[2:5], v[204:207], v[236:239], v[2:5]
	s_setprio 0
	s_barrier
	s_add_i32 s62, 0, 0x18000
	v_add_u32_e32 v149, s62, v171
	s_add_i32 s63, 0, 0x1c000
	ds_read_b128 v[164:167], v149
	ds_read_b128 v[180:183], v149 offset:1024
	ds_read_b128 v[184:187], v149 offset:2048
	ds_read_b128 v[188:191], v149 offset:3072
	v_add_u32_e32 v149, s63, v171
	ds_read_b128 v[192:195], v149
	ds_read_b128 v[196:199], v149 offset:1024
	ds_read_b128 v[200:203], v149 offset:2048
	ds_read_b128 v[204:207], v149 offset:3072
	s_add_u32 s40, s40, 0x40000
	s_addc_u32 s41, s41, 0
	s_mov_b32 m0, s47
	v_lshl_add_u64 v[246:247], s[40:41], 0, v[130:131]
	ds_read_b128 v[208:211], v175 offset:32768
	ds_read_b128 v[212:215], v175 offset:33792
	ds_read_b128 v[216:219], v175 offset:34816
	ds_read_b128 v[220:223], v175 offset:35840
	ds_read_b128 v[224:227], v175 offset:36864
	ds_read_b128 v[228:231], v175 offset:37888
	ds_read_b128 v[232:235], v175 offset:38912
	ds_read_b128 v[236:239], v175 offset:39936
	global_load_lds_dwordx4 v[246:247], off
	v_lshl_add_u64 v[246:247], s[40:41], 0, v[134:135]
	s_mov_b32 m0, s48
	s_nop 0
	global_load_lds_dwordx4 v[246:247], off
	s_waitcnt vmcnt(8)
	s_waitcnt lgkmcnt(0)
	s_barrier
	s_setprio 1
	v_mfma_f32_16x16x32_bf16 v[126:129], v[164:167], v[208:211], v[126:129]
	v_mfma_f32_16x16x32_bf16 v[122:125], v[184:187], v[208:211], v[122:125]
	v_mfma_f32_16x16x32_bf16 v[110:113], v[164:167], v[216:219], v[110:113]
	v_mfma_f32_16x16x32_bf16 v[106:109], v[184:187], v[216:219], v[106:109]
	v_mfma_f32_16x16x32_bf16 v[94:97], v[164:167], v[224:227], v[94:97]
	v_mfma_f32_16x16x32_bf16 v[90:93], v[184:187], v[224:227], v[90:93]
	v_mfma_f32_16x16x32_bf16 v[78:81], v[164:167], v[232:235], v[78:81]
	v_mfma_f32_16x16x32_bf16 v[74:77], v[184:187], v[232:235], v[74:77]
	v_mfma_f32_16x16x32_bf16 v[126:129], v[180:183], v[212:215], v[126:129]
	v_mfma_f32_16x16x32_bf16 v[122:125], v[188:191], v[212:215], v[122:125]
	v_mfma_f32_16x16x32_bf16 v[110:113], v[180:183], v[220:223], v[110:113]
	v_mfma_f32_16x16x32_bf16 v[106:109], v[188:191], v[220:223], v[106:109]
	v_mfma_f32_16x16x32_bf16 v[94:97], v[180:183], v[228:231], v[94:97]
	v_mfma_f32_16x16x32_bf16 v[90:93], v[188:191], v[228:231], v[90:93]
	v_mfma_f32_16x16x32_bf16 v[78:81], v[180:183], v[236:239], v[78:81]
	v_mfma_f32_16x16x32_bf16 v[74:77], v[188:191], v[236:239], v[74:77]
	v_mfma_f32_16x16x32_bf16 v[118:121], v[192:195], v[208:211], v[118:121]
	v_mfma_f32_16x16x32_bf16 v[114:117], v[200:203], v[208:211], v[114:117]
	v_mfma_f32_16x16x32_bf16 v[102:105], v[192:195], v[216:219], v[102:105]
	v_mfma_f32_16x16x32_bf16 v[98:101], v[200:203], v[216:219], v[98:101]
	v_mfma_f32_16x16x32_bf16 v[86:89], v[192:195], v[224:227], v[86:89]
	v_mfma_f32_16x16x32_bf16 v[82:85], v[200:203], v[224:227], v[82:85]
	v_mfma_f32_16x16x32_bf16 v[70:73], v[192:195], v[232:235], v[70:73]
	v_mfma_f32_16x16x32_bf16 v[66:69], v[200:203], v[232:235], v[66:69]
	v_mfma_f32_16x16x32_bf16 v[118:121], v[196:199], v[212:215], v[118:121]
	v_mfma_f32_16x16x32_bf16 v[114:117], v[204:207], v[212:215], v[114:117]
	v_mfma_f32_16x16x32_bf16 v[102:105], v[196:199], v[220:223], v[102:105]
	v_mfma_f32_16x16x32_bf16 v[98:101], v[204:207], v[220:223], v[98:101]
	v_mfma_f32_16x16x32_bf16 v[86:89], v[196:199], v[228:231], v[86:89]
	v_mfma_f32_16x16x32_bf16 v[82:85], v[204:207], v[228:231], v[82:85]
	v_mfma_f32_16x16x32_bf16 v[70:73], v[196:199], v[236:239], v[70:73]
	v_mfma_f32_16x16x32_bf16 v[66:69], v[204:207], v[236:239], v[66:69]
	s_setprio 0
	s_barrier
	s_add_i32 s40, s62, s45
	v_lshl_add_u64 v[176:177], v[176:177], 0, s[8:9]
	s_mov_b32 m0, s40
	ds_read_b128 v[208:211], v175 offset:49152
	ds_read_b128 v[212:215], v175 offset:50176
	ds_read_b128 v[216:219], v175 offset:51200
	ds_read_b128 v[220:223], v175 offset:52224
	ds_read_b128 v[224:227], v175 offset:53248
	ds_read_b128 v[228:231], v175 offset:54272
	ds_read_b128 v[232:235], v175 offset:55296
	ds_read_b128 v[236:239], v175 offset:56320
	global_load_lds_dwordx4 v[176:177], off
	s_add_i32 m0, s40, 0x2000
	s_add_u32 s38, s38, 0x40080
	v_lshl_add_u64 v[176:177], v[240:241], 0, s[8:9]
	s_addc_u32 s39, s39, 0
	s_add_i32 s40, s63, s45
	global_load_lds_dwordx4 v[176:177], off
	v_lshl_add_u64 v[176:177], s[38:39], 0, v[132:133]
	s_mov_b32 m0, s40
	s_nop 0
	global_load_lds_dwordx4 v[176:177], off
	v_lshl_add_u64 v[176:177], s[38:39], 0, v[136:137]
	s_add_i32 m0, s40, 0x2000
	s_nop 0
	global_load_lds_dwordx4 v[176:177], off
	v_lshl_add_u64 v[176:177], v[242:243], 0, s[8:9]
	s_mov_b32 m0, s51
	s_nop 0
	global_load_lds_dwordx4 v[176:177], off
	v_lshl_add_u64 v[176:177], v[244:245], 0, s[8:9]
	s_mov_b32 m0, s52
	s_nop 0
	global_load_lds_dwordx4 v[176:177], off
	s_waitcnt vmcnt(8)
	s_waitcnt lgkmcnt(0)
	s_barrier
	s_setprio 1
	v_mfma_f32_16x16x32_bf16 v[62:65], v[164:167], v[208:211], v[62:65]
	v_mfma_f32_16x16x32_bf16 v[58:61], v[184:187], v[208:211], v[58:61]
	v_mfma_f32_16x16x32_bf16 v[46:49], v[164:167], v[216:219], v[46:49]
	v_mfma_f32_16x16x32_bf16 v[42:45], v[184:187], v[216:219], v[42:45]
	v_mfma_f32_16x16x32_bf16 v[30:33], v[164:167], v[224:227], v[30:33]
	v_mfma_f32_16x16x32_bf16 v[26:29], v[184:187], v[224:227], v[26:29]
	v_mfma_f32_16x16x32_bf16 v[14:17], v[164:167], v[232:235], v[14:17]
	v_mfma_f32_16x16x32_bf16 v[10:13], v[184:187], v[232:235], v[10:13]
	v_mfma_f32_16x16x32_bf16 v[62:65], v[180:183], v[212:215], v[62:65]
	v_mfma_f32_16x16x32_bf16 v[58:61], v[188:191], v[212:215], v[58:61]
	v_mfma_f32_16x16x32_bf16 v[46:49], v[180:183], v[220:223], v[46:49]
	v_mfma_f32_16x16x32_bf16 v[42:45], v[188:191], v[220:223], v[42:45]
	v_mfma_f32_16x16x32_bf16 v[30:33], v[180:183], v[228:231], v[30:33]
	v_mfma_f32_16x16x32_bf16 v[26:29], v[188:191], v[228:231], v[26:29]
	v_mfma_f32_16x16x32_bf16 v[14:17], v[180:183], v[236:239], v[14:17]
	v_mfma_f32_16x16x32_bf16 v[10:13], v[188:191], v[236:239], v[10:13]
	v_mfma_f32_16x16x32_bf16 v[54:57], v[192:195], v[208:211], v[54:57]
	v_mfma_f32_16x16x32_bf16 v[50:53], v[200:203], v[208:211], v[50:53]
	v_mfma_f32_16x16x32_bf16 v[38:41], v[192:195], v[216:219], v[38:41]
	v_mfma_f32_16x16x32_bf16 v[34:37], v[200:203], v[216:219], v[34:37]
	v_mfma_f32_16x16x32_bf16 v[22:25], v[192:195], v[224:227], v[22:25]
	v_mfma_f32_16x16x32_bf16 v[18:21], v[200:203], v[224:227], v[18:21]
	v_mfma_f32_16x16x32_bf16 v[6:9], v[192:195], v[232:235], v[6:9]
	v_mfma_f32_16x16x32_bf16 v[2:5], v[200:203], v[232:235], v[2:5]
	v_mfma_f32_16x16x32_bf16 v[54:57], v[196:199], v[212:215], v[54:57]
	v_mfma_f32_16x16x32_bf16 v[50:53], v[204:207], v[212:215], v[50:53]
	v_mfma_f32_16x16x32_bf16 v[38:41], v[196:199], v[220:223], v[38:41]
	v_mfma_f32_16x16x32_bf16 v[34:37], v[204:207], v[220:223], v[34:37]
	v_mfma_f32_16x16x32_bf16 v[22:25], v[196:199], v[228:231], v[22:25]
	v_mfma_f32_16x16x32_bf16 v[18:21], v[204:207], v[228:231], v[18:21]
	v_mfma_f32_16x16x32_bf16 v[6:9], v[196:199], v[236:239], v[6:9]
	v_mfma_f32_16x16x32_bf16 v[2:5], v[204:207], v[236:239], v[2:5]
	s_setprio 0
	s_barrier
	s_add_i32 s61, s61, 2
	s_add_u32 s59, s59, 0x100
	s_addc_u32 s60, s60, 0
	s_add_u32 s36, s36, 0x100
	s_addc_u32 s37, s37, 0
	s_cmp_gt_u32 s61, 13
	s_cbranch_scc0 .LBB0_858
	s_andn2_b64 vcc, exec, s[2:3]
	s_cbranch_vccnz .Lrs8h_skip1
	v_lshl_add_u32 v188, s24, 8, v170
	v_ashrrev_i32_e32 v189, 31, v188
	v_lshlrev_b64 v[180:181], 6, v[188:189]
	v_lshl_add_u64 v[196:197], v[138:139], 0, v[180:181]
	v_or_b32_e32 v180, 16, v188
	v_or_b32_e32 v190, 32, v188
	v_or_b32_e32 v188, 48, v188
	v_ashrrev_i32_e32 v181, 31, v180
	v_ashrrev_i32_e32 v191, 31, v190
	v_ashrrev_i32_e32 v189, 31, v188
	v_lshlrev_b64 v[180:181], 6, v[180:181]
	v_lshlrev_b64 v[190:191], 6, v[190:191]
	v_lshlrev_b64 v[188:189], 6, v[188:189]
	v_add_co_u32_e32 v208, vcc, s49, v196
	v_lshl_add_u64 v[184:185], v[138:139], 0, v[180:181]
	v_lshl_add_u64 v[190:191], v[138:139], 0, v[190:191]
	v_lshl_add_u64 v[192:193], v[138:139], 0, v[188:189]
	v_addc_co_u32_e32 v209, vcc, 0, v197, vcc
	flat_load_dwordx4 v[180:183], v[196:197]
	s_nop 0
	flat_load_dwordx4 v[184:187], v[184:185]
	s_nop 0
	flat_load_dwordx4 v[188:191], v[190:191]
	s_nop 0
	flat_load_dwordx4 v[192:195], v[192:193]
	s_nop 0
	flat_load_dwordx4 v[196:199], v[208:209]
	flat_load_dwordx4 v[200:203], v[208:209] offset:1024
	flat_load_dwordx4 v[204:207], v[208:209] offset:2048
	s_nop 0
	flat_load_dwordx4 v[208:211], v[208:209] offset:3072

.LBB0_1039:
	v_add_u32_e32 v154, s62, v156
	ds_read_b128 v[130:133], v154
	ds_read_b128 v[150:153], v154 offset:1024
	ds_read_b128 v[160:163], v154 offset:2048
	ds_read_b128 v[164:167], v154 offset:3072
	v_add_u32_e32 v154, s63, v156
	ds_read_b128 v[168:171], v154
	ds_read_b128 v[172:175], v154 offset:1024
	ds_read_b128 v[180:183], v154 offset:2048
	ds_read_b128 v[184:187], v154 offset:3072
	s_add_u32 s42, s40, 0xfff00080
	s_addc_u32 s43, s41, -1
	s_cmp_eq_u32 s68, 60
	s_cselect_b32 s45, s31, s43
	s_cselect_b32 s44, s39, s42
	s_cselect_b32 s43, s29, s67
	s_cselect_b32 s42, s65, s66
	v_lshl_add_u64 v[154:155], s[40:41], 0, v[144:145]
	s_add_i32 m0, s51, 0xc000
	ds_read_b128 v[188:191], v158
	ds_read_b128 v[192:195], v158 offset:1024
	ds_read_b128 v[196:199], v158 offset:2048
	ds_read_b128 v[200:203], v158 offset:3072
	ds_read_b128 v[204:207], v158 offset:4096
	ds_read_b128 v[208:211], v158 offset:5120
	ds_read_b128 v[212:215], v158 offset:6144
	ds_read_b128 v[216:219], v158 offset:7168
	global_load_lds_dwordx4 v[154:155], off
	v_lshl_add_u64 v[154:155], s[40:41], 0, v[142:143]
	s_add_i32 m0, s51, 0xe000
	s_nop 0
	global_load_lds_dwordx4 v[154:155], off
	s_waitcnt vmcnt(8)
	s_waitcnt lgkmcnt(0)
	s_barrier
	s_setprio 1
	v_mfma_f32_16x16x32_bf16 v[114:117], v[130:133], v[188:191], v[114:117]
	v_mfma_f32_16x16x32_bf16 v[118:121], v[160:163], v[188:191], v[118:121]
	v_mfma_f32_16x16x32_bf16 v[98:101], v[130:133], v[196:199], v[98:101]
	v_mfma_f32_16x16x32_bf16 v[102:105], v[160:163], v[196:199], v[102:105]
	v_mfma_f32_16x16x32_bf16 v[82:85], v[130:133], v[204:207], v[82:85]
	v_mfma_f32_16x16x32_bf16 v[86:89], v[160:163], v[204:207], v[86:89]
	v_mfma_f32_16x16x32_bf16 v[66:69], v[130:133], v[212:215], v[66:69]
	v_mfma_f32_16x16x32_bf16 v[70:73], v[160:163], v[212:215], v[70:73]
	v_mfma_f32_16x16x32_bf16 v[114:117], v[150:153], v[192:195], v[114:117]
	v_mfma_f32_16x16x32_bf16 v[118:121], v[164:167], v[192:195], v[118:121]
	v_mfma_f32_16x16x32_bf16 v[98:101], v[150:153], v[200:203], v[98:101]
	v_mfma_f32_16x16x32_bf16 v[102:105], v[164:167], v[200:203], v[102:105]
	v_mfma_f32_16x16x32_bf16 v[82:85], v[150:153], v[208:211], v[82:85]
	v_mfma_f32_16x16x32_bf16 v[86:89], v[164:167], v[208:211], v[86:89]
	v_mfma_f32_16x16x32_bf16 v[66:69], v[150:153], v[216:219], v[66:69]
	v_mfma_f32_16x16x32_bf16 v[70:73], v[164:167], v[216:219], v[70:73]
	v_mfma_f32_16x16x32_bf16 v[122:125], v[168:171], v[188:191], v[122:125]
	v_mfma_f32_16x16x32_bf16 v[126:129], v[180:183], v[188:191], v[126:129]
	v_mfma_f32_16x16x32_bf16 v[106:109], v[168:171], v[196:199], v[106:109]
	v_mfma_f32_16x16x32_bf16 v[110:113], v[180:183], v[196:199], v[110:113]
	v_mfma_f32_16x16x32_bf16 v[90:93], v[168:171], v[204:207], v[90:93]
	v_mfma_f32_16x16x32_bf16 v[94:97], v[180:183], v[204:207], v[94:97]
	v_mfma_f32_16x16x32_bf16 v[74:77], v[168:171], v[212:215], v[74:77]
	v_mfma_f32_16x16x32_bf16 v[78:81], v[180:183], v[212:215], v[78:81]
	v_mfma_f32_16x16x32_bf16 v[122:125], v[172:175], v[192:195], v[122:125]
	v_mfma_f32_16x16x32_bf16 v[126:129], v[184:187], v[192:195], v[126:129]
	v_mfma_f32_16x16x32_bf16 v[106:109], v[172:175], v[200:203], v[106:109]
	v_mfma_f32_16x16x32_bf16 v[110:113], v[184:187], v[200:203], v[110:113]
	v_mfma_f32_16x16x32_bf16 v[90:93], v[172:175], v[208:211], v[90:93]
	v_mfma_f32_16x16x32_bf16 v[94:97], v[184:187], v[208:211], v[94:97]
	v_mfma_f32_16x16x32_bf16 v[74:77], v[172:175], v[216:219], v[74:77]
	v_mfma_f32_16x16x32_bf16 v[78:81], v[184:187], v[216:219], v[78:81]
	s_setprio 0
	s_barrier
	s_add_i32 s69, s62, s50
	v_lshl_add_u64 v[154:155], s[42:43], 0, v[136:137]
	s_mov_b32 m0, s69
	ds_read_b128 v[188:191], v158 offset:16384
	ds_read_b128 v[192:195], v158 offset:17408
	ds_read_b128 v[196:199], v158 offset:18432
	ds_read_b128 v[200:203], v158 offset:19456
	ds_read_b128 v[204:207], v158 offset:20480
	ds_read_b128 v[208:211], v158 offset:21504
	ds_read_b128 v[212:215], v158 offset:22528
	ds_read_b128 v[216:219], v158 offset:23552
	global_load_lds_dwordx4 v[154:155], off
	s_add_i32 m0, s69, 0x2000
	s_add_u32 s70, s42, 0x100000
	v_lshl_add_u64 v[176:177], s[42:43], 0, v[140:141]
	s_addc_u32 s71, s43, 0
	s_add_i32 s69, s63, s50
	global_load_lds_dwordx4 v[176:177], off
	v_lshl_add_u64 v[220:221], s[70:71], 0, v[136:137]
	s_mov_b32 m0, s69
	v_lshl_add_u64 v[222:223], s[44:45], 0, v[138:139]
	global_load_lds_dwordx4 v[220:221], off
	v_lshl_add_u64 v[220:221], s[70:71], 0, v[140:141]
	s_add_i32 m0, s69, 0x2000
	s_nop 0
	global_load_lds_dwordx4 v[220:221], off
	v_lshl_add_u64 v[220:221], s[44:45], 0, v[134:135]
	s_mov_b32 m0, s51
	s_nop 0
	global_load_lds_dwordx4 v[220:221], off
	s_mov_b32 m0, s52
	s_nop 0
	global_load_lds_dwordx4 v[222:223], off
	s_waitcnt vmcnt(8)
	s_waitcnt lgkmcnt(0)
	s_barrier
	s_setprio 1
	v_mfma_f32_16x16x32_bf16 v[50:53], v[130:133], v[188:191], v[50:53]
	v_mfma_f32_16x16x32_bf16 v[54:57], v[160:163], v[188:191], v[54:57]
	v_mfma_f32_16x16x32_bf16 v[26:29], v[130:133], v[196:199], v[26:29]
	v_mfma_f32_16x16x32_bf16 v[30:33], v[160:163], v[196:199], v[30:33]
	v_mfma_f32_16x16x32_bf16 v[18:21], v[130:133], v[204:207], v[18:21]
	v_mfma_f32_16x16x32_bf16 v[22:25], v[160:163], v[204:207], v[22:25]
	v_mfma_f32_16x16x32_bf16 v[2:5], v[130:133], v[212:215], v[2:5]
	v_mfma_f32_16x16x32_bf16 v[6:9], v[160:163], v[212:215], v[6:9]
	v_mfma_f32_16x16x32_bf16 v[50:53], v[150:153], v[192:195], v[50:53]
	v_mfma_f32_16x16x32_bf16 v[54:57], v[164:167], v[192:195], v[54:57]
	v_mfma_f32_16x16x32_bf16 v[26:29], v[150:153], v[200:203], v[26:29]
	v_mfma_f32_16x16x32_bf16 v[30:33], v[164:167], v[200:203], v[30:33]
	v_mfma_f32_16x16x32_bf16 v[18:21], v[150:153], v[208:211], v[18:21]
	v_mfma_f32_16x16x32_bf16 v[22:25], v[164:167], v[208:211], v[22:25]
	v_mfma_f32_16x16x32_bf16 v[2:5], v[150:153], v[216:219], v[2:5]
	v_mfma_f32_16x16x32_bf16 v[6:9], v[164:167], v[216:219], v[6:9]
	v_mfma_f32_16x16x32_bf16 v[58:61], v[168:171], v[188:191], v[58:61]
	v_mfma_f32_16x16x32_bf16 v[62:65], v[180:183], v[188:191], v[62:65]
	v_mfma_f32_16x16x32_bf16 v[42:45], v[168:171], v[196:199], v[42:45]
	v_mfma_f32_16x16x32_bf16 v[46:49], v[180:183], v[196:199], v[46:49]
	v_mfma_f32_16x16x32_bf16 v[34:37], v[168:171], v[204:207], v[34:37]
	v_mfma_f32_16x16x32_bf16 v[38:41], v[180:183], v[204:207], v[38:41]
	v_mfma_f32_16x16x32_bf16 v[10:13], v[168:171], v[212:215], v[10:13]
	v_mfma_f32_16x16x32_bf16 v[14:17], v[180:183], v[212:215], v[14:17]
	v_mfma_f32_16x16x32_bf16 v[58:61], v[172:175], v[192:195], v[58:61]
	v_mfma_f32_16x16x32_bf16 v[62:65], v[184:187], v[192:195], v[62:65]
	v_mfma_f32_16x16x32_bf16 v[42:45], v[172:175], v[200:203], v[42:45]
	v_mfma_f32_16x16x32_bf16 v[46:49], v[184:187], v[200:203], v[46:49]
	v_mfma_f32_16x16x32_bf16 v[34:37], v[172:175], v[208:211], v[34:37]
	v_mfma_f32_16x16x32_bf16 v[38:41], v[184:187], v[208:211], v[38:41]
	v_mfma_f32_16x16x32_bf16 v[10:13], v[172:175], v[216:219], v[10:13]
	v_mfma_f32_16x16x32_bf16 v[14:17], v[184:187], v[216:219], v[14:17]
	s_setprio 0
	s_barrier
	s_add_i32 s69, 0, 0x18000
	s_add_i32 s70, 0, 0x1c000
	v_add_u32_e32 v164, s69, v156
	v_add_u32_e32 v179, s70, v156
	ds_read_b128 v[130:133], v164
	ds_read_b128 v[150:153], v164 offset:1024
	ds_read_b128 v[160:163], v164 offset:2048
	ds_read_b128 v[164:167], v164 offset:3072
	ds_read_b128 v[168:171], v179
	ds_read_b128 v[172:175], v179 offset:1024
	ds_read_b128 v[180:183], v179 offset:2048
	ds_read_b128 v[184:187], v179 offset:3072
	s_add_u32 s44, s44, 0x100000
	s_addc_u32 s45, s45, 0
	s_mov_b32 m0, s53
	v_lshl_add_u64 v[224:225], s[44:45], 0, v[134:135]
	ds_read_b128 v[188:191], v158 offset:32768
	ds_read_b128 v[192:195], v158 offset:33792
	ds_read_b128 v[196:199], v158 offset:34816
	ds_read_b128 v[200:203], v158 offset:35840
	ds_read_b128 v[204:207], v158 offset:36864
	ds_read_b128 v[208:211], v158 offset:37888
	ds_read_b128 v[212:215], v158 offset:38912
	ds_read_b128 v[216:219], v158 offset:39936
	global_load_lds_dwordx4 v[224:225], off
	v_lshl_add_u64 v[224:225], s[44:45], 0, v[138:139]
	s_mov_b32 m0, s54
	s_nop 0
	global_load_lds_dwordx4 v[224:225], off
	s_waitcnt vmcnt(8)
	s_waitcnt lgkmcnt(0)
	s_barrier
	s_setprio 1
	v_mfma_f32_16x16x32_bf16 v[114:117], v[130:133], v[188:191], v[114:117]
	v_mfma_f32_16x16x32_bf16 v[118:121], v[160:163], v[188:191], v[118:121]
	v_mfma_f32_16x16x32_bf16 v[98:101], v[130:133], v[196:199], v[98:101]
	v_mfma_f32_16x16x32_bf16 v[102:105], v[160:163], v[196:199], v[102:105]
	v_mfma_f32_16x16x32_bf16 v[82:85], v[130:133], v[204:207], v[82:85]
	v_mfma_f32_16x16x32_bf16 v[86:89], v[160:163], v[204:207], v[86:89]
	v_mfma_f32_16x16x32_bf16 v[66:69], v[130:133], v[212:215], v[66:69]
	v_mfma_f32_16x16x32_bf16 v[70:73], v[160:163], v[212:215], v[70:73]
	v_mfma_f32_16x16x32_bf16 v[114:117], v[150:153], v[192:195], v[114:117]
	v_mfma_f32_16x16x32_bf16 v[118:121], v[164:167], v[192:195], v[118:121]
	v_mfma_f32_16x16x32_bf16 v[98:101], v[150:153], v[200:203], v[98:101]
	v_mfma_f32_16x16x32_bf16 v[102:105], v[164:167], v[200:203], v[102:105]
	v_mfma_f32_16x16x32_bf16 v[82:85], v[150:153], v[208:211], v[82:85]
	v_mfma_f32_16x16x32_bf16 v[86:89], v[164:167], v[208:211], v[86:89]
	v_mfma_f32_16x16x32_bf16 v[66:69], v[150:153], v[216:219], v[66:69]
	v_mfma_f32_16x16x32_bf16 v[70:73], v[164:167], v[216:219], v[70:73]
	v_mfma_f32_16x16x32_bf16 v[122:125], v[168:171], v[188:191], v[122:125]
	v_mfma_f32_16x16x32_bf16 v[126:129], v[180:183], v[188:191], v[126:129]
	v_mfma_f32_16x16x32_bf16 v[106:109], v[168:171], v[196:199], v[106:109]
	v_mfma_f32_16x16x32_bf16 v[110:113], v[180:183], v[196:199], v[110:113]
	v_mfma_f32_16x16x32_bf16 v[90:93], v[168:171], v[204:207], v[90:93]
	v_mfma_f32_16x16x32_bf16 v[94:97], v[180:183], v[204:207], v[94:97]
	v_mfma_f32_16x16x32_bf16 v[74:77], v[168:171], v[212:215], v[74:77]
	v_mfma_f32_16x16x32_bf16 v[78:81], v[180:183], v[212:215], v[78:81]
	v_mfma_f32_16x16x32_bf16 v[122:125], v[172:175], v[192:195], v[122:125]
	v_mfma_f32_16x16x32_bf16 v[126:129], v[184:187], v[192:195], v[126:129]
	v_mfma_f32_16x16x32_bf16 v[106:109], v[172:175], v[200:203], v[106:109]
	v_mfma_f32_16x16x32_bf16 v[110:113], v[184:187], v[200:203], v[110:113]
	v_mfma_f32_16x16x32_bf16 v[90:93], v[172:175], v[208:211], v[90:93]
	v_mfma_f32_16x16x32_bf16 v[94:97], v[184:187], v[208:211], v[94:97]
	v_mfma_f32_16x16x32_bf16 v[74:77], v[172:175], v[216:219], v[74:77]
	v_mfma_f32_16x16x32_bf16 v[78:81], v[184:187], v[216:219], v[78:81]
	s_setprio 0
	s_barrier
	s_add_i32 s44, s69, s50
	v_lshl_add_u64 v[154:155], v[154:155], 0, s[22:23]
	s_mov_b32 m0, s44
	ds_read_b128 v[188:191], v158 offset:49152
	ds_read_b128 v[192:195], v158 offset:50176
	ds_read_b128 v[196:199], v158 offset:51200
	ds_read_b128 v[200:203], v158 offset:52224
	ds_read_b128 v[204:207], v158 offset:53248
	ds_read_b128 v[208:211], v158 offset:54272
	ds_read_b128 v[212:215], v158 offset:55296
	ds_read_b128 v[216:219], v158 offset:56320
	global_load_lds_dwordx4 v[154:155], off
	s_add_i32 m0, s44, 0x2000
	s_add_u32 s42, s42, 0x100080
	v_lshl_add_u64 v[154:155], v[176:177], 0, s[22:23]
	s_addc_u32 s43, s43, 0
	s_add_i32 s44, s70, s50
	global_load_lds_dwordx4 v[154:155], off
	v_lshl_add_u64 v[154:155], s[42:43], 0, v[136:137]
	s_mov_b32 m0, s44
	s_nop 0
	global_load_lds_dwordx4 v[154:155], off
	v_lshl_add_u64 v[154:155], s[42:43], 0, v[140:141]
	s_add_i32 m0, s44, 0x2000
	s_nop 0
	global_load_lds_dwordx4 v[154:155], off
	v_lshl_add_u64 v[154:155], v[220:221], 0, s[22:23]
	s_mov_b32 m0, s57
	s_nop 0
	global_load_lds_dwordx4 v[154:155], off
	v_lshl_add_u64 v[154:155], v[222:223], 0, s[22:23]
	s_mov_b32 m0, s58
	s_nop 0
	global_load_lds_dwordx4 v[154:155], off
	s_waitcnt vmcnt(8)
	s_waitcnt lgkmcnt(0)
	s_barrier
	s_setprio 1
	v_mfma_f32_16x16x32_bf16 v[50:53], v[130:133], v[188:191], v[50:53]
	v_mfma_f32_16x16x32_bf16 v[54:57], v[160:163], v[188:191], v[54:57]
	v_mfma_f32_16x16x32_bf16 v[26:29], v[130:133], v[196:199], v[26:29]
	v_mfma_f32_16x16x32_bf16 v[30:33], v[160:163], v[196:199], v[30:33]
	v_mfma_f32_16x16x32_bf16 v[18:21], v[130:133], v[204:207], v[18:21]
	v_mfma_f32_16x16x32_bf16 v[22:25], v[160:163], v[204:207], v[22:25]
	v_mfma_f32_16x16x32_bf16 v[2:5], v[130:133], v[212:215], v[2:5]
	v_mfma_f32_16x16x32_bf16 v[6:9], v[160:163], v[212:215], v[6:9]
	v_mfma_f32_16x16x32_bf16 v[50:53], v[150:153], v[192:195], v[50:53]
	v_mfma_f32_16x16x32_bf16 v[54:57], v[164:167], v[192:195], v[54:57]
	v_mfma_f32_16x16x32_bf16 v[26:29], v[150:153], v[200:203], v[26:29]
	v_mfma_f32_16x16x32_bf16 v[30:33], v[164:167], v[200:203], v[30:33]
	v_mfma_f32_16x16x32_bf16 v[18:21], v[150:153], v[208:211], v[18:21]
	v_mfma_f32_16x16x32_bf16 v[22:25], v[164:167], v[208:211], v[22:25]
	v_mfma_f32_16x16x32_bf16 v[2:5], v[150:153], v[216:219], v[2:5]
	v_mfma_f32_16x16x32_bf16 v[6:9], v[164:167], v[216:219], v[6:9]
	v_mfma_f32_16x16x32_bf16 v[58:61], v[168:171], v[188:191], v[58:61]
	v_mfma_f32_16x16x32_bf16 v[62:65], v[180:183], v[188:191], v[62:65]
	v_mfma_f32_16x16x32_bf16 v[42:45], v[168:171], v[196:199], v[42:45]
	v_mfma_f32_16x16x32_bf16 v[46:49], v[180:183], v[196:199], v[46:49]
	v_mfma_f32_16x16x32_bf16 v[34:37], v[168:171], v[204:207], v[34:37]
	v_mfma_f32_16x16x32_bf16 v[38:41], v[180:183], v[204:207], v[38:41]
	v_mfma_f32_16x16x32_bf16 v[10:13], v[168:171], v[212:215], v[10:13]
	v_mfma_f32_16x16x32_bf16 v[14:17], v[180:183], v[212:215], v[14:17]
	v_mfma_f32_16x16x32_bf16 v[58:61], v[172:175], v[192:195], v[58:61]
	v_mfma_f32_16x16x32_bf16 v[62:65], v[184:187], v[192:195], v[62:65]
	v_mfma_f32_16x16x32_bf16 v[42:45], v[172:175], v[200:203], v[42:45]
	v_mfma_f32_16x16x32_bf16 v[46:49], v[184:187], v[200:203], v[46:49]
	v_mfma_f32_16x16x32_bf16 v[34:37], v[172:175], v[208:211], v[34:37]
	v_mfma_f32_16x16x32_bf16 v[38:41], v[184:187], v[208:211], v[38:41]
	v_mfma_f32_16x16x32_bf16 v[10:13], v[172:175], v[216:219], v[10:13]
	v_mfma_f32_16x16x32_bf16 v[14:17], v[184:187], v[216:219], v[14:17]
	s_setprio 0
	s_barrier
	s_add_i32 s68, s68, 2
	s_add_u32 s66, s66, 0x100
	s_addc_u32 s67, s67, 0
	s_add_u32 s40, s40, 0x100
	s_addc_u32 s41, s41, 0
	s_cmp_gt_u32 s68, 61
	s_cbranch_scc0 .LBB0_1039
	s_and_b64 vcc, exec, s[24:25]
	s_cbranch_vccz .LBB0_1042
	s_barrier

.LBB0_1216:
	s_add_u32 s45, s38, s44
	s_addc_u32 s50, s39, 0
	s_add_u32 s48, s45, 0x100
	s_addc_u32 s49, s50, 0
	s_and_b64 s[46:47], s[42:43], exec
	s_cselect_b32 s47, s25, s49
	s_cselect_b32 s46, s31, s48
	s_add_u32 s44, s36, s44
	s_addc_u32 s48, s37, 0
	s_add_u32 s44, s44, 0x100
	s_addc_u32 s48, s48, 0
	s_and_b64 s[42:43], s[42:43], exec
	s_cselect_b32 s49, s23, s48
	s_cselect_b32 s48, s69, s44
	s_add_u32 s52, s45, 0x10080
	ds_read_b128 v[142:145], v148
	ds_read_b128 v[152:155], v148 offset:1024
	ds_read_b128 v[156:159], v148 offset:2048
	ds_read_b128 v[160:163], v148 offset:3072
	ds_read_b128 v[164:167], v149
	ds_read_b128 v[168:171], v149 offset:1024
	ds_read_b128 v[172:175], v149 offset:2048
	ds_read_b128 v[180:183], v149 offset:3072
	s_addc_u32 s53, s50, 0
	s_add_i32 s77, s67, s57
	s_add_i32 m0, s35, 0xc000
	s_add_i32 s80, s35, 0xe000
	s_add_i32 s74, s77, 0x2000
	s_add_u32 s50, s48, 0x10000
	s_addc_u32 s51, s49, 0
	s_add_i32 s76, s68, s57
	s_add_i32 s75, s76, 0x2000
	s_add_i32 s73, 0, 0x18000
	s_add_i32 s72, 0, 0x1c000
	s_add_u32 s44, s46, 0x10000
	s_addc_u32 s45, s47, 0
	s_add_i32 s71, s73, s57
	s_add_i32 s70, s71, 0x2000
	s_add_u32 s42, s48, 0x10080
	s_addc_u32 s43, s49, 0
	s_add_i32 s79, s72, s57
	s_add_i32 s78, s79, 0x2000
	v_lshl_add_u64 v[176:177], s[52:53], 0, v[130:131]
	ds_read_b128 v[184:187], v150
	ds_read_b128 v[188:191], v150 offset:1024
	ds_read_b128 v[192:195], v150 offset:2048
	ds_read_b128 v[196:199], v150 offset:3072
	ds_read_b128 v[200:203], v150 offset:4096
	ds_read_b128 v[204:207], v150 offset:5120
	ds_read_b128 v[208:211], v150 offset:6144
	ds_read_b128 v[212:215], v150 offset:7168
	global_load_lds_dwordx4 v[176:177], off
	v_lshl_add_u64 v[176:177], s[52:53], 0, v[134:135]
	s_mov_b32 m0, s80
	s_nop 0
	global_load_lds_dwordx4 v[176:177], off
	s_waitcnt vmcnt(8)
	s_waitcnt lgkmcnt(0)
	s_barrier
	s_setprio 1
	v_mfma_f32_16x16x32_bf16 v[126:129], v[142:145], v[184:187], v[126:129]
	v_mfma_f32_16x16x32_bf16 v[122:125], v[156:159], v[184:187], v[122:125]
	v_mfma_f32_16x16x32_bf16 v[110:113], v[142:145], v[192:195], v[110:113]
	v_mfma_f32_16x16x32_bf16 v[106:109], v[156:159], v[192:195], v[106:109]
	v_mfma_f32_16x16x32_bf16 v[94:97], v[142:145], v[200:203], v[94:97]
	v_mfma_f32_16x16x32_bf16 v[90:93], v[156:159], v[200:203], v[90:93]
	v_mfma_f32_16x16x32_bf16 v[78:81], v[142:145], v[208:211], v[78:81]
	v_mfma_f32_16x16x32_bf16 v[74:77], v[156:159], v[208:211], v[74:77]
	v_mfma_f32_16x16x32_bf16 v[126:129], v[152:155], v[188:191], v[126:129]
	v_mfma_f32_16x16x32_bf16 v[122:125], v[160:163], v[188:191], v[122:125]
	v_mfma_f32_16x16x32_bf16 v[110:113], v[152:155], v[196:199], v[110:113]
	v_mfma_f32_16x16x32_bf16 v[106:109], v[160:163], v[196:199], v[106:109]
	v_mfma_f32_16x16x32_bf16 v[94:97], v[152:155], v[204:207], v[94:97]
	v_mfma_f32_16x16x32_bf16 v[90:93], v[160:163], v[204:207], v[90:93]
	v_mfma_f32_16x16x32_bf16 v[78:81], v[152:155], v[212:215], v[78:81]
	v_mfma_f32_16x16x32_bf16 v[74:77], v[160:163], v[212:215], v[74:77]
	v_mfma_f32_16x16x32_bf16 v[118:121], v[164:167], v[184:187], v[118:121]
	v_mfma_f32_16x16x32_bf16 v[114:117], v[172:175], v[184:187], v[114:117]
	v_mfma_f32_16x16x32_bf16 v[102:105], v[164:167], v[192:195], v[102:105]
	v_mfma_f32_16x16x32_bf16 v[98:101], v[172:175], v[192:195], v[98:101]
	v_mfma_f32_16x16x32_bf16 v[86:89], v[164:167], v[200:203], v[86:89]
	v_mfma_f32_16x16x32_bf16 v[82:85], v[172:175], v[200:203], v[82:85]
	v_mfma_f32_16x16x32_bf16 v[70:73], v[164:167], v[208:211], v[70:73]
	v_mfma_f32_16x16x32_bf16 v[66:69], v[172:175], v[208:211], v[66:69]
	v_mfma_f32_16x16x32_bf16 v[118:121], v[168:171], v[188:191], v[118:121]
	v_mfma_f32_16x16x32_bf16 v[114:117], v[180:183], v[188:191], v[114:117]
	v_mfma_f32_16x16x32_bf16 v[102:105], v[168:171], v[196:199], v[102:105]
	v_mfma_f32_16x16x32_bf16 v[98:101], v[180:183], v[196:199], v[98:101]
	v_mfma_f32_16x16x32_bf16 v[86:89], v[168:171], v[204:207], v[86:89]
	v_mfma_f32_16x16x32_bf16 v[82:85], v[180:183], v[204:207], v[82:85]
	v_mfma_f32_16x16x32_bf16 v[70:73], v[168:171], v[212:215], v[70:73]
	v_mfma_f32_16x16x32_bf16 v[66:69], v[180:183], v[212:215], v[66:69]
	s_setprio 0
	s_barrier
	s_mov_b32 m0, s77
	v_lshl_add_u64 v[176:177], s[48:49], 0, v[132:133]
	ds_read_b128 v[184:187], v150 offset:16384
	ds_read_b128 v[188:191], v150 offset:17408
	ds_read_b128 v[192:195], v150 offset:18432
	ds_read_b128 v[196:199], v150 offset:19456
	ds_read_b128 v[200:203], v150 offset:20480
	ds_read_b128 v[204:207], v150 offset:21504
	ds_read_b128 v[208:211], v150 offset:22528
	ds_read_b128 v[212:215], v150 offset:23552
	global_load_lds_dwordx4 v[176:177], off
	v_lshl_add_u64 v[216:217], s[48:49], 0, v[136:137]
	s_mov_b32 m0, s74
	v_lshl_add_u64 v[218:219], s[50:51], 0, v[132:133]
	global_load_lds_dwordx4 v[216:217], off
	s_mov_b32 m0, s76
	v_lshl_add_u64 v[220:221], s[46:47], 0, v[134:135]
	global_load_lds_dwordx4 v[218:219], off
	v_lshl_add_u64 v[218:219], s[50:51], 0, v[136:137]
	s_mov_b32 m0, s75
	s_nop 0
	global_load_lds_dwordx4 v[218:219], off
	v_lshl_add_u64 v[218:219], s[46:47], 0, v[130:131]
	s_mov_b32 m0, s35
	s_nop 0
	global_load_lds_dwordx4 v[218:219], off
	s_mov_b32 m0, s58
	s_nop 0
	global_load_lds_dwordx4 v[220:221], off
	s_waitcnt vmcnt(8)
	s_waitcnt lgkmcnt(0)
	s_barrier
	s_setprio 1
	v_mfma_f32_16x16x32_bf16 v[62:65], v[142:145], v[184:187], v[62:65]
	v_mfma_f32_16x16x32_bf16 v[58:61], v[156:159], v[184:187], v[58:61]
	v_mfma_f32_16x16x32_bf16 v[46:49], v[142:145], v[192:195], v[46:49]
	v_mfma_f32_16x16x32_bf16 v[42:45], v[156:159], v[192:195], v[42:45]
	v_mfma_f32_16x16x32_bf16 v[30:33], v[142:145], v[200:203], v[30:33]
	v_mfma_f32_16x16x32_bf16 v[26:29], v[156:159], v[200:203], v[26:29]
	v_mfma_f32_16x16x32_bf16 v[14:17], v[142:145], v[208:211], v[14:17]
	v_mfma_f32_16x16x32_bf16 v[10:13], v[156:159], v[208:211], v[10:13]
	v_mfma_f32_16x16x32_bf16 v[62:65], v[152:155], v[188:191], v[62:65]
	v_mfma_f32_16x16x32_bf16 v[58:61], v[160:163], v[188:191], v[58:61]
	v_mfma_f32_16x16x32_bf16 v[46:49], v[152:155], v[196:199], v[46:49]
	v_mfma_f32_16x16x32_bf16 v[42:45], v[160:163], v[196:199], v[42:45]
	v_mfma_f32_16x16x32_bf16 v[30:33], v[152:155], v[204:207], v[30:33]
	v_mfma_f32_16x16x32_bf16 v[26:29], v[160:163], v[204:207], v[26:29]
	v_mfma_f32_16x16x32_bf16 v[14:17], v[152:155], v[212:215], v[14:17]
	v_mfma_f32_16x16x32_bf16 v[10:13], v[160:163], v[212:215], v[10:13]
	v_mfma_f32_16x16x32_bf16 v[54:57], v[164:167], v[184:187], v[54:57]
	v_mfma_f32_16x16x32_bf16 v[50:53], v[172:175], v[184:187], v[50:53]
	v_mfma_f32_16x16x32_bf16 v[38:41], v[164:167], v[192:195], v[38:41]
	v_mfma_f32_16x16x32_bf16 v[34:37], v[172:175], v[192:195], v[34:37]
	v_mfma_f32_16x16x32_bf16 v[22:25], v[164:167], v[200:203], v[22:25]
	v_mfma_f32_16x16x32_bf16 v[18:21], v[172:175], v[200:203], v[18:21]
	v_mfma_f32_16x16x32_bf16 v[6:9], v[164:167], v[208:211], v[6:9]
	v_mfma_f32_16x16x32_bf16 v[2:5], v[172:175], v[208:211], v[2:5]
	v_mfma_f32_16x16x32_bf16 v[54:57], v[168:171], v[188:191], v[54:57]
	v_mfma_f32_16x16x32_bf16 v[50:53], v[180:183], v[188:191], v[50:53]
	v_mfma_f32_16x16x32_bf16 v[38:41], v[168:171], v[196:199], v[38:41]
	v_mfma_f32_16x16x32_bf16 v[34:37], v[180:183], v[196:199], v[34:37]
	v_mfma_f32_16x16x32_bf16 v[22:25], v[168:171], v[204:207], v[22:25]
	v_mfma_f32_16x16x32_bf16 v[18:21], v[180:183], v[204:207], v[18:21]
	v_mfma_f32_16x16x32_bf16 v[6:9], v[168:171], v[212:215], v[6:9]
	v_mfma_f32_16x16x32_bf16 v[2:5], v[180:183], v[212:215], v[2:5]
	s_setprio 0
	s_barrier
	v_add_u32_e32 v151, s73, v146
	ds_read_b128 v[142:145], v151
	ds_read_b128 v[152:155], v151 offset:1024
	ds_read_b128 v[156:159], v151 offset:2048
	ds_read_b128 v[160:163], v151 offset:3072
	v_add_u32_e32 v151, s72, v146
	ds_read_b128 v[164:167], v151
	ds_read_b128 v[168:171], v151 offset:1024
	ds_read_b128 v[172:175], v151 offset:2048
	ds_read_b128 v[180:183], v151 offset:3072
	s_mov_b32 m0, s59
	v_lshl_add_u64 v[222:223], s[44:45], 0, v[130:131]
	ds_read_b128 v[184:187], v150 offset:32768
	ds_read_b128 v[188:191], v150 offset:33792
	ds_read_b128 v[192:195], v150 offset:34816
	ds_read_b128 v[196:199], v150 offset:35840
	ds_read_b128 v[200:203], v150 offset:36864
	ds_read_b128 v[204:207], v150 offset:37888
	ds_read_b128 v[208:211], v150 offset:38912
	ds_read_b128 v[212:215], v150 offset:39936
	global_load_lds_dwordx4 v[222:223], off
	v_lshl_add_u64 v[222:223], s[44:45], 0, v[134:135]
	s_mov_b32 m0, s60
	s_nop 0
	global_load_lds_dwordx4 v[222:223], off
	s_waitcnt vmcnt(8)
	s_waitcnt lgkmcnt(0)
	s_barrier
	s_setprio 1
	v_mfma_f32_16x16x32_bf16 v[126:129], v[142:145], v[184:187], v[126:129]
	v_mfma_f32_16x16x32_bf16 v[122:125], v[156:159], v[184:187], v[122:125]
	v_mfma_f32_16x16x32_bf16 v[110:113], v[142:145], v[192:195], v[110:113]
	v_mfma_f32_16x16x32_bf16 v[106:109], v[156:159], v[192:195], v[106:109]
	v_mfma_f32_16x16x32_bf16 v[94:97], v[142:145], v[200:203], v[94:97]
	v_mfma_f32_16x16x32_bf16 v[90:93], v[156:159], v[200:203], v[90:93]
	v_mfma_f32_16x16x32_bf16 v[78:81], v[142:145], v[208:211], v[78:81]
	v_mfma_f32_16x16x32_bf16 v[74:77], v[156:159], v[208:211], v[74:77]
	v_mfma_f32_16x16x32_bf16 v[126:129], v[152:155], v[188:191], v[126:129]
	v_mfma_f32_16x16x32_bf16 v[122:125], v[160:163], v[188:191], v[122:125]
	v_mfma_f32_16x16x32_bf16 v[110:113], v[152:155], v[196:199], v[110:113]
	v_mfma_f32_16x16x32_bf16 v[106:109], v[160:163], v[196:199], v[106:109]
	v_mfma_f32_16x16x32_bf16 v[94:97], v[152:155], v[204:207], v[94:97]
	v_mfma_f32_16x16x32_bf16 v[90:93], v[160:163], v[204:207], v[90:93]
	v_mfma_f32_16x16x32_bf16 v[78:81], v[152:155], v[212:215], v[78:81]
	v_mfma_f32_16x16x32_bf16 v[74:77], v[160:163], v[212:215], v[74:77]
	v_mfma_f32_16x16x32_bf16 v[118:121], v[164:167], v[184:187], v[118:121]
	v_mfma_f32_16x16x32_bf16 v[114:117], v[172:175], v[184:187], v[114:117]
	v_mfma_f32_16x16x32_bf16 v[102:105], v[164:167], v[192:195], v[102:105]
	v_mfma_f32_16x16x32_bf16 v[98:101], v[172:175], v[192:195], v[98:101]
	v_mfma_f32_16x16x32_bf16 v[86:89], v[164:167], v[200:203], v[86:89]
	v_mfma_f32_16x16x32_bf16 v[82:85], v[172:175], v[200:203], v[82:85]
	v_mfma_f32_16x16x32_bf16 v[70:73], v[164:167], v[208:211], v[70:73]
	v_mfma_f32_16x16x32_bf16 v[66:69], v[172:175], v[208:211], v[66:69]
	v_mfma_f32_16x16x32_bf16 v[118:121], v[168:171], v[188:191], v[118:121]
	v_mfma_f32_16x16x32_bf16 v[114:117], v[180:183], v[188:191], v[114:117]
	v_mfma_f32_16x16x32_bf16 v[102:105], v[168:171], v[196:199], v[102:105]
	v_mfma_f32_16x16x32_bf16 v[98:101], v[180:183], v[196:199], v[98:101]
	v_mfma_f32_16x16x32_bf16 v[86:89], v[168:171], v[204:207], v[86:89]
	v_mfma_f32_16x16x32_bf16 v[82:85], v[180:183], v[204:207], v[82:85]
	v_mfma_f32_16x16x32_bf16 v[70:73], v[168:171], v[212:215], v[70:73]
	v_mfma_f32_16x16x32_bf16 v[66:69], v[180:183], v[212:215], v[66:69]
	s_setprio 0
	s_barrier
	s_mov_b32 m0, s71
	v_lshl_add_u64 v[176:177], v[176:177], 0, s[8:9]
	ds_read_b128 v[184:187], v150 offset:49152
	ds_read_b128 v[188:191], v150 offset:50176
	ds_read_b128 v[192:195], v150 offset:51200
	ds_read_b128 v[196:199], v150 offset:52224
	ds_read_b128 v[200:203], v150 offset:53248
	ds_read_b128 v[204:207], v150 offset:54272
	ds_read_b128 v[208:211], v150 offset:55296
	ds_read_b128 v[212:215], v150 offset:56320
	global_load_lds_dwordx4 v[176:177], off
	v_lshl_add_u64 v[176:177], v[216:217], 0, s[8:9]
	s_mov_b32 m0, s70
	s_nop 0
	global_load_lds_dwordx4 v[176:177], off
	v_lshl_add_u64 v[176:177], s[42:43], 0, v[132:133]
	s_mov_b32 m0, s79
	s_nop 0
	global_load_lds_dwordx4 v[176:177], off
	v_lshl_add_u64 v[176:177], s[42:43], 0, v[136:137]
	s_mov_b32 m0, s78
	s_nop 0
	global_load_lds_dwordx4 v[176:177], off
	v_lshl_add_u64 v[176:177], v[218:219], 0, s[8:9]
	s_mov_b32 m0, s62
	s_nop 0
	global_load_lds_dwordx4 v[176:177], off
	v_lshl_add_u64 v[176:177], v[220:221], 0, s[8:9]
	s_mov_b32 m0, s63
	s_nop 0
	global_load_lds_dwordx4 v[176:177], off
	s_waitcnt vmcnt(8)
	s_waitcnt lgkmcnt(0)
	s_barrier
	s_setprio 1
	v_mfma_f32_16x16x32_bf16 v[62:65], v[142:145], v[184:187], v[62:65]
	v_mfma_f32_16x16x32_bf16 v[58:61], v[156:159], v[184:187], v[58:61]
	v_mfma_f32_16x16x32_bf16 v[46:49], v[142:145], v[192:195], v[46:49]
	v_mfma_f32_16x16x32_bf16 v[42:45], v[156:159], v[192:195], v[42:45]
	v_mfma_f32_16x16x32_bf16 v[30:33], v[142:145], v[200:203], v[30:33]
	v_mfma_f32_16x16x32_bf16 v[26:29], v[156:159], v[200:203], v[26:29]
	v_mfma_f32_16x16x32_bf16 v[14:17], v[142:145], v[208:211], v[14:17]
	v_mfma_f32_16x16x32_bf16 v[10:13], v[156:159], v[208:211], v[10:13]
	v_mfma_f32_16x16x32_bf16 v[62:65], v[152:155], v[188:191], v[62:65]
	v_mfma_f32_16x16x32_bf16 v[58:61], v[160:163], v[188:191], v[58:61]
	v_mfma_f32_16x16x32_bf16 v[46:49], v[152:155], v[196:199], v[46:49]
	v_mfma_f32_16x16x32_bf16 v[42:45], v[160:163], v[196:199], v[42:45]
	v_mfma_f32_16x16x32_bf16 v[30:33], v[152:155], v[204:207], v[30:33]
	v_mfma_f32_16x16x32_bf16 v[26:29], v[160:163], v[204:207], v[26:29]
	v_mfma_f32_16x16x32_bf16 v[14:17], v[152:155], v[212:215], v[14:17]
	v_mfma_f32_16x16x32_bf16 v[10:13], v[160:163], v[212:215], v[10:13]
	v_mfma_f32_16x16x32_bf16 v[54:57], v[164:167], v[184:187], v[54:57]
	v_mfma_f32_16x16x32_bf16 v[50:53], v[172:175], v[184:187], v[50:53]
	v_mfma_f32_16x16x32_bf16 v[38:41], v[164:167], v[192:195], v[38:41]
	v_mfma_f32_16x16x32_bf16 v[34:37], v[172:175], v[192:195], v[34:37]
	v_mfma_f32_16x16x32_bf16 v[22:25], v[164:167], v[200:203], v[22:25]
	v_mfma_f32_16x16x32_bf16 v[18:21], v[172:175], v[200:203], v[18:21]
	v_mfma_f32_16x16x32_bf16 v[6:9], v[164:167], v[208:211], v[6:9]
	v_mfma_f32_16x16x32_bf16 v[2:5], v[172:175], v[208:211], v[2:5]
	v_mfma_f32_16x16x32_bf16 v[54:57], v[168:171], v[188:191], v[54:57]
	v_mfma_f32_16x16x32_bf16 v[50:53], v[180:183], v[188:191], v[50:53]
	v_mfma_f32_16x16x32_bf16 v[38:41], v[168:171], v[196:199], v[38:41]
	v_mfma_f32_16x16x32_bf16 v[34:37], v[180:183], v[196:199], v[34:37]
	v_mfma_f32_16x16x32_bf16 v[22:25], v[168:171], v[204:207], v[22:25]
	v_mfma_f32_16x16x32_bf16 v[18:21], v[180:183], v[204:207], v[18:21]
	v_mfma_f32_16x16x32_bf16 v[6:9], v[168:171], v[212:215], v[6:9]
	v_mfma_f32_16x16x32_bf16 v[2:5], v[180:183], v[212:215], v[2:5]
	s_setprio 0
	s_barrier
	s_movk_i32 s44, 0x100
	s_andn2_b64 vcc, exec, s[40:41]
	s_mov_b64 s[42:43], -1
	s_mov_b64 s[40:41], 0
	s_cbranch_vccz .LBB0_1216
	s_and_b64 vcc, exec, s[10:11]
	s_cbranch_vccz .LBB0_1219
	s_barrier

.LBB0_1308:
	ds_read_b128 v[130:133], v184
	ds_read_b128 v[134:137], v184 offset:1024
	ds_read_b128 v[138:141], v184 offset:2048
	ds_read_b128 v[142:145], v184 offset:3072
	ds_read_b128 v[146:149], v185
	ds_read_b128 v[150:153], v185 offset:1024
	ds_read_b128 v[172:175], v185 offset:2048
	ds_read_b128 v[196:199], v185 offset:3072
	s_add_u32 s38, s36, 0xfffc0080
	s_addc_u32 s39, s37, -1
	s_cmp_eq_u32 s61, 12
	s_cselect_b32 s41, s27, s39
	s_cselect_b32 s40, s35, s38
	s_cselect_b32 s39, s25, s60
	s_cselect_b32 s38, s58, s59
	v_lshl_add_u64 v[176:177], s[36:37], 0, v[166:167]
	s_add_i32 m0, s45, 0xc000
	ds_read_b128 v[200:203], v186
	ds_read_b128 v[204:207], v186 offset:1024
	ds_read_b128 v[208:211], v186 offset:2048
	ds_read_b128 v[212:215], v186 offset:3072
	ds_read_b128 v[216:219], v186 offset:4096
	ds_read_b128 v[220:223], v186 offset:5120
	ds_read_b128 v[224:227], v186 offset:6144
	ds_read_b128 v[228:231], v186 offset:7168
	global_load_lds_dwordx4 v[176:177], off
	v_lshl_add_u64 v[176:177], s[36:37], 0, v[164:165]
	s_add_i32 m0, s45, 0xe000
	s_nop 0
	global_load_lds_dwordx4 v[176:177], off
	s_waitcnt vmcnt(8)
	s_waitcnt lgkmcnt(0)
	s_barrier
	s_setprio 1
	v_mfma_f32_16x16x32_bf16 v[126:129], v[130:133], v[200:203], v[126:129]
	v_mfma_f32_16x16x32_bf16 v[122:125], v[138:141], v[200:203], v[122:125]
	v_mfma_f32_16x16x32_bf16 v[110:113], v[130:133], v[208:211], v[110:113]
	v_mfma_f32_16x16x32_bf16 v[106:109], v[138:141], v[208:211], v[106:109]
	v_mfma_f32_16x16x32_bf16 v[94:97], v[130:133], v[216:219], v[94:97]
	v_mfma_f32_16x16x32_bf16 v[90:93], v[138:141], v[216:219], v[90:93]
	v_mfma_f32_16x16x32_bf16 v[78:81], v[130:133], v[224:227], v[78:81]
	v_mfma_f32_16x16x32_bf16 v[74:77], v[138:141], v[224:227], v[74:77]
	v_mfma_f32_16x16x32_bf16 v[126:129], v[134:137], v[204:207], v[126:129]
	v_mfma_f32_16x16x32_bf16 v[122:125], v[142:145], v[204:207], v[122:125]
	v_mfma_f32_16x16x32_bf16 v[110:113], v[134:137], v[212:215], v[110:113]
	v_mfma_f32_16x16x32_bf16 v[106:109], v[142:145], v[212:215], v[106:109]
	v_mfma_f32_16x16x32_bf16 v[94:97], v[134:137], v[220:223], v[94:97]
	v_mfma_f32_16x16x32_bf16 v[90:93], v[142:145], v[220:223], v[90:93]
	v_mfma_f32_16x16x32_bf16 v[78:81], v[134:137], v[228:231], v[78:81]
	v_mfma_f32_16x16x32_bf16 v[74:77], v[142:145], v[228:231], v[74:77]
	v_mfma_f32_16x16x32_bf16 v[118:121], v[146:149], v[200:203], v[118:121]
	v_mfma_f32_16x16x32_bf16 v[114:117], v[172:175], v[200:203], v[114:117]
	v_mfma_f32_16x16x32_bf16 v[102:105], v[146:149], v[208:211], v[102:105]
	v_mfma_f32_16x16x32_bf16 v[98:101], v[172:175], v[208:211], v[98:101]
	v_mfma_f32_16x16x32_bf16 v[86:89], v[146:149], v[216:219], v[86:89]
	v_mfma_f32_16x16x32_bf16 v[82:85], v[172:175], v[216:219], v[82:85]
	v_mfma_f32_16x16x32_bf16 v[70:73], v[146:149], v[224:227], v[70:73]
	v_mfma_f32_16x16x32_bf16 v[66:69], v[172:175], v[224:227], v[66:69]
	v_mfma_f32_16x16x32_bf16 v[118:121], v[150:153], v[204:207], v[118:121]
	v_mfma_f32_16x16x32_bf16 v[114:117], v[196:199], v[204:207], v[114:117]
	v_mfma_f32_16x16x32_bf16 v[102:105], v[150:153], v[212:215], v[102:105]
	v_mfma_f32_16x16x32_bf16 v[98:101], v[196:199], v[212:215], v[98:101]
	v_mfma_f32_16x16x32_bf16 v[86:89], v[150:153], v[220:223], v[86:89]
	v_mfma_f32_16x16x32_bf16 v[82:85], v[196:199], v[220:223], v[82:85]
	v_mfma_f32_16x16x32_bf16 v[70:73], v[150:153], v[228:231], v[70:73]
	v_mfma_f32_16x16x32_bf16 v[66:69], v[196:199], v[228:231], v[66:69]
	s_setprio 0
	s_barrier
	s_add_i32 s62, s55, s44
	v_lshl_add_u64 v[176:177], s[38:39], 0, v[156:157]
	s_mov_b32 m0, s62
	ds_read_b128 v[200:203], v186 offset:16384
	ds_read_b128 v[204:207], v186 offset:17408
	ds_read_b128 v[208:211], v186 offset:18432
	ds_read_b128 v[212:215], v186 offset:19456
	ds_read_b128 v[216:219], v186 offset:20480
	ds_read_b128 v[220:223], v186 offset:21504
	ds_read_b128 v[224:227], v186 offset:22528
	ds_read_b128 v[228:231], v186 offset:23552
	global_load_lds_dwordx4 v[176:177], off
	s_add_i32 m0, s62, 0x2000
	s_add_u32 s62, s38, 0x40000
	v_lshl_add_u64 v[232:233], s[38:39], 0, v[160:161]
	s_addc_u32 s63, s39, 0
	s_add_i32 s64, s56, s44
	global_load_lds_dwordx4 v[232:233], off
	v_lshl_add_u64 v[234:235], s[62:63], 0, v[156:157]
	s_mov_b32 m0, s64
	v_lshl_add_u64 v[236:237], s[40:41], 0, v[158:159]
	global_load_lds_dwordx4 v[234:235], off
	v_lshl_add_u64 v[234:235], s[62:63], 0, v[160:161]
	s_add_i32 m0, s64, 0x2000
	s_nop 0
	global_load_lds_dwordx4 v[234:235], off
	v_lshl_add_u64 v[234:235], s[40:41], 0, v[154:155]
	s_mov_b32 m0, s45
	s_nop 0
	global_load_lds_dwordx4 v[234:235], off
	s_mov_b32 m0, s46
	s_nop 0
	global_load_lds_dwordx4 v[236:237], off
	s_waitcnt vmcnt(8)
	s_waitcnt lgkmcnt(0)
	s_barrier
	s_setprio 1
	v_mfma_f32_16x16x32_bf16 v[62:65], v[130:133], v[200:203], v[62:65]
	v_mfma_f32_16x16x32_bf16 v[58:61], v[138:141], v[200:203], v[58:61]
	v_mfma_f32_16x16x32_bf16 v[46:49], v[130:133], v[208:211], v[46:49]
	v_mfma_f32_16x16x32_bf16 v[42:45], v[138:141], v[208:211], v[42:45]
	v_mfma_f32_16x16x32_bf16 v[30:33], v[130:133], v[216:219], v[30:33]
	v_mfma_f32_16x16x32_bf16 v[26:29], v[138:141], v[216:219], v[26:29]
	v_mfma_f32_16x16x32_bf16 v[14:17], v[130:133], v[224:227], v[14:17]
	v_mfma_f32_16x16x32_bf16 v[10:13], v[138:141], v[224:227], v[10:13]
	v_mfma_f32_16x16x32_bf16 v[62:65], v[134:137], v[204:207], v[62:65]
	v_mfma_f32_16x16x32_bf16 v[58:61], v[142:145], v[204:207], v[58:61]
	v_mfma_f32_16x16x32_bf16 v[46:49], v[134:137], v[212:215], v[46:49]
	v_mfma_f32_16x16x32_bf16 v[42:45], v[142:145], v[212:215], v[42:45]
	v_mfma_f32_16x16x32_bf16 v[30:33], v[134:137], v[220:223], v[30:33]
	v_mfma_f32_16x16x32_bf16 v[26:29], v[142:145], v[220:223], v[26:29]
	v_mfma_f32_16x16x32_bf16 v[14:17], v[134:137], v[228:231], v[14:17]
	v_mfma_f32_16x16x32_bf16 v[10:13], v[142:145], v[228:231], v[10:13]
	v_mfma_f32_16x16x32_bf16 v[54:57], v[146:149], v[200:203], v[54:57]
	v_mfma_f32_16x16x32_bf16 v[50:53], v[172:175], v[200:203], v[50:53]
	v_mfma_f32_16x16x32_bf16 v[38:41], v[146:149], v[208:211], v[38:41]
	v_mfma_f32_16x16x32_bf16 v[34:37], v[172:175], v[208:211], v[34:37]
	v_mfma_f32_16x16x32_bf16 v[22:25], v[146:149], v[216:219], v[22:25]
	v_mfma_f32_16x16x32_bf16 v[18:21], v[172:175], v[216:219], v[18:21]
	v_mfma_f32_16x16x32_bf16 v[6:9], v[146:149], v[224:227], v[6:9]
	v_mfma_f32_16x16x32_bf16 v[2:5], v[172:175], v[224:227], v[2:5]
	v_mfma_f32_16x16x32_bf16 v[54:57], v[150:153], v[204:207], v[54:57]
	v_mfma_f32_16x16x32_bf16 v[50:53], v[196:199], v[204:207], v[50:53]
	v_mfma_f32_16x16x32_bf16 v[38:41], v[150:153], v[212:215], v[38:41]
	v_mfma_f32_16x16x32_bf16 v[34:37], v[196:199], v[212:215], v[34:37]
	v_mfma_f32_16x16x32_bf16 v[22:25], v[150:153], v[220:223], v[22:25]
	v_mfma_f32_16x16x32_bf16 v[18:21], v[196:199], v[220:223], v[18:21]
	v_mfma_f32_16x16x32_bf16 v[6:9], v[150:153], v[228:231], v[6:9]
	v_mfma_f32_16x16x32_bf16 v[2:5], v[196:199], v[228:231], v[2:5]
	s_setprio 0
	s_barrier
	s_add_i32 s62, 0, 0x18000
	s_add_i32 s63, 0, 0x1c000
	v_add_u32_e32 v142, s62, v182
	v_add_u32_e32 v195, s63, v182
	ds_read_b128 v[130:133], v142
	ds_read_b128 v[134:137], v142 offset:1024
	ds_read_b128 v[138:141], v142 offset:2048
	ds_read_b128 v[142:145], v142 offset:3072
	ds_read_b128 v[146:149], v195
	ds_read_b128 v[150:153], v195 offset:1024
	ds_read_b128 v[172:175], v195 offset:2048
	ds_read_b128 v[196:199], v195 offset:3072
	s_add_u32 s40, s40, 0x40000
	s_addc_u32 s41, s41, 0
	s_mov_b32 m0, s47
	v_lshl_add_u64 v[238:239], s[40:41], 0, v[154:155]
	ds_read_b128 v[200:203], v186 offset:32768
	ds_read_b128 v[204:207], v186 offset:33792
	ds_read_b128 v[208:211], v186 offset:34816
	ds_read_b128 v[212:215], v186 offset:35840
	ds_read_b128 v[216:219], v186 offset:36864
	ds_read_b128 v[220:223], v186 offset:37888
	ds_read_b128 v[224:227], v186 offset:38912
	ds_read_b128 v[228:231], v186 offset:39936
	global_load_lds_dwordx4 v[238:239], off
	v_lshl_add_u64 v[238:239], s[40:41], 0, v[158:159]
	s_mov_b32 m0, s48
	s_nop 0
	global_load_lds_dwordx4 v[238:239], off
	s_waitcnt vmcnt(8)
	s_waitcnt lgkmcnt(0)
	s_barrier
	s_setprio 1
	v_mfma_f32_16x16x32_bf16 v[126:129], v[130:133], v[200:203], v[126:129]
	v_mfma_f32_16x16x32_bf16 v[122:125], v[138:141], v[200:203], v[122:125]
	v_mfma_f32_16x16x32_bf16 v[110:113], v[130:133], v[208:211], v[110:113]
	v_mfma_f32_16x16x32_bf16 v[106:109], v[138:141], v[208:211], v[106:109]
	v_mfma_f32_16x16x32_bf16 v[94:97], v[130:133], v[216:219], v[94:97]
	v_mfma_f32_16x16x32_bf16 v[90:93], v[138:141], v[216:219], v[90:93]
	v_mfma_f32_16x16x32_bf16 v[78:81], v[130:133], v[224:227], v[78:81]
	v_mfma_f32_16x16x32_bf16 v[74:77], v[138:141], v[224:227], v[74:77]
	v_mfma_f32_16x16x32_bf16 v[126:129], v[134:137], v[204:207], v[126:129]
	v_mfma_f32_16x16x32_bf16 v[122:125], v[142:145], v[204:207], v[122:125]
	v_mfma_f32_16x16x32_bf16 v[110:113], v[134:137], v[212:215], v[110:113]
	v_mfma_f32_16x16x32_bf16 v[106:109], v[142:145], v[212:215], v[106:109]
	v_mfma_f32_16x16x32_bf16 v[94:97], v[134:137], v[220:223], v[94:97]
	v_mfma_f32_16x16x32_bf16 v[90:93], v[142:145], v[220:223], v[90:93]
	v_mfma_f32_16x16x32_bf16 v[78:81], v[134:137], v[228:231], v[78:81]
	v_mfma_f32_16x16x32_bf16 v[74:77], v[142:145], v[228:231], v[74:77]
	v_mfma_f32_16x16x32_bf16 v[118:121], v[146:149], v[200:203], v[118:121]
	v_mfma_f32_16x16x32_bf16 v[114:117], v[172:175], v[200:203], v[114:117]
	v_mfma_f32_16x16x32_bf16 v[102:105], v[146:149], v[208:211], v[102:105]
	v_mfma_f32_16x16x32_bf16 v[98:101], v[172:175], v[208:211], v[98:101]
	v_mfma_f32_16x16x32_bf16 v[86:89], v[146:149], v[216:219], v[86:89]
	v_mfma_f32_16x16x32_bf16 v[82:85], v[172:175], v[216:219], v[82:85]
	v_mfma_f32_16x16x32_bf16 v[70:73], v[146:149], v[224:227], v[70:73]
	v_mfma_f32_16x16x32_bf16 v[66:69], v[172:175], v[224:227], v[66:69]
	v_mfma_f32_16x16x32_bf16 v[118:121], v[150:153], v[204:207], v[118:121]
	v_mfma_f32_16x16x32_bf16 v[114:117], v[196:199], v[204:207], v[114:117]
	v_mfma_f32_16x16x32_bf16 v[102:105], v[150:153], v[212:215], v[102:105]
	v_mfma_f32_16x16x32_bf16 v[98:101], v[196:199], v[212:215], v[98:101]
	v_mfma_f32_16x16x32_bf16 v[86:89], v[150:153], v[220:223], v[86:89]
	v_mfma_f32_16x16x32_bf16 v[82:85], v[196:199], v[220:223], v[82:85]
	v_mfma_f32_16x16x32_bf16 v[70:73], v[150:153], v[228:231], v[70:73]
	v_mfma_f32_16x16x32_bf16 v[66:69], v[196:199], v[228:231], v[66:69]
	s_setprio 0
	s_barrier
	s_add_i32 s40, s62, s44
	v_lshl_add_u64 v[176:177], v[176:177], 0, s[18:19]
	s_mov_b32 m0, s40
	ds_read_b128 v[200:203], v186 offset:49152
	ds_read_b128 v[204:207], v186 offset:50176
	ds_read_b128 v[208:211], v186 offset:51200
	ds_read_b128 v[212:215], v186 offset:52224
	ds_read_b128 v[216:219], v186 offset:53248
	ds_read_b128 v[220:223], v186 offset:54272
	ds_read_b128 v[224:227], v186 offset:55296
	ds_read_b128 v[228:231], v186 offset:56320
	global_load_lds_dwordx4 v[176:177], off
	s_add_i32 m0, s40, 0x2000
	s_add_u32 s38, s38, 0x40080
	v_lshl_add_u64 v[176:177], v[232:233], 0, s[18:19]
	s_addc_u32 s39, s39, 0
	s_add_i32 s40, s63, s44
	global_load_lds_dwordx4 v[176:177], off
	v_lshl_add_u64 v[176:177], s[38:39], 0, v[156:157]
	s_mov_b32 m0, s40
	s_nop 0
	global_load_lds_dwordx4 v[176:177], off
	v_lshl_add_u64 v[176:177], s[38:39], 0, v[160:161]
	s_add_i32 m0, s40, 0x2000
	s_nop 0
	global_load_lds_dwordx4 v[176:177], off
	v_lshl_add_u64 v[176:177], v[234:235], 0, s[18:19]
	s_mov_b32 m0, s33
	s_nop 0
	global_load_lds_dwordx4 v[176:177], off
	v_lshl_add_u64 v[176:177], v[236:237], 0, s[18:19]
	s_mov_b32 m0, s51
	s_nop 0
	global_load_lds_dwordx4 v[176:177], off
	s_waitcnt vmcnt(8)
	s_waitcnt lgkmcnt(0)
	s_barrier
	s_setprio 1
	v_mfma_f32_16x16x32_bf16 v[62:65], v[130:133], v[200:203], v[62:65]
	v_mfma_f32_16x16x32_bf16 v[58:61], v[138:141], v[200:203], v[58:61]
	v_mfma_f32_16x16x32_bf16 v[46:49], v[130:133], v[208:211], v[46:49]
	v_mfma_f32_16x16x32_bf16 v[42:45], v[138:141], v[208:211], v[42:45]
	v_mfma_f32_16x16x32_bf16 v[30:33], v[130:133], v[216:219], v[30:33]
	v_mfma_f32_16x16x32_bf16 v[26:29], v[138:141], v[216:219], v[26:29]
	v_mfma_f32_16x16x32_bf16 v[14:17], v[130:133], v[224:227], v[14:17]
	v_mfma_f32_16x16x32_bf16 v[10:13], v[138:141], v[224:227], v[10:13]
	v_mfma_f32_16x16x32_bf16 v[62:65], v[134:137], v[204:207], v[62:65]
	v_mfma_f32_16x16x32_bf16 v[58:61], v[142:145], v[204:207], v[58:61]
	v_mfma_f32_16x16x32_bf16 v[46:49], v[134:137], v[212:215], v[46:49]
	v_mfma_f32_16x16x32_bf16 v[42:45], v[142:145], v[212:215], v[42:45]
	v_mfma_f32_16x16x32_bf16 v[30:33], v[134:137], v[220:223], v[30:33]
	v_mfma_f32_16x16x32_bf16 v[26:29], v[142:145], v[220:223], v[26:29]
	v_mfma_f32_16x16x32_bf16 v[14:17], v[134:137], v[228:231], v[14:17]
	v_mfma_f32_16x16x32_bf16 v[10:13], v[142:145], v[228:231], v[10:13]
	v_mfma_f32_16x16x32_bf16 v[54:57], v[146:149], v[200:203], v[54:57]
	v_mfma_f32_16x16x32_bf16 v[50:53], v[172:175], v[200:203], v[50:53]
	v_mfma_f32_16x16x32_bf16 v[38:41], v[146:149], v[208:211], v[38:41]
	v_mfma_f32_16x16x32_bf16 v[34:37], v[172:175], v[208:211], v[34:37]
	v_mfma_f32_16x16x32_bf16 v[22:25], v[146:149], v[216:219], v[22:25]
	v_mfma_f32_16x16x32_bf16 v[18:21], v[172:175], v[216:219], v[18:21]
	v_mfma_f32_16x16x32_bf16 v[6:9], v[146:149], v[224:227], v[6:9]
	v_mfma_f32_16x16x32_bf16 v[2:5], v[172:175], v[224:227], v[2:5]
	v_mfma_f32_16x16x32_bf16 v[54:57], v[150:153], v[204:207], v[54:57]
	v_mfma_f32_16x16x32_bf16 v[50:53], v[196:199], v[204:207], v[50:53]
	v_mfma_f32_16x16x32_bf16 v[38:41], v[150:153], v[212:215], v[38:41]
	v_mfma_f32_16x16x32_bf16 v[34:37], v[196:199], v[212:215], v[34:37]
	v_mfma_f32_16x16x32_bf16 v[22:25], v[150:153], v[220:223], v[22:25]
	v_mfma_f32_16x16x32_bf16 v[18:21], v[196:199], v[220:223], v[18:21]
	v_mfma_f32_16x16x32_bf16 v[6:9], v[150:153], v[228:231], v[6:9]
	v_mfma_f32_16x16x32_bf16 v[2:5], v[196:199], v[228:231], v[2:5]
	s_setprio 0
	s_barrier
	s_add_i32 s61, s61, 2
	s_add_u32 s59, s59, 0x100
	s_addc_u32 s60, s60, 0
	s_add_u32 s36, s36, 0x100
	s_addc_u32 s37, s37, 0
	s_cmp_gt_u32 s61, 13
	s_cbranch_scc0 .LBB0_1308
	s_and_b64 vcc, exec, s[20:21]
	s_cbranch_vccz .LBB0_1311
	s_barrier

.LBB0_1477:
	ds_read_b128 v[82:85], v180
	ds_read_b128 v[86:89], v180 offset:1024
	ds_read_b128 v[90:93], v180 offset:2048
	ds_read_b128 v[94:97], v180 offset:3072
	ds_read_b128 v[168:171], v181
	ds_read_b128 v[192:195], v181 offset:1024
	ds_read_b128 v[196:199], v181 offset:2048
	ds_read_b128 v[200:203], v181 offset:3072
	s_add_u32 s8, s6, 0xfffc0080
	s_addc_u32 s9, s7, -1
	s_cmp_eq_u32 s61, 12
	s_cselect_b32 s37, s25, s9
	s_cselect_b32 s36, s57, s8
	s_cselect_b32 s9, s23, s60
	s_cselect_b32 s8, s58, s59
	v_lshl_add_u64 v[172:173], s[6:7], 0, v[160:161]
	s_add_i32 m0, s31, 0xc000
	ds_read_b128 v[204:207], v182
	ds_read_b128 v[208:211], v182 offset:1024
	ds_read_b128 v[212:215], v182 offset:2048
	ds_read_b128 v[216:219], v182 offset:3072
	ds_read_b128 v[220:223], v182 offset:4096
	ds_read_b128 v[224:227], v182 offset:5120
	ds_read_b128 v[228:231], v182 offset:6144
	ds_read_b128 v[232:235], v182 offset:7168
	global_load_lds_dwordx4 v[172:173], off
	v_lshl_add_u64 v[172:173], s[6:7], 0, v[158:159]
	s_add_i32 m0, s31, 0xe000
	s_nop 0
	global_load_lds_dwordx4 v[172:173], off
	s_waitcnt vmcnt(8)
	s_waitcnt lgkmcnt(0)
	s_barrier
	s_setprio 1
	v_mfma_f32_16x16x32_bf16 v[142:145], v[82:85], v[204:207], v[142:145]
	v_mfma_f32_16x16x32_bf16 v[138:141], v[90:93], v[204:207], v[138:141]
	v_mfma_f32_16x16x32_bf16 v[126:129], v[82:85], v[212:215], v[126:129]
	v_mfma_f32_16x16x32_bf16 v[122:125], v[90:93], v[212:215], v[122:125]
	v_mfma_f32_16x16x32_bf16 v[110:113], v[82:85], v[220:223], v[110:113]
	v_mfma_f32_16x16x32_bf16 v[106:109], v[90:93], v[220:223], v[106:109]
	v_mfma_f32_16x16x32_bf16 v[78:81], v[82:85], v[228:231], v[78:81]
	v_mfma_f32_16x16x32_bf16 v[74:77], v[90:93], v[228:231], v[74:77]
	v_mfma_f32_16x16x32_bf16 v[142:145], v[86:89], v[208:211], v[142:145]
	v_mfma_f32_16x16x32_bf16 v[138:141], v[94:97], v[208:211], v[138:141]
	v_mfma_f32_16x16x32_bf16 v[126:129], v[86:89], v[216:219], v[126:129]
	v_mfma_f32_16x16x32_bf16 v[122:125], v[94:97], v[216:219], v[122:125]
	v_mfma_f32_16x16x32_bf16 v[110:113], v[86:89], v[224:227], v[110:113]
	v_mfma_f32_16x16x32_bf16 v[106:109], v[94:97], v[224:227], v[106:109]
	v_mfma_f32_16x16x32_bf16 v[78:81], v[86:89], v[232:235], v[78:81]
	v_mfma_f32_16x16x32_bf16 v[74:77], v[94:97], v[232:235], v[74:77]
	v_mfma_f32_16x16x32_bf16 v[134:137], v[168:171], v[204:207], v[134:137]
	v_mfma_f32_16x16x32_bf16 v[130:133], v[196:199], v[204:207], v[130:133]
	v_mfma_f32_16x16x32_bf16 v[118:121], v[168:171], v[212:215], v[118:121]
	v_mfma_f32_16x16x32_bf16 v[114:117], v[196:199], v[212:215], v[114:117]
	v_mfma_f32_16x16x32_bf16 v[102:105], v[168:171], v[220:223], v[102:105]
	v_mfma_f32_16x16x32_bf16 v[98:101], v[196:199], v[220:223], v[98:101]
	v_mfma_f32_16x16x32_bf16 v[70:73], v[168:171], v[228:231], v[70:73]
	v_mfma_f32_16x16x32_bf16 v[66:69], v[196:199], v[228:231], v[66:69]
	v_mfma_f32_16x16x32_bf16 v[134:137], v[192:195], v[208:211], v[134:137]
	v_mfma_f32_16x16x32_bf16 v[130:133], v[200:203], v[208:211], v[130:133]
	v_mfma_f32_16x16x32_bf16 v[118:121], v[192:195], v[216:219], v[118:121]
	v_mfma_f32_16x16x32_bf16 v[114:117], v[200:203], v[216:219], v[114:117]
	v_mfma_f32_16x16x32_bf16 v[102:105], v[192:195], v[224:227], v[102:105]
	v_mfma_f32_16x16x32_bf16 v[98:101], v[200:203], v[224:227], v[98:101]
	v_mfma_f32_16x16x32_bf16 v[70:73], v[192:195], v[232:235], v[70:73]
	v_mfma_f32_16x16x32_bf16 v[66:69], v[200:203], v[232:235], v[66:69]
	s_setprio 0
	s_barrier
	s_add_i32 s62, s54, s41
	v_lshl_add_u64 v[172:173], s[8:9], 0, v[148:149]
	s_mov_b32 m0, s62
	ds_read_b128 v[204:207], v182 offset:16384
	ds_read_b128 v[208:211], v182 offset:17408
	ds_read_b128 v[212:215], v182 offset:18432
	ds_read_b128 v[216:219], v182 offset:19456
	ds_read_b128 v[220:223], v182 offset:20480
	ds_read_b128 v[224:227], v182 offset:21504
	ds_read_b128 v[228:231], v182 offset:22528
	ds_read_b128 v[232:235], v182 offset:23552
	global_load_lds_dwordx4 v[172:173], off
	s_add_i32 m0, s62, 0x2000
	s_add_u32 s62, s8, 0x40000
	v_lshl_add_u64 v[236:237], s[8:9], 0, v[152:153]
	s_addc_u32 s63, s9, 0
	s_add_i32 s64, s55, s41
	global_load_lds_dwordx4 v[236:237], off
	v_lshl_add_u64 v[238:239], s[62:63], 0, v[148:149]
	s_mov_b32 m0, s64
	v_lshl_add_u64 v[240:241], s[36:37], 0, v[150:151]
	global_load_lds_dwordx4 v[238:239], off
	v_lshl_add_u64 v[238:239], s[62:63], 0, v[152:153]
	s_add_i32 m0, s64, 0x2000
	s_nop 0
	global_load_lds_dwordx4 v[238:239], off
	v_lshl_add_u64 v[238:239], s[36:37], 0, v[146:147]
	s_mov_b32 m0, s31
	s_nop 0
	global_load_lds_dwordx4 v[238:239], off
	s_mov_b32 m0, s35
	s_nop 0
	global_load_lds_dwordx4 v[240:241], off
	s_waitcnt vmcnt(8)
	s_waitcnt lgkmcnt(0)
	s_barrier
	s_setprio 1
	v_mfma_f32_16x16x32_bf16 v[62:65], v[82:85], v[204:207], v[62:65]
	v_mfma_f32_16x16x32_bf16 v[58:61], v[90:93], v[204:207], v[58:61]
	v_mfma_f32_16x16x32_bf16 v[46:49], v[82:85], v[212:215], v[46:49]
	v_mfma_f32_16x16x32_bf16 v[42:45], v[90:93], v[212:215], v[42:45]
	v_mfma_f32_16x16x32_bf16 v[30:33], v[82:85], v[220:223], v[30:33]
	v_mfma_f32_16x16x32_bf16 v[26:29], v[90:93], v[220:223], v[26:29]
	v_mfma_f32_16x16x32_bf16 v[14:17], v[82:85], v[228:231], v[14:17]
	v_mfma_f32_16x16x32_bf16 v[10:13], v[90:93], v[228:231], v[10:13]
	v_mfma_f32_16x16x32_bf16 v[62:65], v[86:89], v[208:211], v[62:65]
	v_mfma_f32_16x16x32_bf16 v[58:61], v[94:97], v[208:211], v[58:61]
	v_mfma_f32_16x16x32_bf16 v[46:49], v[86:89], v[216:219], v[46:49]
	v_mfma_f32_16x16x32_bf16 v[42:45], v[94:97], v[216:219], v[42:45]
	v_mfma_f32_16x16x32_bf16 v[30:33], v[86:89], v[224:227], v[30:33]
	v_mfma_f32_16x16x32_bf16 v[26:29], v[94:97], v[224:227], v[26:29]
	v_mfma_f32_16x16x32_bf16 v[14:17], v[86:89], v[232:235], v[14:17]
	v_mfma_f32_16x16x32_bf16 v[10:13], v[94:97], v[232:235], v[10:13]
	v_mfma_f32_16x16x32_bf16 v[54:57], v[168:171], v[204:207], v[54:57]
	v_mfma_f32_16x16x32_bf16 v[50:53], v[196:199], v[204:207], v[50:53]
	v_mfma_f32_16x16x32_bf16 v[38:41], v[168:171], v[212:215], v[38:41]
	v_mfma_f32_16x16x32_bf16 v[34:37], v[196:199], v[212:215], v[34:37]
	v_mfma_f32_16x16x32_bf16 v[22:25], v[168:171], v[220:223], v[22:25]
	v_mfma_f32_16x16x32_bf16 v[18:21], v[196:199], v[220:223], v[18:21]
	v_mfma_f32_16x16x32_bf16 v[6:9], v[168:171], v[228:231], v[6:9]
	v_mfma_f32_16x16x32_bf16 v[2:5], v[196:199], v[228:231], v[2:5]
	v_mfma_f32_16x16x32_bf16 v[54:57], v[192:195], v[208:211], v[54:57]
	v_mfma_f32_16x16x32_bf16 v[50:53], v[200:203], v[208:211], v[50:53]
	v_mfma_f32_16x16x32_bf16 v[38:41], v[192:195], v[216:219], v[38:41]
	v_mfma_f32_16x16x32_bf16 v[34:37], v[200:203], v[216:219], v[34:37]
	v_mfma_f32_16x16x32_bf16 v[22:25], v[192:195], v[224:227], v[22:25]
	v_mfma_f32_16x16x32_bf16 v[18:21], v[200:203], v[224:227], v[18:21]
	v_mfma_f32_16x16x32_bf16 v[6:9], v[192:195], v[232:235], v[6:9]
	v_mfma_f32_16x16x32_bf16 v[2:5], v[200:203], v[232:235], v[2:5]
	s_setprio 0
	s_barrier
	s_add_i32 s62, 0, 0x18000
	s_add_i32 s63, 0, 0x1c000
	v_add_u32_e32 v94, s62, v177
	v_add_u32_e32 v166, s63, v177
	ds_read_b128 v[82:85], v94
	ds_read_b128 v[86:89], v94 offset:1024
	ds_read_b128 v[90:93], v94 offset:2048
	ds_read_b128 v[94:97], v94 offset:3072
	ds_read_b128 v[168:171], v166
	ds_read_b128 v[192:195], v166 offset:1024
	ds_read_b128 v[196:199], v166 offset:2048
	ds_read_b128 v[200:203], v166 offset:3072
	s_add_u32 s36, s36, 0x40000
	s_addc_u32 s37, s37, 0
	s_mov_b32 m0, s42
	v_lshl_add_u64 v[242:243], s[36:37], 0, v[146:147]
	ds_read_b128 v[204:207], v182 offset:32768
	ds_read_b128 v[208:211], v182 offset:33792
	ds_read_b128 v[212:215], v182 offset:34816
	ds_read_b128 v[216:219], v182 offset:35840
	ds_read_b128 v[220:223], v182 offset:36864
	ds_read_b128 v[224:227], v182 offset:37888
	ds_read_b128 v[228:231], v182 offset:38912
	ds_read_b128 v[232:235], v182 offset:39936
	global_load_lds_dwordx4 v[242:243], off
	v_lshl_add_u64 v[242:243], s[36:37], 0, v[150:151]
	s_mov_b32 m0, s43
	s_nop 0
	global_load_lds_dwordx4 v[242:243], off
	s_waitcnt vmcnt(8)
	s_waitcnt lgkmcnt(0)
	s_barrier
	s_setprio 1
	v_mfma_f32_16x16x32_bf16 v[142:145], v[82:85], v[204:207], v[142:145]
	v_mfma_f32_16x16x32_bf16 v[138:141], v[90:93], v[204:207], v[138:141]
	v_mfma_f32_16x16x32_bf16 v[126:129], v[82:85], v[212:215], v[126:129]
	v_mfma_f32_16x16x32_bf16 v[122:125], v[90:93], v[212:215], v[122:125]
	v_mfma_f32_16x16x32_bf16 v[110:113], v[82:85], v[220:223], v[110:113]
	v_mfma_f32_16x16x32_bf16 v[106:109], v[90:93], v[220:223], v[106:109]
	v_mfma_f32_16x16x32_bf16 v[78:81], v[82:85], v[228:231], v[78:81]
	v_mfma_f32_16x16x32_bf16 v[74:77], v[90:93], v[228:231], v[74:77]
	v_mfma_f32_16x16x32_bf16 v[142:145], v[86:89], v[208:211], v[142:145]
	v_mfma_f32_16x16x32_bf16 v[138:141], v[94:97], v[208:211], v[138:141]
	v_mfma_f32_16x16x32_bf16 v[126:129], v[86:89], v[216:219], v[126:129]
	v_mfma_f32_16x16x32_bf16 v[122:125], v[94:97], v[216:219], v[122:125]
	v_mfma_f32_16x16x32_bf16 v[110:113], v[86:89], v[224:227], v[110:113]
	v_mfma_f32_16x16x32_bf16 v[106:109], v[94:97], v[224:227], v[106:109]
	v_mfma_f32_16x16x32_bf16 v[78:81], v[86:89], v[232:235], v[78:81]
	v_mfma_f32_16x16x32_bf16 v[74:77], v[94:97], v[232:235], v[74:77]
	v_mfma_f32_16x16x32_bf16 v[134:137], v[168:171], v[204:207], v[134:137]
	v_mfma_f32_16x16x32_bf16 v[130:133], v[196:199], v[204:207], v[130:133]
	v_mfma_f32_16x16x32_bf16 v[118:121], v[168:171], v[212:215], v[118:121]
	v_mfma_f32_16x16x32_bf16 v[114:117], v[196:199], v[212:215], v[114:117]
	v_mfma_f32_16x16x32_bf16 v[102:105], v[168:171], v[220:223], v[102:105]
	v_mfma_f32_16x16x32_bf16 v[98:101], v[196:199], v[220:223], v[98:101]
	v_mfma_f32_16x16x32_bf16 v[70:73], v[168:171], v[228:231], v[70:73]
	v_mfma_f32_16x16x32_bf16 v[66:69], v[196:199], v[228:231], v[66:69]
	v_mfma_f32_16x16x32_bf16 v[134:137], v[192:195], v[208:211], v[134:137]
	v_mfma_f32_16x16x32_bf16 v[130:133], v[200:203], v[208:211], v[130:133]
	v_mfma_f32_16x16x32_bf16 v[118:121], v[192:195], v[216:219], v[118:121]
	v_mfma_f32_16x16x32_bf16 v[114:117], v[200:203], v[216:219], v[114:117]
	v_mfma_f32_16x16x32_bf16 v[102:105], v[192:195], v[224:227], v[102:105]
	v_mfma_f32_16x16x32_bf16 v[98:101], v[200:203], v[224:227], v[98:101]
	v_mfma_f32_16x16x32_bf16 v[70:73], v[192:195], v[232:235], v[70:73]
	v_mfma_f32_16x16x32_bf16 v[66:69], v[200:203], v[232:235], v[66:69]
	s_setprio 0
	s_barrier
	s_add_i32 s36, s62, s41
	v_lshl_add_u64 v[172:173], v[172:173], 0, s[12:13]
	s_mov_b32 m0, s36
	ds_read_b128 v[204:207], v182 offset:49152
	ds_read_b128 v[208:211], v182 offset:50176
	ds_read_b128 v[212:215], v182 offset:51200
	ds_read_b128 v[216:219], v182 offset:52224
	ds_read_b128 v[220:223], v182 offset:53248
	ds_read_b128 v[224:227], v182 offset:54272
	ds_read_b128 v[228:231], v182 offset:55296
	ds_read_b128 v[232:235], v182 offset:56320
	global_load_lds_dwordx4 v[172:173], off
	s_add_i32 m0, s36, 0x2000
	s_add_u32 s8, s8, 0x40080
	v_lshl_add_u64 v[172:173], v[236:237], 0, s[12:13]
	s_addc_u32 s9, s9, 0
	s_add_i32 s36, s63, s41
	global_load_lds_dwordx4 v[172:173], off
	v_lshl_add_u64 v[172:173], s[8:9], 0, v[148:149]
	s_mov_b32 m0, s36
	s_nop 0
	global_load_lds_dwordx4 v[172:173], off
	v_lshl_add_u64 v[172:173], s[8:9], 0, v[152:153]
	s_add_i32 m0, s36, 0x2000
	s_nop 0
	global_load_lds_dwordx4 v[172:173], off
	v_lshl_add_u64 v[172:173], v[238:239], 0, s[12:13]
	s_mov_b32 m0, s48
	s_nop 0
	global_load_lds_dwordx4 v[172:173], off
	v_lshl_add_u64 v[172:173], v[240:241], 0, s[12:13]
	s_mov_b32 m0, s49
	s_nop 0
	global_load_lds_dwordx4 v[172:173], off
	s_waitcnt vmcnt(8)
	s_waitcnt lgkmcnt(0)
	s_barrier
	s_setprio 1
	v_mfma_f32_16x16x32_bf16 v[62:65], v[82:85], v[204:207], v[62:65]
	v_mfma_f32_16x16x32_bf16 v[58:61], v[90:93], v[204:207], v[58:61]
	v_mfma_f32_16x16x32_bf16 v[46:49], v[82:85], v[212:215], v[46:49]
	v_mfma_f32_16x16x32_bf16 v[42:45], v[90:93], v[212:215], v[42:45]
	v_mfma_f32_16x16x32_bf16 v[30:33], v[82:85], v[220:223], v[30:33]
	v_mfma_f32_16x16x32_bf16 v[26:29], v[90:93], v[220:223], v[26:29]
	v_mfma_f32_16x16x32_bf16 v[14:17], v[82:85], v[228:231], v[14:17]
	v_mfma_f32_16x16x32_bf16 v[10:13], v[90:93], v[228:231], v[10:13]
	v_mfma_f32_16x16x32_bf16 v[62:65], v[86:89], v[208:211], v[62:65]
	v_mfma_f32_16x16x32_bf16 v[58:61], v[94:97], v[208:211], v[58:61]
	v_mfma_f32_16x16x32_bf16 v[46:49], v[86:89], v[216:219], v[46:49]
	v_mfma_f32_16x16x32_bf16 v[42:45], v[94:97], v[216:219], v[42:45]
	v_mfma_f32_16x16x32_bf16 v[30:33], v[86:89], v[224:227], v[30:33]
	v_mfma_f32_16x16x32_bf16 v[26:29], v[94:97], v[224:227], v[26:29]
	v_mfma_f32_16x16x32_bf16 v[14:17], v[86:89], v[232:235], v[14:17]
	v_mfma_f32_16x16x32_bf16 v[10:13], v[94:97], v[232:235], v[10:13]
	v_mfma_f32_16x16x32_bf16 v[54:57], v[168:171], v[204:207], v[54:57]
	v_mfma_f32_16x16x32_bf16 v[50:53], v[196:199], v[204:207], v[50:53]
	v_mfma_f32_16x16x32_bf16 v[38:41], v[168:171], v[212:215], v[38:41]
	v_mfma_f32_16x16x32_bf16 v[34:37], v[196:199], v[212:215], v[34:37]
	v_mfma_f32_16x16x32_bf16 v[22:25], v[168:171], v[220:223], v[22:25]
	v_mfma_f32_16x16x32_bf16 v[18:21], v[196:199], v[220:223], v[18:21]
	v_mfma_f32_16x16x32_bf16 v[6:9], v[168:171], v[228:231], v[6:9]
	v_mfma_f32_16x16x32_bf16 v[2:5], v[196:199], v[228:231], v[2:5]
	v_mfma_f32_16x16x32_bf16 v[54:57], v[192:195], v[208:211], v[54:57]
	v_mfma_f32_16x16x32_bf16 v[50:53], v[200:203], v[208:211], v[50:53]
	v_mfma_f32_16x16x32_bf16 v[38:41], v[192:195], v[216:219], v[38:41]
	v_mfma_f32_16x16x32_bf16 v[34:37], v[200:203], v[216:219], v[34:37]
	v_mfma_f32_16x16x32_bf16 v[22:25], v[192:195], v[224:227], v[22:25]
	v_mfma_f32_16x16x32_bf16 v[18:21], v[200:203], v[224:227], v[18:21]
	v_mfma_f32_16x16x32_bf16 v[6:9], v[192:195], v[232:235], v[6:9]
	v_mfma_f32_16x16x32_bf16 v[2:5], v[200:203], v[232:235], v[2:5]
	s_setprio 0
	s_barrier
	s_add_i32 s61, s61, 2
	s_add_u32 s59, s59, 0x100
	s_addc_u32 s60, s60, 0
	s_add_u32 s6, s6, 0x100
	s_addc_u32 s7, s7, 0
	s_cmp_gt_u32 s61, 13
	s_cbranch_scc0 .LBB0_1477
	s_andn2_b64 vcc, exec, s[2:3]
	s_cbranch_vccnz .Lrs8h_skip2
	v_lshl_add_u32 v204, s24, 8, v176
	v_ashrrev_i32_e32 v205, 31, v204
	v_lshlrev_b64 v[196:197], 6, v[204:205]
	v_lshl_add_u64 v[212:213], v[156:157], 0, v[196:197]
	v_or_b32_e32 v196, 16, v204
	v_or_b32_e32 v206, 32, v204
	v_or_b32_e32 v204, 48, v204
	v_ashrrev_i32_e32 v197, 31, v196
	v_ashrrev_i32_e32 v207, 31, v206
	v_ashrrev_i32_e32 v205, 31, v204
	v_lshlrev_b64 v[196:197], 6, v[196:197]
	v_lshlrev_b64 v[206:207], 6, v[206:207]
	v_lshlrev_b64 v[204:205], 6, v[204:205]
	v_add_co_u32_e32 v224, vcc, s44, v212
	v_lshl_add_u64 v[200:201], v[156:157], 0, v[196:197]
	v_lshl_add_u64 v[206:207], v[156:157], 0, v[206:207]
	v_lshl_add_u64 v[208:209], v[156:157], 0, v[204:205]
	v_addc_co_u32_e32 v225, vcc, 0, v213, vcc
	flat_load_dwordx4 v[196:199], v[212:213]
	s_nop 0
	flat_load_dwordx4 v[200:203], v[200:201]
	s_nop 0
	flat_load_dwordx4 v[204:207], v[206:207]
	s_nop 0
	flat_load_dwordx4 v[208:211], v[208:209]
	s_nop 0
	flat_load_dwordx4 v[212:215], v[224:225]
	flat_load_dwordx4 v[216:219], v[224:225] offset:1024
	flat_load_dwordx4 v[220:223], v[224:225] offset:2048
	s_nop 0
	flat_load_dwordx4 v[224:227], v[224:225] offset:3072

.LBB0_1817:
	v_add_u32_e32 v154, s64, v156
	ds_read_b128 v[130:133], v154
	ds_read_b128 v[150:153], v154 offset:1024
	ds_read_b128 v[160:163], v154 offset:2048
	ds_read_b128 v[164:167], v154 offset:3072
	v_add_u32_e32 v154, s65, v156
	ds_read_b128 v[168:171], v154
	ds_read_b128 v[172:175], v154 offset:1024
	ds_read_b128 v[180:183], v154 offset:2048
	ds_read_b128 v[184:187], v154 offset:3072
	s_add_u32 s44, s42, 0xfffc0080
	s_addc_u32 s45, s43, -1
	s_cmp_eq_u32 s70, 12
	s_cselect_b32 s47, s35, s45
	s_cselect_b32 s46, s41, s44
	s_cselect_b32 s45, s31, s69
	s_cselect_b32 s44, s67, s68
	v_lshl_add_u64 v[154:155], s[42:43], 0, v[144:145]
	s_add_i32 m0, s53, 0xc000
	ds_read_b128 v[188:191], v158
	ds_read_b128 v[192:195], v158 offset:1024
	ds_read_b128 v[196:199], v158 offset:2048
	ds_read_b128 v[200:203], v158 offset:3072
	ds_read_b128 v[204:207], v158 offset:4096
	ds_read_b128 v[208:211], v158 offset:5120
	ds_read_b128 v[212:215], v158 offset:6144
	ds_read_b128 v[216:219], v158 offset:7168
	global_load_lds_dwordx4 v[154:155], off
	v_lshl_add_u64 v[154:155], s[42:43], 0, v[142:143]
	s_add_i32 m0, s53, 0xe000
	s_nop 0
	global_load_lds_dwordx4 v[154:155], off
	s_waitcnt vmcnt(8)
	s_waitcnt lgkmcnt(0)
	s_barrier
	s_setprio 1
	v_mfma_f32_16x16x32_bf16 v[114:117], v[130:133], v[188:191], v[114:117]
	v_mfma_f32_16x16x32_bf16 v[118:121], v[160:163], v[188:191], v[118:121]
	v_mfma_f32_16x16x32_bf16 v[98:101], v[130:133], v[196:199], v[98:101]
	v_mfma_f32_16x16x32_bf16 v[102:105], v[160:163], v[196:199], v[102:105]
	v_mfma_f32_16x16x32_bf16 v[82:85], v[130:133], v[204:207], v[82:85]
	v_mfma_f32_16x16x32_bf16 v[86:89], v[160:163], v[204:207], v[86:89]
	v_mfma_f32_16x16x32_bf16 v[66:69], v[130:133], v[212:215], v[66:69]
	v_mfma_f32_16x16x32_bf16 v[70:73], v[160:163], v[212:215], v[70:73]
	v_mfma_f32_16x16x32_bf16 v[114:117], v[150:153], v[192:195], v[114:117]
	v_mfma_f32_16x16x32_bf16 v[118:121], v[164:167], v[192:195], v[118:121]
	v_mfma_f32_16x16x32_bf16 v[98:101], v[150:153], v[200:203], v[98:101]
	v_mfma_f32_16x16x32_bf16 v[102:105], v[164:167], v[200:203], v[102:105]
	v_mfma_f32_16x16x32_bf16 v[82:85], v[150:153], v[208:211], v[82:85]
	v_mfma_f32_16x16x32_bf16 v[86:89], v[164:167], v[208:211], v[86:89]
	v_mfma_f32_16x16x32_bf16 v[66:69], v[150:153], v[216:219], v[66:69]
	v_mfma_f32_16x16x32_bf16 v[70:73], v[164:167], v[216:219], v[70:73]
	v_mfma_f32_16x16x32_bf16 v[122:125], v[168:171], v[188:191], v[122:125]
	v_mfma_f32_16x16x32_bf16 v[126:129], v[180:183], v[188:191], v[126:129]
	v_mfma_f32_16x16x32_bf16 v[106:109], v[168:171], v[196:199], v[106:109]
	v_mfma_f32_16x16x32_bf16 v[110:113], v[180:183], v[196:199], v[110:113]
	v_mfma_f32_16x16x32_bf16 v[90:93], v[168:171], v[204:207], v[90:93]
	v_mfma_f32_16x16x32_bf16 v[94:97], v[180:183], v[204:207], v[94:97]
	v_mfma_f32_16x16x32_bf16 v[74:77], v[168:171], v[212:215], v[74:77]
	v_mfma_f32_16x16x32_bf16 v[78:81], v[180:183], v[212:215], v[78:81]
	v_mfma_f32_16x16x32_bf16 v[122:125], v[172:175], v[192:195], v[122:125]
	v_mfma_f32_16x16x32_bf16 v[126:129], v[184:187], v[192:195], v[126:129]
	v_mfma_f32_16x16x32_bf16 v[106:109], v[172:175], v[200:203], v[106:109]
	v_mfma_f32_16x16x32_bf16 v[110:113], v[184:187], v[200:203], v[110:113]
	v_mfma_f32_16x16x32_bf16 v[90:93], v[172:175], v[208:211], v[90:93]
	v_mfma_f32_16x16x32_bf16 v[94:97], v[184:187], v[208:211], v[94:97]
	v_mfma_f32_16x16x32_bf16 v[74:77], v[172:175], v[216:219], v[74:77]
	v_mfma_f32_16x16x32_bf16 v[78:81], v[184:187], v[216:219], v[78:81]
	s_setprio 0
	s_barrier
	s_add_i32 s71, s64, s52
	v_lshl_add_u64 v[154:155], s[44:45], 0, v[136:137]
	s_mov_b32 m0, s71
	ds_read_b128 v[188:191], v158 offset:16384
	ds_read_b128 v[192:195], v158 offset:17408
	ds_read_b128 v[196:199], v158 offset:18432
	ds_read_b128 v[200:203], v158 offset:19456
	ds_read_b128 v[204:207], v158 offset:20480
	ds_read_b128 v[208:211], v158 offset:21504
	ds_read_b128 v[212:215], v158 offset:22528
	ds_read_b128 v[216:219], v158 offset:23552
	global_load_lds_dwordx4 v[154:155], off
	s_add_i32 m0, s71, 0x2000
	s_add_u32 s72, s44, 0x40000
	v_lshl_add_u64 v[176:177], s[44:45], 0, v[140:141]
	s_addc_u32 s73, s45, 0
	s_add_i32 s71, s65, s52
	global_load_lds_dwordx4 v[176:177], off
	v_lshl_add_u64 v[220:221], s[72:73], 0, v[136:137]
	s_mov_b32 m0, s71
	v_lshl_add_u64 v[222:223], s[46:47], 0, v[138:139]
	global_load_lds_dwordx4 v[220:221], off
	v_lshl_add_u64 v[220:221], s[72:73], 0, v[140:141]
	s_add_i32 m0, s71, 0x2000
	s_nop 0
	global_load_lds_dwordx4 v[220:221], off
	v_lshl_add_u64 v[220:221], s[46:47], 0, v[134:135]
	s_mov_b32 m0, s53
	s_nop 0
	global_load_lds_dwordx4 v[220:221], off
	s_mov_b32 m0, s54
	s_nop 0
	global_load_lds_dwordx4 v[222:223], off
	s_waitcnt vmcnt(8)
	s_waitcnt lgkmcnt(0)
	s_barrier
	s_setprio 1
	v_mfma_f32_16x16x32_bf16 v[50:53], v[130:133], v[188:191], v[50:53]
	v_mfma_f32_16x16x32_bf16 v[54:57], v[160:163], v[188:191], v[54:57]
	v_mfma_f32_16x16x32_bf16 v[26:29], v[130:133], v[196:199], v[26:29]
	v_mfma_f32_16x16x32_bf16 v[30:33], v[160:163], v[196:199], v[30:33]
	v_mfma_f32_16x16x32_bf16 v[18:21], v[130:133], v[204:207], v[18:21]
	v_mfma_f32_16x16x32_bf16 v[22:25], v[160:163], v[204:207], v[22:25]
	v_mfma_f32_16x16x32_bf16 v[2:5], v[130:133], v[212:215], v[2:5]
	v_mfma_f32_16x16x32_bf16 v[6:9], v[160:163], v[212:215], v[6:9]
	v_mfma_f32_16x16x32_bf16 v[50:53], v[150:153], v[192:195], v[50:53]
	v_mfma_f32_16x16x32_bf16 v[54:57], v[164:167], v[192:195], v[54:57]
	v_mfma_f32_16x16x32_bf16 v[26:29], v[150:153], v[200:203], v[26:29]
	v_mfma_f32_16x16x32_bf16 v[30:33], v[164:167], v[200:203], v[30:33]
	v_mfma_f32_16x16x32_bf16 v[18:21], v[150:153], v[208:211], v[18:21]
	v_mfma_f32_16x16x32_bf16 v[22:25], v[164:167], v[208:211], v[22:25]
	v_mfma_f32_16x16x32_bf16 v[2:5], v[150:153], v[216:219], v[2:5]
	v_mfma_f32_16x16x32_bf16 v[6:9], v[164:167], v[216:219], v[6:9]
	v_mfma_f32_16x16x32_bf16 v[58:61], v[168:171], v[188:191], v[58:61]
	v_mfma_f32_16x16x32_bf16 v[62:65], v[180:183], v[188:191], v[62:65]
	v_mfma_f32_16x16x32_bf16 v[42:45], v[168:171], v[196:199], v[42:45]
	v_mfma_f32_16x16x32_bf16 v[46:49], v[180:183], v[196:199], v[46:49]
	v_mfma_f32_16x16x32_bf16 v[34:37], v[168:171], v[204:207], v[34:37]
	v_mfma_f32_16x16x32_bf16 v[38:41], v[180:183], v[204:207], v[38:41]
	v_mfma_f32_16x16x32_bf16 v[10:13], v[168:171], v[212:215], v[10:13]
	v_mfma_f32_16x16x32_bf16 v[14:17], v[180:183], v[212:215], v[14:17]
	v_mfma_f32_16x16x32_bf16 v[58:61], v[172:175], v[192:195], v[58:61]
	v_mfma_f32_16x16x32_bf16 v[62:65], v[184:187], v[192:195], v[62:65]
	v_mfma_f32_16x16x32_bf16 v[42:45], v[172:175], v[200:203], v[42:45]
	v_mfma_f32_16x16x32_bf16 v[46:49], v[184:187], v[200:203], v[46:49]
	v_mfma_f32_16x16x32_bf16 v[34:37], v[172:175], v[208:211], v[34:37]
	v_mfma_f32_16x16x32_bf16 v[38:41], v[184:187], v[208:211], v[38:41]
	v_mfma_f32_16x16x32_bf16 v[10:13], v[172:175], v[216:219], v[10:13]
	v_mfma_f32_16x16x32_bf16 v[14:17], v[184:187], v[216:219], v[14:17]
	s_setprio 0
	s_barrier
	s_add_i32 s71, 0, 0x18000
	s_add_i32 s72, 0, 0x1c000
	v_add_u32_e32 v164, s71, v156
	v_add_u32_e32 v179, s72, v156
	ds_read_b128 v[130:133], v164
	ds_read_b128 v[150:153], v164 offset:1024
	ds_read_b128 v[160:163], v164 offset:2048
	ds_read_b128 v[164:167], v164 offset:3072
	ds_read_b128 v[168:171], v179
	ds_read_b128 v[172:175], v179 offset:1024
	ds_read_b128 v[180:183], v179 offset:2048
	ds_read_b128 v[184:187], v179 offset:3072
	s_add_u32 s46, s46, 0x40000
	s_addc_u32 s47, s47, 0
	s_mov_b32 m0, s55
	v_lshl_add_u64 v[224:225], s[46:47], 0, v[134:135]
	ds_read_b128 v[188:191], v158 offset:32768
	ds_read_b128 v[192:195], v158 offset:33792
	ds_read_b128 v[196:199], v158 offset:34816
	ds_read_b128 v[200:203], v158 offset:35840
	ds_read_b128 v[204:207], v158 offset:36864
	ds_read_b128 v[208:211], v158 offset:37888
	ds_read_b128 v[212:215], v158 offset:38912
	ds_read_b128 v[216:219], v158 offset:39936
	global_load_lds_dwordx4 v[224:225], off
	v_lshl_add_u64 v[224:225], s[46:47], 0, v[138:139]
	s_mov_b32 m0, s56
	s_nop 0
	global_load_lds_dwordx4 v[224:225], off
	s_waitcnt vmcnt(8)
	s_waitcnt lgkmcnt(0)
	s_barrier
	s_setprio 1
	v_mfma_f32_16x16x32_bf16 v[114:117], v[130:133], v[188:191], v[114:117]
	v_mfma_f32_16x16x32_bf16 v[118:121], v[160:163], v[188:191], v[118:121]
	v_mfma_f32_16x16x32_bf16 v[98:101], v[130:133], v[196:199], v[98:101]
	v_mfma_f32_16x16x32_bf16 v[102:105], v[160:163], v[196:199], v[102:105]
	v_mfma_f32_16x16x32_bf16 v[82:85], v[130:133], v[204:207], v[82:85]
	v_mfma_f32_16x16x32_bf16 v[86:89], v[160:163], v[204:207], v[86:89]
	v_mfma_f32_16x16x32_bf16 v[66:69], v[130:133], v[212:215], v[66:69]
	v_mfma_f32_16x16x32_bf16 v[70:73], v[160:163], v[212:215], v[70:73]
	v_mfma_f32_16x16x32_bf16 v[114:117], v[150:153], v[192:195], v[114:117]
	v_mfma_f32_16x16x32_bf16 v[118:121], v[164:167], v[192:195], v[118:121]
	v_mfma_f32_16x16x32_bf16 v[98:101], v[150:153], v[200:203], v[98:101]
	v_mfma_f32_16x16x32_bf16 v[102:105], v[164:167], v[200:203], v[102:105]
	v_mfma_f32_16x16x32_bf16 v[82:85], v[150:153], v[208:211], v[82:85]
	v_mfma_f32_16x16x32_bf16 v[86:89], v[164:167], v[208:211], v[86:89]
	v_mfma_f32_16x16x32_bf16 v[66:69], v[150:153], v[216:219], v[66:69]
	v_mfma_f32_16x16x32_bf16 v[70:73], v[164:167], v[216:219], v[70:73]
	v_mfma_f32_16x16x32_bf16 v[122:125], v[168:171], v[188:191], v[122:125]
	v_mfma_f32_16x16x32_bf16 v[126:129], v[180:183], v[188:191], v[126:129]
	v_mfma_f32_16x16x32_bf16 v[106:109], v[168:171], v[196:199], v[106:109]
	v_mfma_f32_16x16x32_bf16 v[110:113], v[180:183], v[196:199], v[110:113]
	v_mfma_f32_16x16x32_bf16 v[90:93], v[168:171], v[204:207], v[90:93]
	v_mfma_f32_16x16x32_bf16 v[94:97], v[180:183], v[204:207], v[94:97]
	v_mfma_f32_16x16x32_bf16 v[74:77], v[168:171], v[212:215], v[74:77]
	v_mfma_f32_16x16x32_bf16 v[78:81], v[180:183], v[212:215], v[78:81]
	v_mfma_f32_16x16x32_bf16 v[122:125], v[172:175], v[192:195], v[122:125]
	v_mfma_f32_16x16x32_bf16 v[126:129], v[184:187], v[192:195], v[126:129]
	v_mfma_f32_16x16x32_bf16 v[106:109], v[172:175], v[200:203], v[106:109]
	v_mfma_f32_16x16x32_bf16 v[110:113], v[184:187], v[200:203], v[110:113]
	v_mfma_f32_16x16x32_bf16 v[90:93], v[172:175], v[208:211], v[90:93]
	v_mfma_f32_16x16x32_bf16 v[94:97], v[184:187], v[208:211], v[94:97]
	v_mfma_f32_16x16x32_bf16 v[74:77], v[172:175], v[216:219], v[74:77]
	v_mfma_f32_16x16x32_bf16 v[78:81], v[184:187], v[216:219], v[78:81]
	s_setprio 0
	s_barrier
	s_add_i32 s46, s71, s52
	v_lshl_add_u64 v[154:155], v[154:155], 0, s[24:25]
	s_mov_b32 m0, s46
	ds_read_b128 v[188:191], v158 offset:49152
	ds_read_b128 v[192:195], v158 offset:50176
	ds_read_b128 v[196:199], v158 offset:51200
	ds_read_b128 v[200:203], v158 offset:52224
	ds_read_b128 v[204:207], v158 offset:53248
	ds_read_b128 v[208:211], v158 offset:54272
	ds_read_b128 v[212:215], v158 offset:55296
	ds_read_b128 v[216:219], v158 offset:56320
	global_load_lds_dwordx4 v[154:155], off
	s_add_i32 m0, s46, 0x2000
	s_add_u32 s44, s44, 0x40080
	v_lshl_add_u64 v[154:155], v[176:177], 0, s[24:25]
	s_addc_u32 s45, s45, 0
	s_add_i32 s46, s72, s52
	global_load_lds_dwordx4 v[154:155], off
	v_lshl_add_u64 v[154:155], s[44:45], 0, v[136:137]
	s_mov_b32 m0, s46
	s_nop 0
	global_load_lds_dwordx4 v[154:155], off
	v_lshl_add_u64 v[154:155], s[44:45], 0, v[140:141]
	s_add_i32 m0, s46, 0x2000
	s_nop 0
	global_load_lds_dwordx4 v[154:155], off
	v_lshl_add_u64 v[154:155], v[220:221], 0, s[24:25]
	s_mov_b32 m0, s59
	s_nop 0
	global_load_lds_dwordx4 v[154:155], off
	v_lshl_add_u64 v[154:155], v[222:223], 0, s[24:25]
	s_mov_b32 m0, s60
	s_nop 0
	global_load_lds_dwordx4 v[154:155], off
	s_waitcnt vmcnt(8)
	s_waitcnt lgkmcnt(0)
	s_barrier
	s_setprio 1
	v_mfma_f32_16x16x32_bf16 v[50:53], v[130:133], v[188:191], v[50:53]
	v_mfma_f32_16x16x32_bf16 v[54:57], v[160:163], v[188:191], v[54:57]
	v_mfma_f32_16x16x32_bf16 v[26:29], v[130:133], v[196:199], v[26:29]
	v_mfma_f32_16x16x32_bf16 v[30:33], v[160:163], v[196:199], v[30:33]
	v_mfma_f32_16x16x32_bf16 v[18:21], v[130:133], v[204:207], v[18:21]
	v_mfma_f32_16x16x32_bf16 v[22:25], v[160:163], v[204:207], v[22:25]
	v_mfma_f32_16x16x32_bf16 v[2:5], v[130:133], v[212:215], v[2:5]
	v_mfma_f32_16x16x32_bf16 v[6:9], v[160:163], v[212:215], v[6:9]
	v_mfma_f32_16x16x32_bf16 v[50:53], v[150:153], v[192:195], v[50:53]
	v_mfma_f32_16x16x32_bf16 v[54:57], v[164:167], v[192:195], v[54:57]
	v_mfma_f32_16x16x32_bf16 v[26:29], v[150:153], v[200:203], v[26:29]
	v_mfma_f32_16x16x32_bf16 v[30:33], v[164:167], v[200:203], v[30:33]
	v_mfma_f32_16x16x32_bf16 v[18:21], v[150:153], v[208:211], v[18:21]
	v_mfma_f32_16x16x32_bf16 v[22:25], v[164:167], v[208:211], v[22:25]
	v_mfma_f32_16x16x32_bf16 v[2:5], v[150:153], v[216:219], v[2:5]
	v_mfma_f32_16x16x32_bf16 v[6:9], v[164:167], v[216:219], v[6:9]
	v_mfma_f32_16x16x32_bf16 v[58:61], v[168:171], v[188:191], v[58:61]
	v_mfma_f32_16x16x32_bf16 v[62:65], v[180:183], v[188:191], v[62:65]
	v_mfma_f32_16x16x32_bf16 v[42:45], v[168:171], v[196:199], v[42:45]
	v_mfma_f32_16x16x32_bf16 v[46:49], v[180:183], v[196:199], v[46:49]
	v_mfma_f32_16x16x32_bf16 v[34:37], v[168:171], v[204:207], v[34:37]
	v_mfma_f32_16x16x32_bf16 v[38:41], v[180:183], v[204:207], v[38:41]
	v_mfma_f32_16x16x32_bf16 v[10:13], v[168:171], v[212:215], v[10:13]
	v_mfma_f32_16x16x32_bf16 v[14:17], v[180:183], v[212:215], v[14:17]
	v_mfma_f32_16x16x32_bf16 v[58:61], v[172:175], v[192:195], v[58:61]
	v_mfma_f32_16x16x32_bf16 v[62:65], v[184:187], v[192:195], v[62:65]
	v_mfma_f32_16x16x32_bf16 v[42:45], v[172:175], v[200:203], v[42:45]
	v_mfma_f32_16x16x32_bf16 v[46:49], v[184:187], v[200:203], v[46:49]
	v_mfma_f32_16x16x32_bf16 v[34:37], v[172:175], v[208:211], v[34:37]
	v_mfma_f32_16x16x32_bf16 v[38:41], v[184:187], v[208:211], v[38:41]
	v_mfma_f32_16x16x32_bf16 v[10:13], v[172:175], v[216:219], v[10:13]
	v_mfma_f32_16x16x32_bf16 v[14:17], v[184:187], v[216:219], v[14:17]
	s_setprio 0
	s_barrier
	s_add_i32 s70, s70, 2
	s_add_u32 s68, s68, 0x100
	s_addc_u32 s69, s69, 0
	s_add_u32 s42, s42, 0x100
	s_addc_u32 s43, s43, 0
	s_cmp_gt_u32 s70, 13
	s_cbranch_scc0 .LBB0_1817
	s_and_b64 vcc, exec, s[26:27]
	s_cbranch_vccz .LBB0_1820
	s_barrier

.LBB0_2352:
	s_add_u32 s45, s38, s44
	s_addc_u32 s50, s39, 0
	s_add_u32 s48, s45, 0x100
	s_addc_u32 s49, s50, 0
	s_and_b64 s[46:47], s[42:43], exec
	s_cselect_b32 s47, s25, s49
	s_cselect_b32 s46, s31, s48
	s_add_u32 s44, s36, s44
	s_addc_u32 s48, s37, 0
	s_add_u32 s44, s44, 0x100
	s_addc_u32 s48, s48, 0
	s_and_b64 s[42:43], s[42:43], exec
	s_cselect_b32 s49, s23, s48
	s_cselect_b32 s48, s68, s44
	s_add_u32 s52, s45, 0x10080
	ds_read_b128 v[140:143], v147
	ds_read_b128 v[150:153], v147 offset:1024
	ds_read_b128 v[154:157], v147 offset:2048
	ds_read_b128 v[158:161], v147 offset:3072
	ds_read_b128 v[162:165], v148
	ds_read_b128 v[166:169], v148 offset:1024
	ds_read_b128 v[170:173], v148 offset:2048
	ds_read_b128 v[174:177], v148 offset:3072
	s_addc_u32 s53, s50, 0
	s_add_i32 s76, s66, s57
	s_add_i32 m0, s35, 0xc000
	s_add_i32 s79, s35, 0xe000
	s_add_i32 s73, s76, 0x2000
	s_add_u32 s50, s48, 0x10000
	s_addc_u32 s51, s49, 0
	s_add_i32 s75, s67, s57
	s_add_i32 s74, s75, 0x2000
	s_add_i32 s72, 0, 0x18000
	s_add_i32 s71, 0, 0x1c000
	s_add_u32 s44, s46, 0x10000
	s_addc_u32 s45, s47, 0
	s_add_i32 s70, s72, s57
	s_add_i32 s69, s70, 0x2000
	s_add_u32 s42, s48, 0x10080
	s_addc_u32 s43, s49, 0
	s_add_i32 s78, s71, s57
	s_add_i32 s77, s78, 0x2000
	v_lshl_add_u64 v[212:213], s[52:53], 0, v[128:129]
	ds_read_b128 v[180:183], v149
	ds_read_b128 v[184:187], v149 offset:1024
	ds_read_b128 v[188:191], v149 offset:2048
	ds_read_b128 v[192:195], v149 offset:3072
	ds_read_b128 v[196:199], v149 offset:4096
	ds_read_b128 v[200:203], v149 offset:5120
	ds_read_b128 v[204:207], v149 offset:6144
	ds_read_b128 v[208:211], v149 offset:7168
	global_load_lds_dwordx4 v[212:213], off
	v_lshl_add_u64 v[212:213], s[52:53], 0, v[132:133]
	s_mov_b32 m0, s79
	s_nop 0
	global_load_lds_dwordx4 v[212:213], off
	s_waitcnt vmcnt(8)
	s_waitcnt lgkmcnt(0)
	s_barrier
	s_setprio 1
	v_mfma_f32_16x16x32_bf16 v[124:127], v[140:143], v[180:183], v[124:127]
	v_mfma_f32_16x16x32_bf16 v[120:123], v[154:157], v[180:183], v[120:123]
	v_mfma_f32_16x16x32_bf16 v[108:111], v[140:143], v[188:191], v[108:111]
	v_mfma_f32_16x16x32_bf16 v[104:107], v[154:157], v[188:191], v[104:107]
	v_mfma_f32_16x16x32_bf16 v[92:95], v[140:143], v[196:199], v[92:95]
	v_mfma_f32_16x16x32_bf16 v[88:91], v[154:157], v[196:199], v[88:91]
	v_mfma_f32_16x16x32_bf16 v[76:79], v[140:143], v[204:207], v[76:79]
	v_mfma_f32_16x16x32_bf16 v[72:75], v[154:157], v[204:207], v[72:75]
	v_mfma_f32_16x16x32_bf16 v[124:127], v[150:153], v[184:187], v[124:127]
	v_mfma_f32_16x16x32_bf16 v[120:123], v[158:161], v[184:187], v[120:123]
	v_mfma_f32_16x16x32_bf16 v[108:111], v[150:153], v[192:195], v[108:111]
	v_mfma_f32_16x16x32_bf16 v[104:107], v[158:161], v[192:195], v[104:107]
	v_mfma_f32_16x16x32_bf16 v[92:95], v[150:153], v[200:203], v[92:95]
	v_mfma_f32_16x16x32_bf16 v[88:91], v[158:161], v[200:203], v[88:91]
	v_mfma_f32_16x16x32_bf16 v[76:79], v[150:153], v[208:211], v[76:79]
	v_mfma_f32_16x16x32_bf16 v[72:75], v[158:161], v[208:211], v[72:75]
	v_mfma_f32_16x16x32_bf16 v[116:119], v[162:165], v[180:183], v[116:119]
	v_mfma_f32_16x16x32_bf16 v[112:115], v[170:173], v[180:183], v[112:115]
	v_mfma_f32_16x16x32_bf16 v[100:103], v[162:165], v[188:191], v[100:103]
	v_mfma_f32_16x16x32_bf16 v[96:99], v[170:173], v[188:191], v[96:99]
	v_mfma_f32_16x16x32_bf16 v[84:87], v[162:165], v[196:199], v[84:87]
	v_mfma_f32_16x16x32_bf16 v[80:83], v[170:173], v[196:199], v[80:83]
	v_mfma_f32_16x16x32_bf16 v[68:71], v[162:165], v[204:207], v[68:71]
	v_mfma_f32_16x16x32_bf16 v[64:67], v[170:173], v[204:207], v[64:67]
	v_mfma_f32_16x16x32_bf16 v[116:119], v[166:169], v[184:187], v[116:119]
	v_mfma_f32_16x16x32_bf16 v[112:115], v[174:177], v[184:187], v[112:115]
	v_mfma_f32_16x16x32_bf16 v[100:103], v[166:169], v[192:195], v[100:103]
	v_mfma_f32_16x16x32_bf16 v[96:99], v[174:177], v[192:195], v[96:99]
	v_mfma_f32_16x16x32_bf16 v[84:87], v[166:169], v[200:203], v[84:87]
	v_mfma_f32_16x16x32_bf16 v[80:83], v[174:177], v[200:203], v[80:83]
	v_mfma_f32_16x16x32_bf16 v[68:71], v[166:169], v[208:211], v[68:71]
	v_mfma_f32_16x16x32_bf16 v[64:67], v[174:177], v[208:211], v[64:67]
	s_setprio 0
	s_barrier
	s_mov_b32 m0, s76
	v_lshl_add_u64 v[212:213], s[48:49], 0, v[130:131]
	ds_read_b128 v[180:183], v149 offset:16384
	ds_read_b128 v[184:187], v149 offset:17408
	ds_read_b128 v[188:191], v149 offset:18432
	ds_read_b128 v[192:195], v149 offset:19456
	ds_read_b128 v[196:199], v149 offset:20480
	ds_read_b128 v[200:203], v149 offset:21504
	ds_read_b128 v[204:207], v149 offset:22528
	ds_read_b128 v[208:211], v149 offset:23552
	global_load_lds_dwordx4 v[212:213], off
	v_lshl_add_u64 v[214:215], s[48:49], 0, v[134:135]
	s_mov_b32 m0, s73
	v_lshl_add_u64 v[216:217], s[50:51], 0, v[130:131]
	global_load_lds_dwordx4 v[214:215], off
	s_mov_b32 m0, s75
	v_lshl_add_u64 v[218:219], s[46:47], 0, v[132:133]
	global_load_lds_dwordx4 v[216:217], off
	v_lshl_add_u64 v[216:217], s[50:51], 0, v[134:135]
	s_mov_b32 m0, s74
	s_nop 0
	global_load_lds_dwordx4 v[216:217], off
	v_lshl_add_u64 v[216:217], s[46:47], 0, v[128:129]
	s_mov_b32 m0, s35
	s_nop 0
	global_load_lds_dwordx4 v[216:217], off
	s_mov_b32 m0, s58
	s_nop 0
	global_load_lds_dwordx4 v[218:219], off
	s_waitcnt vmcnt(8)
	s_waitcnt lgkmcnt(0)
	s_barrier
	s_setprio 1
	v_mfma_f32_16x16x32_bf16 v[60:63], v[140:143], v[180:183], v[60:63]
	v_mfma_f32_16x16x32_bf16 v[56:59], v[154:157], v[180:183], v[56:59]
	v_mfma_f32_16x16x32_bf16 v[44:47], v[140:143], v[188:191], v[44:47]
	v_mfma_f32_16x16x32_bf16 v[40:43], v[154:157], v[188:191], v[40:43]
	v_mfma_f32_16x16x32_bf16 v[28:31], v[140:143], v[196:199], v[28:31]
	v_mfma_f32_16x16x32_bf16 v[24:27], v[154:157], v[196:199], v[24:27]
	v_mfma_f32_16x16x32_bf16 v[12:15], v[140:143], v[204:207], v[12:15]
	v_mfma_f32_16x16x32_bf16 v[8:11], v[154:157], v[204:207], v[8:11]
	v_mfma_f32_16x16x32_bf16 v[60:63], v[150:153], v[184:187], v[60:63]
	v_mfma_f32_16x16x32_bf16 v[56:59], v[158:161], v[184:187], v[56:59]
	v_mfma_f32_16x16x32_bf16 v[44:47], v[150:153], v[192:195], v[44:47]
	v_mfma_f32_16x16x32_bf16 v[40:43], v[158:161], v[192:195], v[40:43]
	v_mfma_f32_16x16x32_bf16 v[28:31], v[150:153], v[200:203], v[28:31]
	v_mfma_f32_16x16x32_bf16 v[24:27], v[158:161], v[200:203], v[24:27]
	v_mfma_f32_16x16x32_bf16 v[12:15], v[150:153], v[208:211], v[12:15]
	v_mfma_f32_16x16x32_bf16 v[8:11], v[158:161], v[208:211], v[8:11]
	v_mfma_f32_16x16x32_bf16 v[52:55], v[162:165], v[180:183], v[52:55]
	v_mfma_f32_16x16x32_bf16 v[48:51], v[170:173], v[180:183], v[48:51]
	v_mfma_f32_16x16x32_bf16 v[36:39], v[162:165], v[188:191], v[36:39]
	v_mfma_f32_16x16x32_bf16 v[32:35], v[170:173], v[188:191], v[32:35]
	v_mfma_f32_16x16x32_bf16 v[20:23], v[162:165], v[196:199], v[20:23]
	v_mfma_f32_16x16x32_bf16 v[16:19], v[170:173], v[196:199], v[16:19]
	v_mfma_f32_16x16x32_bf16 v[4:7], v[162:165], v[204:207], v[4:7]
	v_mfma_f32_16x16x32_bf16 v[0:3], v[170:173], v[204:207], v[0:3]
	v_mfma_f32_16x16x32_bf16 v[52:55], v[166:169], v[184:187], v[52:55]
	v_mfma_f32_16x16x32_bf16 v[48:51], v[174:177], v[184:187], v[48:51]
	v_mfma_f32_16x16x32_bf16 v[36:39], v[166:169], v[192:195], v[36:39]
	v_mfma_f32_16x16x32_bf16 v[32:35], v[174:177], v[192:195], v[32:35]
	v_mfma_f32_16x16x32_bf16 v[20:23], v[166:169], v[200:203], v[20:23]
	v_mfma_f32_16x16x32_bf16 v[16:19], v[174:177], v[200:203], v[16:19]
	v_mfma_f32_16x16x32_bf16 v[4:7], v[166:169], v[208:211], v[4:7]
	v_mfma_f32_16x16x32_bf16 v[0:3], v[174:177], v[208:211], v[0:3]
	s_setprio 0
	s_barrier
	v_add_u32_e32 v158, s72, v145
	v_add_u32_e32 v174, s71, v145
	ds_read_b128 v[140:143], v158
	ds_read_b128 v[150:153], v158 offset:1024
	ds_read_b128 v[154:157], v158 offset:2048
	ds_read_b128 v[158:161], v158 offset:3072
	ds_read_b128 v[162:165], v174
	ds_read_b128 v[166:169], v174 offset:1024
	ds_read_b128 v[170:173], v174 offset:2048
	ds_read_b128 v[174:177], v174 offset:3072
	s_mov_b32 m0, s59
	v_lshl_add_u64 v[220:221], s[44:45], 0, v[128:129]
	ds_read_b128 v[180:183], v149 offset:32768
	ds_read_b128 v[184:187], v149 offset:33792
	ds_read_b128 v[188:191], v149 offset:34816
	ds_read_b128 v[192:195], v149 offset:35840
	ds_read_b128 v[196:199], v149 offset:36864
	ds_read_b128 v[200:203], v149 offset:37888
	ds_read_b128 v[204:207], v149 offset:38912
	ds_read_b128 v[208:211], v149 offset:39936
	global_load_lds_dwordx4 v[220:221], off
	v_lshl_add_u64 v[220:221], s[44:45], 0, v[132:133]
	s_mov_b32 m0, s60
	s_nop 0
	global_load_lds_dwordx4 v[220:221], off
	s_waitcnt vmcnt(8)
	s_waitcnt lgkmcnt(0)
	s_barrier
	s_setprio 1
	v_mfma_f32_16x16x32_bf16 v[124:127], v[140:143], v[180:183], v[124:127]
	v_mfma_f32_16x16x32_bf16 v[120:123], v[154:157], v[180:183], v[120:123]
	v_mfma_f32_16x16x32_bf16 v[108:111], v[140:143], v[188:191], v[108:111]
	v_mfma_f32_16x16x32_bf16 v[104:107], v[154:157], v[188:191], v[104:107]
	v_mfma_f32_16x16x32_bf16 v[92:95], v[140:143], v[196:199], v[92:95]
	v_mfma_f32_16x16x32_bf16 v[88:91], v[154:157], v[196:199], v[88:91]
	v_mfma_f32_16x16x32_bf16 v[76:79], v[140:143], v[204:207], v[76:79]
	v_mfma_f32_16x16x32_bf16 v[72:75], v[154:157], v[204:207], v[72:75]
	v_mfma_f32_16x16x32_bf16 v[124:127], v[150:153], v[184:187], v[124:127]
	v_mfma_f32_16x16x32_bf16 v[120:123], v[158:161], v[184:187], v[120:123]
	v_mfma_f32_16x16x32_bf16 v[108:111], v[150:153], v[192:195], v[108:111]
	v_mfma_f32_16x16x32_bf16 v[104:107], v[158:161], v[192:195], v[104:107]
	v_mfma_f32_16x16x32_bf16 v[92:95], v[150:153], v[200:203], v[92:95]
	v_mfma_f32_16x16x32_bf16 v[88:91], v[158:161], v[200:203], v[88:91]
	v_mfma_f32_16x16x32_bf16 v[76:79], v[150:153], v[208:211], v[76:79]
	v_mfma_f32_16x16x32_bf16 v[72:75], v[158:161], v[208:211], v[72:75]
	v_mfma_f32_16x16x32_bf16 v[116:119], v[162:165], v[180:183], v[116:119]
	v_mfma_f32_16x16x32_bf16 v[112:115], v[170:173], v[180:183], v[112:115]
	v_mfma_f32_16x16x32_bf16 v[100:103], v[162:165], v[188:191], v[100:103]
	v_mfma_f32_16x16x32_bf16 v[96:99], v[170:173], v[188:191], v[96:99]
	v_mfma_f32_16x16x32_bf16 v[84:87], v[162:165], v[196:199], v[84:87]
	v_mfma_f32_16x16x32_bf16 v[80:83], v[170:173], v[196:199], v[80:83]
	v_mfma_f32_16x16x32_bf16 v[68:71], v[162:165], v[204:207], v[68:71]
	v_mfma_f32_16x16x32_bf16 v[64:67], v[170:173], v[204:207], v[64:67]
	v_mfma_f32_16x16x32_bf16 v[116:119], v[166:169], v[184:187], v[116:119]
	v_mfma_f32_16x16x32_bf16 v[112:115], v[174:177], v[184:187], v[112:115]
	v_mfma_f32_16x16x32_bf16 v[100:103], v[166:169], v[192:195], v[100:103]
	v_mfma_f32_16x16x32_bf16 v[96:99], v[174:177], v[192:195], v[96:99]
	v_mfma_f32_16x16x32_bf16 v[84:87], v[166:169], v[200:203], v[84:87]
	v_mfma_f32_16x16x32_bf16 v[80:83], v[174:177], v[200:203], v[80:83]
	v_mfma_f32_16x16x32_bf16 v[68:71], v[166:169], v[208:211], v[68:71]
	v_mfma_f32_16x16x32_bf16 v[64:67], v[174:177], v[208:211], v[64:67]
	s_setprio 0
	s_barrier
	s_mov_b32 m0, s70
	v_lshl_add_u64 v[212:213], v[212:213], 0, s[8:9]
	ds_read_b128 v[180:183], v149 offset:49152
	ds_read_b128 v[184:187], v149 offset:50176
	ds_read_b128 v[188:191], v149 offset:51200
	ds_read_b128 v[192:195], v149 offset:52224
	ds_read_b128 v[196:199], v149 offset:53248
	ds_read_b128 v[200:203], v149 offset:54272
	ds_read_b128 v[204:207], v149 offset:55296
	ds_read_b128 v[208:211], v149 offset:56320
	global_load_lds_dwordx4 v[212:213], off
	v_lshl_add_u64 v[212:213], v[214:215], 0, s[8:9]
	s_mov_b32 m0, s69
	s_nop 0
	global_load_lds_dwordx4 v[212:213], off
	v_lshl_add_u64 v[212:213], s[42:43], 0, v[130:131]
	s_mov_b32 m0, s78
	s_nop 0
	global_load_lds_dwordx4 v[212:213], off
	v_lshl_add_u64 v[212:213], s[42:43], 0, v[134:135]
	s_mov_b32 m0, s77
	s_nop 0
	global_load_lds_dwordx4 v[212:213], off
	v_lshl_add_u64 v[212:213], v[216:217], 0, s[8:9]
	s_mov_b32 m0, s62
	s_nop 0
	global_load_lds_dwordx4 v[212:213], off
	v_lshl_add_u64 v[212:213], v[218:219], 0, s[8:9]
	s_mov_b32 m0, s63
	s_nop 0
	global_load_lds_dwordx4 v[212:213], off
	s_waitcnt vmcnt(8)
	s_waitcnt lgkmcnt(0)
	s_barrier
	s_setprio 1
	v_mfma_f32_16x16x32_bf16 v[60:63], v[140:143], v[180:183], v[60:63]
	v_mfma_f32_16x16x32_bf16 v[56:59], v[154:157], v[180:183], v[56:59]
	v_mfma_f32_16x16x32_bf16 v[44:47], v[140:143], v[188:191], v[44:47]
	v_mfma_f32_16x16x32_bf16 v[40:43], v[154:157], v[188:191], v[40:43]
	v_mfma_f32_16x16x32_bf16 v[28:31], v[140:143], v[196:199], v[28:31]
	v_mfma_f32_16x16x32_bf16 v[24:27], v[154:157], v[196:199], v[24:27]
	v_mfma_f32_16x16x32_bf16 v[12:15], v[140:143], v[204:207], v[12:15]
	v_mfma_f32_16x16x32_bf16 v[8:11], v[154:157], v[204:207], v[8:11]
	v_mfma_f32_16x16x32_bf16 v[60:63], v[150:153], v[184:187], v[60:63]
	v_mfma_f32_16x16x32_bf16 v[56:59], v[158:161], v[184:187], v[56:59]
	v_mfma_f32_16x16x32_bf16 v[44:47], v[150:153], v[192:195], v[44:47]
	v_mfma_f32_16x16x32_bf16 v[40:43], v[158:161], v[192:195], v[40:43]
	v_mfma_f32_16x16x32_bf16 v[28:31], v[150:153], v[200:203], v[28:31]
	v_mfma_f32_16x16x32_bf16 v[24:27], v[158:161], v[200:203], v[24:27]
	v_mfma_f32_16x16x32_bf16 v[12:15], v[150:153], v[208:211], v[12:15]
	v_mfma_f32_16x16x32_bf16 v[8:11], v[158:161], v[208:211], v[8:11]
	v_mfma_f32_16x16x32_bf16 v[52:55], v[162:165], v[180:183], v[52:55]
	v_mfma_f32_16x16x32_bf16 v[48:51], v[170:173], v[180:183], v[48:51]
	v_mfma_f32_16x16x32_bf16 v[36:39], v[162:165], v[188:191], v[36:39]
	v_mfma_f32_16x16x32_bf16 v[32:35], v[170:173], v[188:191], v[32:35]
	v_mfma_f32_16x16x32_bf16 v[20:23], v[162:165], v[196:199], v[20:23]
	v_mfma_f32_16x16x32_bf16 v[16:19], v[170:173], v[196:199], v[16:19]
	v_mfma_f32_16x16x32_bf16 v[4:7], v[162:165], v[204:207], v[4:7]
	v_mfma_f32_16x16x32_bf16 v[0:3], v[170:173], v[204:207], v[0:3]
	v_mfma_f32_16x16x32_bf16 v[52:55], v[166:169], v[184:187], v[52:55]
	v_mfma_f32_16x16x32_bf16 v[48:51], v[174:177], v[184:187], v[48:51]
	v_mfma_f32_16x16x32_bf16 v[36:39], v[166:169], v[192:195], v[36:39]
	v_mfma_f32_16x16x32_bf16 v[32:35], v[174:177], v[192:195], v[32:35]
	v_mfma_f32_16x16x32_bf16 v[20:23], v[166:169], v[200:203], v[20:23]
	v_mfma_f32_16x16x32_bf16 v[16:19], v[174:177], v[200:203], v[16:19]
	v_mfma_f32_16x16x32_bf16 v[4:7], v[166:169], v[208:211], v[4:7]
	v_mfma_f32_16x16x32_bf16 v[0:3], v[174:177], v[208:211], v[0:3]
	s_setprio 0
	s_barrier
	s_movk_i32 s44, 0x100
	s_andn2_b64 vcc, exec, s[40:41]
	s_mov_b64 s[42:43], -1
	s_mov_b64 s[40:41], 0
	s_cbranch_vccz .LBB0_2352
	s_and_b64 vcc, exec, s[10:11]
	s_cbranch_vccz .LBB0_2355
	s_barrier

.LBB0_2442:
	ds_read_b128 v[130:133], v178
	ds_read_b128 v[134:137], v178 offset:1024
	ds_read_b128 v[138:141], v178 offset:2048
	ds_read_b128 v[162:165], v178 offset:3072
	ds_read_b128 v[166:169], v179
	ds_read_b128 v[188:191], v179 offset:1024
	ds_read_b128 v[192:195], v179 offset:2048
	ds_read_b128 v[196:199], v179 offset:3072
	s_add_u32 s34, s30, 0xfffc0080
	s_addc_u32 s35, s31, -1
	s_cmp_eq_u32 s59, 12
	s_cselect_b32 s37, s23, s35
	s_cselect_b32 s36, s55, s34
	s_cselect_b32 s35, s21, s58
	s_cselect_b32 s34, s56, s57
	v_lshl_add_u64 v[142:143], s[30:31], 0, v[156:157]
	s_add_i32 m0, s29, 0xc000
	ds_read_b128 v[200:203], v180
	ds_read_b128 v[204:207], v180 offset:1024
	ds_read_b128 v[208:211], v180 offset:2048
	ds_read_b128 v[212:215], v180 offset:3072
	ds_read_b128 v[216:219], v180 offset:4096
	ds_read_b128 v[220:223], v180 offset:5120
	ds_read_b128 v[224:227], v180 offset:6144
	ds_read_b128 v[228:231], v180 offset:7168
	global_load_lds_dwordx4 v[142:143], off
	v_lshl_add_u64 v[142:143], s[30:31], 0, v[154:155]
	s_add_i32 m0, s29, 0xe000
	s_nop 0
	global_load_lds_dwordx4 v[142:143], off
	s_waitcnt vmcnt(8)
	s_waitcnt lgkmcnt(0)
	s_barrier
	s_setprio 1
	v_mfma_f32_16x16x32_bf16 v[124:127], v[130:133], v[200:203], v[124:127]
	v_mfma_f32_16x16x32_bf16 v[120:123], v[138:141], v[200:203], v[120:123]
	v_mfma_f32_16x16x32_bf16 v[108:111], v[130:133], v[208:211], v[108:111]
	v_mfma_f32_16x16x32_bf16 v[104:107], v[138:141], v[208:211], v[104:107]
	v_mfma_f32_16x16x32_bf16 v[92:95], v[130:133], v[216:219], v[92:95]
	v_mfma_f32_16x16x32_bf16 v[88:91], v[138:141], v[216:219], v[88:91]
	v_mfma_f32_16x16x32_bf16 v[76:79], v[130:133], v[224:227], v[76:79]
	v_mfma_f32_16x16x32_bf16 v[72:75], v[138:141], v[224:227], v[72:75]
	v_mfma_f32_16x16x32_bf16 v[124:127], v[134:137], v[204:207], v[124:127]
	v_mfma_f32_16x16x32_bf16 v[120:123], v[162:165], v[204:207], v[120:123]
	v_mfma_f32_16x16x32_bf16 v[108:111], v[134:137], v[212:215], v[108:111]
	v_mfma_f32_16x16x32_bf16 v[104:107], v[162:165], v[212:215], v[104:107]
	v_mfma_f32_16x16x32_bf16 v[92:95], v[134:137], v[220:223], v[92:95]
	v_mfma_f32_16x16x32_bf16 v[88:91], v[162:165], v[220:223], v[88:91]
	v_mfma_f32_16x16x32_bf16 v[76:79], v[134:137], v[228:231], v[76:79]
	v_mfma_f32_16x16x32_bf16 v[72:75], v[162:165], v[228:231], v[72:75]
	v_mfma_f32_16x16x32_bf16 v[116:119], v[166:169], v[200:203], v[116:119]
	v_mfma_f32_16x16x32_bf16 v[112:115], v[192:195], v[200:203], v[112:115]
	v_mfma_f32_16x16x32_bf16 v[100:103], v[166:169], v[208:211], v[100:103]
	v_mfma_f32_16x16x32_bf16 v[96:99], v[192:195], v[208:211], v[96:99]
	v_mfma_f32_16x16x32_bf16 v[84:87], v[166:169], v[216:219], v[84:87]
	v_mfma_f32_16x16x32_bf16 v[80:83], v[192:195], v[216:219], v[80:83]
	v_mfma_f32_16x16x32_bf16 v[68:71], v[166:169], v[224:227], v[68:71]
	v_mfma_f32_16x16x32_bf16 v[64:67], v[192:195], v[224:227], v[64:67]
	v_mfma_f32_16x16x32_bf16 v[116:119], v[188:191], v[204:207], v[116:119]
	v_mfma_f32_16x16x32_bf16 v[112:115], v[196:199], v[204:207], v[112:115]
	v_mfma_f32_16x16x32_bf16 v[100:103], v[188:191], v[212:215], v[100:103]
	v_mfma_f32_16x16x32_bf16 v[96:99], v[196:199], v[212:215], v[96:99]
	v_mfma_f32_16x16x32_bf16 v[84:87], v[188:191], v[220:223], v[84:87]
	v_mfma_f32_16x16x32_bf16 v[80:83], v[196:199], v[220:223], v[80:83]
	v_mfma_f32_16x16x32_bf16 v[68:71], v[188:191], v[228:231], v[68:71]
	v_mfma_f32_16x16x32_bf16 v[64:67], v[196:199], v[228:231], v[64:67]
	s_setprio 0
	s_barrier
	s_add_i32 s60, s49, s40
	v_lshl_add_u64 v[142:143], s[34:35], 0, v[146:147]
	s_mov_b32 m0, s60
	ds_read_b128 v[200:203], v180 offset:16384
	ds_read_b128 v[204:207], v180 offset:17408
	ds_read_b128 v[208:211], v180 offset:18432
	ds_read_b128 v[212:215], v180 offset:19456
	ds_read_b128 v[216:219], v180 offset:20480
	ds_read_b128 v[220:223], v180 offset:21504
	ds_read_b128 v[224:227], v180 offset:22528
	ds_read_b128 v[228:231], v180 offset:23552
	global_load_lds_dwordx4 v[142:143], off
	s_add_i32 m0, s60, 0x2000
	s_add_u32 s60, s34, 0x40000
	v_lshl_add_u64 v[170:171], s[34:35], 0, v[150:151]
	s_addc_u32 s61, s35, 0
	s_add_i32 s62, s50, s40
	global_load_lds_dwordx4 v[170:171], off
	v_lshl_add_u64 v[232:233], s[60:61], 0, v[146:147]
	s_mov_b32 m0, s62
	v_lshl_add_u64 v[234:235], s[36:37], 0, v[148:149]
	global_load_lds_dwordx4 v[232:233], off
	v_lshl_add_u64 v[232:233], s[60:61], 0, v[150:151]
	s_add_i32 m0, s62, 0x2000
	s_nop 0
	global_load_lds_dwordx4 v[232:233], off
	v_lshl_add_u64 v[232:233], s[36:37], 0, v[144:145]
	s_mov_b32 m0, s29
	s_nop 0
	global_load_lds_dwordx4 v[232:233], off
	s_mov_b32 m0, s41
	s_nop 0
	global_load_lds_dwordx4 v[234:235], off
	s_waitcnt vmcnt(8)
	s_waitcnt lgkmcnt(0)
	s_barrier
	s_setprio 1
	v_mfma_f32_16x16x32_bf16 v[60:63], v[130:133], v[200:203], v[60:63]
	v_mfma_f32_16x16x32_bf16 v[56:59], v[138:141], v[200:203], v[56:59]
	v_mfma_f32_16x16x32_bf16 v[44:47], v[130:133], v[208:211], v[44:47]
	v_mfma_f32_16x16x32_bf16 v[40:43], v[138:141], v[208:211], v[40:43]
	v_mfma_f32_16x16x32_bf16 v[28:31], v[130:133], v[216:219], v[28:31]
	v_mfma_f32_16x16x32_bf16 v[24:27], v[138:141], v[216:219], v[24:27]
	v_mfma_f32_16x16x32_bf16 v[12:15], v[130:133], v[224:227], v[12:15]
	v_mfma_f32_16x16x32_bf16 v[8:11], v[138:141], v[224:227], v[8:11]
	v_mfma_f32_16x16x32_bf16 v[60:63], v[134:137], v[204:207], v[60:63]
	v_mfma_f32_16x16x32_bf16 v[56:59], v[162:165], v[204:207], v[56:59]
	v_mfma_f32_16x16x32_bf16 v[44:47], v[134:137], v[212:215], v[44:47]
	v_mfma_f32_16x16x32_bf16 v[40:43], v[162:165], v[212:215], v[40:43]
	v_mfma_f32_16x16x32_bf16 v[28:31], v[134:137], v[220:223], v[28:31]
	v_mfma_f32_16x16x32_bf16 v[24:27], v[162:165], v[220:223], v[24:27]
	v_mfma_f32_16x16x32_bf16 v[12:15], v[134:137], v[228:231], v[12:15]
	v_mfma_f32_16x16x32_bf16 v[8:11], v[162:165], v[228:231], v[8:11]
	v_mfma_f32_16x16x32_bf16 v[52:55], v[166:169], v[200:203], v[52:55]
	v_mfma_f32_16x16x32_bf16 v[48:51], v[192:195], v[200:203], v[48:51]
	v_mfma_f32_16x16x32_bf16 v[36:39], v[166:169], v[208:211], v[36:39]
	v_mfma_f32_16x16x32_bf16 v[32:35], v[192:195], v[208:211], v[32:35]
	v_mfma_f32_16x16x32_bf16 v[20:23], v[166:169], v[216:219], v[20:23]
	v_mfma_f32_16x16x32_bf16 v[16:19], v[192:195], v[216:219], v[16:19]
	v_mfma_f32_16x16x32_bf16 v[4:7], v[166:169], v[224:227], v[4:7]
	v_mfma_f32_16x16x32_bf16 v[0:3], v[192:195], v[224:227], v[0:3]
	v_mfma_f32_16x16x32_bf16 v[52:55], v[188:191], v[204:207], v[52:55]
	v_mfma_f32_16x16x32_bf16 v[48:51], v[196:199], v[204:207], v[48:51]
	v_mfma_f32_16x16x32_bf16 v[36:39], v[188:191], v[212:215], v[36:39]
	v_mfma_f32_16x16x32_bf16 v[32:35], v[196:199], v[212:215], v[32:35]
	v_mfma_f32_16x16x32_bf16 v[20:23], v[188:191], v[220:223], v[20:23]
	v_mfma_f32_16x16x32_bf16 v[16:19], v[196:199], v[220:223], v[16:19]
	v_mfma_f32_16x16x32_bf16 v[4:7], v[188:191], v[228:231], v[4:7]
	v_mfma_f32_16x16x32_bf16 v[0:3], v[196:199], v[228:231], v[0:3]
	s_setprio 0
	s_barrier
	s_add_i32 s60, 0, 0x18000
	v_add_u32_e32 v129, s60, v176
	s_add_i32 s61, 0, 0x1c000
	ds_read_b128 v[130:133], v129
	ds_read_b128 v[134:137], v129 offset:1024
	ds_read_b128 v[138:141], v129 offset:2048
	ds_read_b128 v[162:165], v129 offset:3072
	v_add_u32_e32 v129, s61, v176
	ds_read_b128 v[166:169], v129
	ds_read_b128 v[188:191], v129 offset:1024
	ds_read_b128 v[192:195], v129 offset:2048
	ds_read_b128 v[196:199], v129 offset:3072
	s_add_u32 s36, s36, 0x40000
	s_addc_u32 s37, s37, 0
	s_mov_b32 m0, s42
	v_lshl_add_u64 v[236:237], s[36:37], 0, v[144:145]
	ds_read_b128 v[200:203], v180 offset:32768
	ds_read_b128 v[204:207], v180 offset:33792
	ds_read_b128 v[208:211], v180 offset:34816
	ds_read_b128 v[212:215], v180 offset:35840
	ds_read_b128 v[216:219], v180 offset:36864
	ds_read_b128 v[220:223], v180 offset:37888
	ds_read_b128 v[224:227], v180 offset:38912
	ds_read_b128 v[228:231], v180 offset:39936
	global_load_lds_dwordx4 v[236:237], off
	v_lshl_add_u64 v[236:237], s[36:37], 0, v[148:149]
	s_mov_b32 m0, s43
	s_nop 0
	global_load_lds_dwordx4 v[236:237], off
	s_waitcnt vmcnt(8)
	s_waitcnt lgkmcnt(0)
	s_barrier
	s_setprio 1
	v_mfma_f32_16x16x32_bf16 v[124:127], v[130:133], v[200:203], v[124:127]
	v_mfma_f32_16x16x32_bf16 v[120:123], v[138:141], v[200:203], v[120:123]
	v_mfma_f32_16x16x32_bf16 v[108:111], v[130:133], v[208:211], v[108:111]
	v_mfma_f32_16x16x32_bf16 v[104:107], v[138:141], v[208:211], v[104:107]
	v_mfma_f32_16x16x32_bf16 v[92:95], v[130:133], v[216:219], v[92:95]
	v_mfma_f32_16x16x32_bf16 v[88:91], v[138:141], v[216:219], v[88:91]
	v_mfma_f32_16x16x32_bf16 v[76:79], v[130:133], v[224:227], v[76:79]
	v_mfma_f32_16x16x32_bf16 v[72:75], v[138:141], v[224:227], v[72:75]
	v_mfma_f32_16x16x32_bf16 v[124:127], v[134:137], v[204:207], v[124:127]
	v_mfma_f32_16x16x32_bf16 v[120:123], v[162:165], v[204:207], v[120:123]
	v_mfma_f32_16x16x32_bf16 v[108:111], v[134:137], v[212:215], v[108:111]
	v_mfma_f32_16x16x32_bf16 v[104:107], v[162:165], v[212:215], v[104:107]
	v_mfma_f32_16x16x32_bf16 v[92:95], v[134:137], v[220:223], v[92:95]
	v_mfma_f32_16x16x32_bf16 v[88:91], v[162:165], v[220:223], v[88:91]
	v_mfma_f32_16x16x32_bf16 v[76:79], v[134:137], v[228:231], v[76:79]
	v_mfma_f32_16x16x32_bf16 v[72:75], v[162:165], v[228:231], v[72:75]
	v_mfma_f32_16x16x32_bf16 v[116:119], v[166:169], v[200:203], v[116:119]
	v_mfma_f32_16x16x32_bf16 v[112:115], v[192:195], v[200:203], v[112:115]
	v_mfma_f32_16x16x32_bf16 v[100:103], v[166:169], v[208:211], v[100:103]
	v_mfma_f32_16x16x32_bf16 v[96:99], v[192:195], v[208:211], v[96:99]
	v_mfma_f32_16x16x32_bf16 v[84:87], v[166:169], v[216:219], v[84:87]
	v_mfma_f32_16x16x32_bf16 v[80:83], v[192:195], v[216:219], v[80:83]
	v_mfma_f32_16x16x32_bf16 v[68:71], v[166:169], v[224:227], v[68:71]
	v_mfma_f32_16x16x32_bf16 v[64:67], v[192:195], v[224:227], v[64:67]
	v_mfma_f32_16x16x32_bf16 v[116:119], v[188:191], v[204:207], v[116:119]
	v_mfma_f32_16x16x32_bf16 v[112:115], v[196:199], v[204:207], v[112:115]
	v_mfma_f32_16x16x32_bf16 v[100:103], v[188:191], v[212:215], v[100:103]
	v_mfma_f32_16x16x32_bf16 v[96:99], v[196:199], v[212:215], v[96:99]
	v_mfma_f32_16x16x32_bf16 v[84:87], v[188:191], v[220:223], v[84:87]
	v_mfma_f32_16x16x32_bf16 v[80:83], v[196:199], v[220:223], v[80:83]
	v_mfma_f32_16x16x32_bf16 v[68:71], v[188:191], v[228:231], v[68:71]
	v_mfma_f32_16x16x32_bf16 v[64:67], v[196:199], v[228:231], v[64:67]
	s_setprio 0
	s_barrier
	s_add_i32 s36, s60, s40
	v_lshl_add_u64 v[142:143], v[142:143], 0, s[8:9]
	s_mov_b32 m0, s36
	ds_read_b128 v[200:203], v180 offset:49152
	ds_read_b128 v[204:207], v180 offset:50176
	ds_read_b128 v[208:211], v180 offset:51200
	ds_read_b128 v[212:215], v180 offset:52224
	ds_read_b128 v[216:219], v180 offset:53248
	ds_read_b128 v[220:223], v180 offset:54272
	ds_read_b128 v[224:227], v180 offset:55296
	ds_read_b128 v[228:231], v180 offset:56320
	global_load_lds_dwordx4 v[142:143], off
	s_add_i32 m0, s36, 0x2000
	s_add_u32 s34, s34, 0x40080
	v_lshl_add_u64 v[142:143], v[170:171], 0, s[8:9]
	s_addc_u32 s35, s35, 0
	s_add_i32 s36, s61, s40
	global_load_lds_dwordx4 v[142:143], off
	v_lshl_add_u64 v[142:143], s[34:35], 0, v[146:147]
	s_mov_b32 m0, s36
	s_nop 0
	global_load_lds_dwordx4 v[142:143], off
	v_lshl_add_u64 v[142:143], s[34:35], 0, v[150:151]
	s_add_i32 m0, s36, 0x2000
	s_nop 0
	global_load_lds_dwordx4 v[142:143], off
	v_lshl_add_u64 v[142:143], v[232:233], 0, s[8:9]
	s_mov_b32 m0, s46
	s_nop 0
	global_load_lds_dwordx4 v[142:143], off
	v_lshl_add_u64 v[142:143], v[234:235], 0, s[8:9]
	s_mov_b32 m0, s47
	s_nop 0
	global_load_lds_dwordx4 v[142:143], off
	s_waitcnt vmcnt(8)
	s_waitcnt lgkmcnt(0)
	s_barrier
	s_setprio 1
	v_mfma_f32_16x16x32_bf16 v[60:63], v[130:133], v[200:203], v[60:63]
	v_mfma_f32_16x16x32_bf16 v[56:59], v[138:141], v[200:203], v[56:59]
	v_mfma_f32_16x16x32_bf16 v[44:47], v[130:133], v[208:211], v[44:47]
	v_mfma_f32_16x16x32_bf16 v[40:43], v[138:141], v[208:211], v[40:43]
	v_mfma_f32_16x16x32_bf16 v[28:31], v[130:133], v[216:219], v[28:31]
	v_mfma_f32_16x16x32_bf16 v[24:27], v[138:141], v[216:219], v[24:27]
	v_mfma_f32_16x16x32_bf16 v[12:15], v[130:133], v[224:227], v[12:15]
	v_mfma_f32_16x16x32_bf16 v[8:11], v[138:141], v[224:227], v[8:11]
	v_mfma_f32_16x16x32_bf16 v[60:63], v[134:137], v[204:207], v[60:63]
	v_mfma_f32_16x16x32_bf16 v[56:59], v[162:165], v[204:207], v[56:59]
	v_mfma_f32_16x16x32_bf16 v[44:47], v[134:137], v[212:215], v[44:47]
	v_mfma_f32_16x16x32_bf16 v[40:43], v[162:165], v[212:215], v[40:43]
	v_mfma_f32_16x16x32_bf16 v[28:31], v[134:137], v[220:223], v[28:31]
	v_mfma_f32_16x16x32_bf16 v[24:27], v[162:165], v[220:223], v[24:27]
	v_mfma_f32_16x16x32_bf16 v[12:15], v[134:137], v[228:231], v[12:15]
	v_mfma_f32_16x16x32_bf16 v[8:11], v[162:165], v[228:231], v[8:11]
	v_mfma_f32_16x16x32_bf16 v[52:55], v[166:169], v[200:203], v[52:55]
	v_mfma_f32_16x16x32_bf16 v[48:51], v[192:195], v[200:203], v[48:51]
	v_mfma_f32_16x16x32_bf16 v[36:39], v[166:169], v[208:211], v[36:39]
	v_mfma_f32_16x16x32_bf16 v[32:35], v[192:195], v[208:211], v[32:35]
	v_mfma_f32_16x16x32_bf16 v[20:23], v[166:169], v[216:219], v[20:23]
	v_mfma_f32_16x16x32_bf16 v[16:19], v[192:195], v[216:219], v[16:19]
	v_mfma_f32_16x16x32_bf16 v[4:7], v[166:169], v[224:227], v[4:7]
	v_mfma_f32_16x16x32_bf16 v[0:3], v[192:195], v[224:227], v[0:3]
	v_mfma_f32_16x16x32_bf16 v[52:55], v[188:191], v[204:207], v[52:55]
	v_mfma_f32_16x16x32_bf16 v[48:51], v[196:199], v[204:207], v[48:51]
	v_mfma_f32_16x16x32_bf16 v[36:39], v[188:191], v[212:215], v[36:39]
	v_mfma_f32_16x16x32_bf16 v[32:35], v[196:199], v[212:215], v[32:35]
	v_mfma_f32_16x16x32_bf16 v[20:23], v[188:191], v[220:223], v[20:23]
	v_mfma_f32_16x16x32_bf16 v[16:19], v[196:199], v[220:223], v[16:19]
	v_mfma_f32_16x16x32_bf16 v[4:7], v[188:191], v[228:231], v[4:7]
	v_mfma_f32_16x16x32_bf16 v[0:3], v[196:199], v[228:231], v[0:3]
	s_setprio 0
	s_barrier
	s_add_i32 s59, s59, 2
	s_add_u32 s57, s57, 0x100
	s_addc_u32 s58, s58, 0
	s_add_u32 s30, s30, 0x100
	s_addc_u32 s31, s31, 0
	s_cmp_gt_u32 s59, 13
	s_cbranch_scc0 .LBB0_2442
	s_and_b64 vcc, exec, s[10:11]
	s_cbranch_vccz .LBB0_2445
	s_barrier
